# chainzz2 + E2: BAR1 of each K-loop phase moved below the first 4 MFMAs (2 for fp8), on top of the chain/zigzag MFMA order
# speedup vs baseline: 1.0049x; 1.0037x over previous
; #define PG8_STAGE(bufoff, gbase, voff) do { _Pragma("unroll") for (int _i = 0; _i < 2; ++_i) \
;         __builtin_amdgcn_global_load_lds((const unsigned*)((const char*)(gbase) + (voff)[_i]), (LAS unsigned*)(lds + (bufoff) + ldsw + _i * 8192), 16, 0, 0); } while (0)
; #define PG8_LDA(dst, b, h) do { _Pragma("unroll") for (int m = 0; m < 4; ++m) _Pragma("unroll") for (int k = 0; k < 2; ++k) dst[m][k] = *(const LAS bf16x8*)(lds + PG8_SA(b, h) + aoffk[k] + m * 2048); } while (0)
; #define PG8_LDB(dst, b, h) do { _Pragma("unroll") for (int n = 0; n < 2; ++n) _Pragma("unroll") for (int k = 0; k < 2; ++k) dst[n][k] = *(const LAS bf16x8*)(lds + PG8_SB(b, h) + boffk[k] + n * 2048); } while (0)
; #define PG8_WAIT_V(n) asm volatile("s_waitcnt vmcnt(" #n ")" ::: "memory")
; #define PG8_WAIT_L(n) asm volatile("s_waitcnt lgkmcnt(" #n ")" ::: "memory")
; #define PG8_BAR __builtin_amdgcn_s_barrier()
; #define PG8_SCHED __builtin_amdgcn_sched_barrier(0)
; template <class Epi, class Sched, class GemmT>
; __device__ __forceinline__ void gemm_phase(LAS unsigned char* lds, const GemmT& g, const Sched& S, const Epi& E, const int wid) {
;     ...
;             for (int t = 0; t < nt; t += 2) {
;                 const bool last = (t == nt - 2);
;                 const char* a1 = cA + (size_t)(t + 1) * kstep;
;                 const char* a2 = last ? ns.A : cA + (size_t)(t + 2) * kstep; const char* b2 = last ? ns.B : cB + (size_t)(t + 2) * kstep;
;                 const char* a3 = a2 + kstep; const char* b3 = b2 + kstep;
;                 unsigned vA2[2], vB2[2];
; #pragma unroll
;                 for (int i = 0; i < 2; ++i) { vA2[i] = last ? nvA[i] : voffA[i]; vB2[i] = last ? nvB[i] : voffB[i]; }
;                 const size_t hA2 = last ? nhA : hstepA, hB2 = last ? nhB : hstepB;
;                 PG8_LDB(B0, 0, 0); PG8_LDB(B1, 0, 1); PG8_SCHED; PG8_LDA(At, 0, 0); PG8_STAGE(PG8_SA(1, 1), a1 + hstepA, voffA);
;                 PG8_WAIT_V(8); PG8_WAIT_L(0); PG8_BAR; PG8_MMA(0, 0, At, B0); PG8_MMA(0, 1, At, B1); PG8_BAR; PG8_SCHED;
;                 PG8_LDA(At, 0, 1); PG8_STAGE(PG8_SB(0, 0), b2, vB2); PG8_STAGE(PG8_SB(0, 1), b2 + hB2, vB2); PG8_STAGE(PG8_SA(0, 0), a2, vA2);
;                 PG8_WAIT_V(8); PG8_WAIT_L(0); PG8_BAR; PG8_MMA(1, 0, At, B0); PG8_MMA(1, 1, At, B1); PG8_BAR; PG8_SCHED;
.LBB0_361:
	ds_read_b128 v[24:27], v186
	ds_read_b128 v[28:31], v187
	ds_read_b128 v[16:19], v188
	ds_read_b128 v[20:23], v189
	ds_read_b128 v[8:11], v190
	ds_read_b128 v[12:15], v191
	ds_read_b128 v[0:3], v192
	ds_read_b128 v[4:7], v193
	s_add_u32 s41, s56, 0xfff80080
	s_addc_u32 s48, s57, -1
	s_cmp_eq_u32 s40, 28
	s_cselect_b32 s83, s43, s48
	s_cselect_b32 s82, s42, s41
	s_cselect_b32 s59, s37, s39
	s_cselect_b32 s58, s36, s38
	v_lshl_add_u64 v[230:231], s[56:57], 0, v[160:161]
	s_add_i32 m0, s12, 0xc000
	ds_read_b128 v[174:177], v194
	ds_read_b128 v[204:207], v194 offset:2048
	ds_read_b128 v[178:181], v195
	ds_read_b128 v[208:211], v195 offset:2048
	ds_read_b128 v[212:215], v194 offset:4096
	ds_read_b128 v[220:223], v194 offset:6144
	ds_read_b128 v[216:219], v195 offset:4096
	ds_read_b128 v[224:227], v195 offset:6144
	global_load_lds_dwordx4 v[230:231], off
	v_lshl_add_u64 v[230:231], s[56:57], 0, v[164:165]
	s_add_i32 m0, s12, 0xe000
	s_nop 0
	global_load_lds_dwordx4 v[230:231], off
	s_waitcnt vmcnt(8)
	s_waitcnt lgkmcnt(0)
	s_waitcnt lgkmcnt(0)
	v_mfma_scale_f32_16x16x128_f8f6f4 v[156:159], v[24:31], v[174:181], v[156:159], v196, v196 op_sel_hi:[0,0,0]
	v_mfma_scale_f32_16x16x128_f8f6f4 v[152:155], v[16:23], v[174:181], v[152:155], v196, v196 op_sel_hi:[0,0,0]
	s_barrier
	s_setprio 3
	v_mfma_scale_f32_16x16x128_f8f6f4 v[136:139], v[16:23], v[204:211], v[136:139], v196, v196 op_sel_hi:[0,0,0]
	v_mfma_scale_f32_16x16x128_f8f6f4 v[140:143], v[24:31], v[204:211], v[140:143], v196, v196 op_sel_hi:[0,0,0]
	v_mfma_scale_f32_16x16x128_f8f6f4 v[124:127], v[24:31], v[212:219], v[124:127], v196, v196 op_sel_hi:[0,0,0]
	v_mfma_scale_f32_16x16x128_f8f6f4 v[120:123], v[16:23], v[212:219], v[120:123], v196, v196 op_sel_hi:[0,0,0]
	v_mfma_scale_f32_16x16x128_f8f6f4 v[104:107], v[16:23], v[220:227], v[104:107], v196, v196 op_sel_hi:[0,0,0]
	v_mfma_scale_f32_16x16x128_f8f6f4 v[108:111], v[24:31], v[220:227], v[108:111], v196, v196 op_sel_hi:[0,0,0]
	s_setprio 0
	s_setprio 3
	v_mfma_scale_f32_16x16x128_f8f6f4 v[148:151], v[8:15], v[174:181], v[148:151], v196, v196 op_sel_hi:[0,0,0]
	v_mfma_scale_f32_16x16x128_f8f6f4 v[144:147], v[0:7], v[174:181], v[144:147], v196, v196 op_sel_hi:[0,0,0]
	v_mfma_scale_f32_16x16x128_f8f6f4 v[128:131], v[0:7], v[204:211], v[128:131], v196, v196 op_sel_hi:[0,0,0]
	v_mfma_scale_f32_16x16x128_f8f6f4 v[132:135], v[8:15], v[204:211], v[132:135], v196, v196 op_sel_hi:[0,0,0]
	v_mfma_scale_f32_16x16x128_f8f6f4 v[116:119], v[8:15], v[212:219], v[116:119], v196, v196 op_sel_hi:[0,0,0]
	v_mfma_scale_f32_16x16x128_f8f6f4 v[112:115], v[0:7], v[212:219], v[112:115], v196, v196 op_sel_hi:[0,0,0]
	v_mfma_scale_f32_16x16x128_f8f6f4 v[96:99], v[0:7], v[220:227], v[96:99], v196, v196 op_sel_hi:[0,0,0]
	v_mfma_scale_f32_16x16x128_f8f6f4 v[100:103], v[8:15], v[220:227], v[100:103], v196, v196 op_sel_hi:[0,0,0]
	s_setprio 0
	s_barrier
	s_add_i32 s41, s64, s68
	v_lshl_add_u64 v[174:175], s[58:59], 0, v[162:163]
	s_mov_b32 m0, s41
	ds_read_b128 v[204:207], v194 offset:16384
	ds_read_b128 v[212:215], v194 offset:18432
	ds_read_b128 v[208:211], v195 offset:16384
	ds_read_b128 v[216:219], v195 offset:18432
	ds_read_b128 v[220:223], v194 offset:20480
	ds_read_b128 v[230:233], v194 offset:22528
	ds_read_b128 v[224:227], v195 offset:20480
	ds_read_b128 v[234:237], v195 offset:22528
	global_load_lds_dwordx4 v[174:175], off
	s_add_i32 m0, s41, 0x2000
	s_add_u32 s50, s58, 0x80000
	v_lshl_add_u64 v[176:177], s[58:59], 0, v[166:167]
	s_addc_u32 s51, s59, 0
	s_add_i32 s41, s65, s68
	global_load_lds_dwordx4 v[176:177], off
	v_lshl_add_u64 v[178:179], s[50:51], 0, v[162:163]
	s_mov_b32 m0, s41
	v_lshl_add_u64 v[180:181], s[82:83], 0, v[164:165]
	global_load_lds_dwordx4 v[178:179], off
	v_lshl_add_u64 v[178:179], s[50:51], 0, v[166:167]
	s_add_i32 m0, s41, 0x2000
	s_nop 0
	global_load_lds_dwordx4 v[178:179], off
	v_lshl_add_u64 v[178:179], s[82:83], 0, v[160:161]
	s_mov_b32 m0, s12
	s_nop 0
	global_load_lds_dwordx4 v[178:179], off
	s_mov_b32 m0, s13
	s_nop 0
	global_load_lds_dwordx4 v[180:181], off
	s_waitcnt vmcnt(8)
	s_waitcnt lgkmcnt(0)
	s_waitcnt lgkmcnt(0)
	v_mfma_scale_f32_16x16x128_f8f6f4 v[84:87], v[24:31], v[204:211], v[84:87], v196, v196 op_sel_hi:[0,0,0]
	v_mfma_scale_f32_16x16x128_f8f6f4 v[80:83], v[16:23], v[204:211], v[80:83], v196, v196 op_sel_hi:[0,0,0]
	s_barrier
	s_setprio 3
	v_mfma_scale_f32_16x16x128_f8f6f4 v[64:67], v[16:23], v[212:219], v[64:67], v196, v196 op_sel_hi:[0,0,0]
	v_mfma_scale_f32_16x16x128_f8f6f4 v[68:71], v[24:31], v[212:219], v[68:71], v196, v196 op_sel_hi:[0,0,0]
	v_mfma_scale_f32_16x16x128_f8f6f4 v[52:55], v[24:31], v[220:227], v[52:55], v196, v196 op_sel_hi:[0,0,0]
	v_mfma_scale_f32_16x16x128_f8f6f4 v[48:51], v[16:23], v[220:227], v[48:51], v196, v196 op_sel_hi:[0,0,0]
	v_mfma_scale_f32_16x16x128_f8f6f4 v[32:35], v[16:23], v[230:237], v[32:35], v196, v196 op_sel_hi:[0,0,0]
	v_mfma_scale_f32_16x16x128_f8f6f4 v[36:39], v[24:31], v[230:237], v[36:39], v196, v196 op_sel_hi:[0,0,0]
	s_setprio 0
	s_setprio 3
	v_mfma_scale_f32_16x16x128_f8f6f4 v[92:95], v[8:15], v[204:211], v[92:95], v196, v196 op_sel_hi:[0,0,0]
	v_mfma_scale_f32_16x16x128_f8f6f4 v[88:91], v[0:7], v[204:211], v[88:91], v196, v196 op_sel_hi:[0,0,0]
	v_mfma_scale_f32_16x16x128_f8f6f4 v[72:75], v[0:7], v[212:219], v[72:75], v196, v196 op_sel_hi:[0,0,0]
	v_mfma_scale_f32_16x16x128_f8f6f4 v[76:79], v[8:15], v[212:219], v[76:79], v196, v196 op_sel_hi:[0,0,0]
	v_mfma_scale_f32_16x16x128_f8f6f4 v[60:63], v[8:15], v[220:227], v[60:63], v196, v196 op_sel_hi:[0,0,0]
	v_mfma_scale_f32_16x16x128_f8f6f4 v[56:59], v[0:7], v[220:227], v[56:59], v196, v196 op_sel_hi:[0,0,0]
	v_mfma_scale_f32_16x16x128_f8f6f4 v[40:43], v[0:7], v[230:237], v[40:43], v196, v196 op_sel_hi:[0,0,0]
	v_mfma_scale_f32_16x16x128_f8f6f4 v[44:47], v[8:15], v[230:237], v[44:47], v196, v196 op_sel_hi:[0,0,0]
	s_setprio 0
	s_barrier
; #define PG8_STAGE(bufoff, gbase, voff) do { _Pragma("unroll") for (int _i = 0; _i < 2; ++_i) \
;         __builtin_amdgcn_global_load_lds((const unsigned*)((const char*)(gbase) + (voff)[_i]), (LAS unsigned*)(lds + (bufoff) + ldsw + _i * 8192), 16, 0, 0); } while (0)
; #define PG8_LDA(dst, b, h) do { _Pragma("unroll") for (int m = 0; m < 4; ++m) _Pragma("unroll") for (int k = 0; k < 2; ++k) dst[m][k] = *(const LAS bf16x8*)(lds + PG8_SA(b, h) + aoffk[k] + m * 2048); } while (0)
; #define PG8_LDB(dst, b, h) do { _Pragma("unroll") for (int n = 0; n < 2; ++n) _Pragma("unroll") for (int k = 0; k < 2; ++k) dst[n][k] = *(const LAS bf16x8*)(lds + PG8_SB(b, h) + boffk[k] + n * 2048); } while (0)
; #define PG8_WAIT_V(n) asm volatile("s_waitcnt vmcnt(" #n ")" ::: "memory")
; #define PG8_WAIT_L(n) asm volatile("s_waitcnt lgkmcnt(" #n ")" ::: "memory")
; #define PG8_BAR __builtin_amdgcn_s_barrier()
; #define PG8_SCHED __builtin_amdgcn_sched_barrier(0)
; template <class Epi, class Sched, class GemmT>
; __device__ __forceinline__ void gemm_phase(LAS unsigned char* lds, const GemmT& g, const Sched& S, const Epi& E, const int wid) {
;     ...
;                 PG8_LDB(B0, 1, 0); PG8_LDB(B1, 1, 1); PG8_SCHED; PG8_LDA(At, 1, 0); PG8_STAGE(PG8_SA(0, 1), a2 + hA2, vA2);
;                 PG8_WAIT_V(8); PG8_WAIT_L(0); PG8_BAR; PG8_MMA(0, 0, At, B0); PG8_MMA(0, 1, At, B1); PG8_BAR; PG8_SCHED;
;                 PG8_LDA(At, 1, 1); PG8_STAGE(PG8_SB(1, 0), b3, vB2); PG8_STAGE(PG8_SB(1, 1), b3 + hB2, vB2); PG8_STAGE(PG8_SA(1, 0), a3, vA2);
;                 PG8_WAIT_V(8); PG8_WAIT_L(0); PG8_BAR; PG8_MMA(1, 0, At, B0); PG8_MMA(1, 1, At, B1); PG8_BAR; PG8_SCHED;
;             }
	s_add_i32 s41, 0, 0x18000
	s_add_i32 s48, 0, 0x1c000
	v_add_u32_e32 v0, s41, v184
	v_add_u32_e32 v4, s41, v185
	v_add_u32_e32 v16, s48, v184
	v_add_u32_e32 v20, s48, v185
	ds_read_b128 v[0:3], v0
	ds_read_b128 v[4:7], v4
	ds_read_b128 v[8:11], v197
	ds_read_b128 v[12:15], v198
	ds_read_b128 v[16:19], v16
	ds_read_b128 v[20:23], v20
	ds_read_b128 v[24:27], v199
	ds_read_b128 v[28:31], v200
	s_add_u32 s50, s82, 0x80000
	s_addc_u32 s51, s83, 0
	s_mov_b32 m0, s15
	v_lshl_add_u64 v[238:239], s[50:51], 0, v[160:161]
	ds_read_b128 v[204:207], v194 offset:32768
	ds_read_b128 v[212:215], v194 offset:34816
	ds_read_b128 v[208:211], v195 offset:32768
	ds_read_b128 v[216:219], v195 offset:34816
	ds_read_b128 v[220:223], v194 offset:36864
	ds_read_b128 v[230:233], v194 offset:38912
	ds_read_b128 v[224:227], v195 offset:36864
	ds_read_b128 v[234:237], v195 offset:38912
	global_load_lds_dwordx4 v[238:239], off
	v_lshl_add_u64 v[238:239], s[50:51], 0, v[164:165]
	s_mov_b32 m0, s21
	s_nop 0
	global_load_lds_dwordx4 v[238:239], off
	s_waitcnt vmcnt(8)
	s_waitcnt lgkmcnt(0)
	s_waitcnt lgkmcnt(0)
	v_mfma_scale_f32_16x16x128_f8f6f4 v[156:159], v[0:7], v[204:211], v[156:159], v196, v196 op_sel_hi:[0,0,0]
	v_mfma_scale_f32_16x16x128_f8f6f4 v[152:155], v[8:15], v[204:211], v[152:155], v196, v196 op_sel_hi:[0,0,0]
	s_barrier
	s_setprio 3
	v_mfma_scale_f32_16x16x128_f8f6f4 v[136:139], v[8:15], v[212:219], v[136:139], v196, v196 op_sel_hi:[0,0,0]
	v_mfma_scale_f32_16x16x128_f8f6f4 v[140:143], v[0:7], v[212:219], v[140:143], v196, v196 op_sel_hi:[0,0,0]
	v_mfma_scale_f32_16x16x128_f8f6f4 v[124:127], v[0:7], v[220:227], v[124:127], v196, v196 op_sel_hi:[0,0,0]
	v_mfma_scale_f32_16x16x128_f8f6f4 v[120:123], v[8:15], v[220:227], v[120:123], v196, v196 op_sel_hi:[0,0,0]
	v_mfma_scale_f32_16x16x128_f8f6f4 v[104:107], v[8:15], v[230:237], v[104:107], v196, v196 op_sel_hi:[0,0,0]
	v_mfma_scale_f32_16x16x128_f8f6f4 v[108:111], v[0:7], v[230:237], v[108:111], v196, v196 op_sel_hi:[0,0,0]
	s_setprio 0
	s_setprio 3
	v_mfma_scale_f32_16x16x128_f8f6f4 v[148:151], v[16:23], v[204:211], v[148:151], v196, v196 op_sel_hi:[0,0,0]
	v_mfma_scale_f32_16x16x128_f8f6f4 v[144:147], v[24:31], v[204:211], v[144:147], v196, v196 op_sel_hi:[0,0,0]
	v_mfma_scale_f32_16x16x128_f8f6f4 v[128:131], v[24:31], v[212:219], v[128:131], v196, v196 op_sel_hi:[0,0,0]
	v_mfma_scale_f32_16x16x128_f8f6f4 v[132:135], v[16:23], v[212:219], v[132:135], v196, v196 op_sel_hi:[0,0,0]
	v_mfma_scale_f32_16x16x128_f8f6f4 v[116:119], v[16:23], v[220:227], v[116:119], v196, v196 op_sel_hi:[0,0,0]
	v_mfma_scale_f32_16x16x128_f8f6f4 v[112:115], v[24:31], v[220:227], v[112:115], v196, v196 op_sel_hi:[0,0,0]
	v_mfma_scale_f32_16x16x128_f8f6f4 v[96:99], v[24:31], v[230:237], v[96:99], v196, v196 op_sel_hi:[0,0,0]
	v_mfma_scale_f32_16x16x128_f8f6f4 v[100:103], v[16:23], v[230:237], v[100:103], v196, v196 op_sel_hi:[0,0,0]
	s_setprio 0
	s_barrier
	s_add_i32 s41, s41, s68
	v_lshl_add_u64 v[174:175], v[174:175], 0, s[10:11]
	s_mov_b32 m0, s41
	ds_read_b128 v[204:207], v194 offset:49152
	ds_read_b128 v[212:215], v194 offset:51200
	ds_read_b128 v[208:211], v195 offset:49152
	ds_read_b128 v[216:219], v195 offset:51200
	ds_read_b128 v[220:223], v194 offset:53248
	ds_read_b128 v[230:233], v194 offset:55296
	ds_read_b128 v[224:227], v195 offset:53248
	ds_read_b128 v[234:237], v195 offset:55296
	global_load_lds_dwordx4 v[174:175], off
	s_add_i32 m0, s41, 0x2000
	s_add_u32 s50, s58, 0x80080
	v_lshl_add_u64 v[174:175], v[176:177], 0, s[10:11]
	s_addc_u32 s51, s59, 0
	s_add_i32 s41, s48, s68
	global_load_lds_dwordx4 v[174:175], off
	v_lshl_add_u64 v[174:175], s[50:51], 0, v[162:163]
	s_mov_b32 m0, s41
	s_nop 0
	global_load_lds_dwordx4 v[174:175], off
	v_lshl_add_u64 v[174:175], s[50:51], 0, v[166:167]
	s_add_i32 m0, s41, 0x2000
	s_nop 0
	global_load_lds_dwordx4 v[174:175], off
	v_lshl_add_u64 v[174:175], v[178:179], 0, s[10:11]
	s_mov_b32 m0, s35
	s_nop 0
	global_load_lds_dwordx4 v[174:175], off
	v_lshl_add_u64 v[174:175], v[180:181], 0, s[10:11]
	s_mov_b32 m0, s53
	s_nop 0
	global_load_lds_dwordx4 v[174:175], off
	s_waitcnt vmcnt(8)
	s_waitcnt lgkmcnt(0)
	s_waitcnt lgkmcnt(0)
	v_mfma_scale_f32_16x16x128_f8f6f4 v[84:87], v[0:7], v[204:211], v[84:87], v196, v196 op_sel_hi:[0,0,0]
	v_mfma_scale_f32_16x16x128_f8f6f4 v[80:83], v[8:15], v[204:211], v[80:83], v196, v196 op_sel_hi:[0,0,0]
	s_barrier
	s_setprio 3
	v_mfma_scale_f32_16x16x128_f8f6f4 v[64:67], v[8:15], v[212:219], v[64:67], v196, v196 op_sel_hi:[0,0,0]
	v_mfma_scale_f32_16x16x128_f8f6f4 v[68:71], v[0:7], v[212:219], v[68:71], v196, v196 op_sel_hi:[0,0,0]
	v_mfma_scale_f32_16x16x128_f8f6f4 v[52:55], v[0:7], v[220:227], v[52:55], v196, v196 op_sel_hi:[0,0,0]
	v_mfma_scale_f32_16x16x128_f8f6f4 v[48:51], v[8:15], v[220:227], v[48:51], v196, v196 op_sel_hi:[0,0,0]
	v_mfma_scale_f32_16x16x128_f8f6f4 v[32:35], v[8:15], v[230:237], v[32:35], v196, v196 op_sel_hi:[0,0,0]
	v_mfma_scale_f32_16x16x128_f8f6f4 v[36:39], v[0:7], v[230:237], v[36:39], v196, v196 op_sel_hi:[0,0,0]
	s_setprio 0
	s_setprio 3
	v_mfma_scale_f32_16x16x128_f8f6f4 v[92:95], v[16:23], v[204:211], v[92:95], v196, v196 op_sel_hi:[0,0,0]
	v_mfma_scale_f32_16x16x128_f8f6f4 v[88:91], v[24:31], v[204:211], v[88:91], v196, v196 op_sel_hi:[0,0,0]
	v_mfma_scale_f32_16x16x128_f8f6f4 v[72:75], v[24:31], v[212:219], v[72:75], v196, v196 op_sel_hi:[0,0,0]
	v_mfma_scale_f32_16x16x128_f8f6f4 v[76:79], v[16:23], v[212:219], v[76:79], v196, v196 op_sel_hi:[0,0,0]
	v_mfma_scale_f32_16x16x128_f8f6f4 v[60:63], v[16:23], v[220:227], v[60:63], v196, v196 op_sel_hi:[0,0,0]
	v_mfma_scale_f32_16x16x128_f8f6f4 v[56:59], v[24:31], v[220:227], v[56:59], v196, v196 op_sel_hi:[0,0,0]
	v_mfma_scale_f32_16x16x128_f8f6f4 v[40:43], v[24:31], v[230:237], v[40:43], v196, v196 op_sel_hi:[0,0,0]
	v_mfma_scale_f32_16x16x128_f8f6f4 v[44:47], v[16:23], v[230:237], v[44:47], v196, v196 op_sel_hi:[0,0,0]
	s_setprio 0
	s_barrier
	s_add_i32 s40, s40, 2
	s_add_u32 s56, s56, 0x100
	s_addc_u32 s57, s57, 0
	s_add_u32 s38, s38, 0x100
	s_addc_u32 s39, s39, 0
	s_cmp_gt_u32 s40, 29
	s_cbranch_scc0 .LBB0_361
	s_and_b64 vcc, exec, s[16:17]
	s_cbranch_vccz .LBB0_364
	s_barrier

; #define PG8_STAGE(bufoff, gbase, voff) do { _Pragma("unroll") for (int _i = 0; _i < 2; ++_i) \
;         __builtin_amdgcn_global_load_lds((const unsigned*)((const char*)(gbase) + (voff)[_i]), (LAS unsigned*)(lds + (bufoff) + ldsw + _i * 8192), 16, 0, 0); } while (0)
; #define PG8_LDA(dst, b, h) do { _Pragma("unroll") for (int m = 0; m < 4; ++m) _Pragma("unroll") for (int k = 0; k < 2; ++k) dst[m][k] = *(const LAS bf16x8*)(lds + PG8_SA(b, h) + aoffk[k] + m * 2048); } while (0)
; #define PG8_LDB(dst, b, h) do { _Pragma("unroll") for (int n = 0; n < 2; ++n) _Pragma("unroll") for (int k = 0; k < 2; ++k) dst[n][k] = *(const LAS bf16x8*)(lds + PG8_SB(b, h) + boffk[k] + n * 2048); } while (0)
; #define PG8_WAIT_V(n) asm volatile("s_waitcnt vmcnt(" #n ")" ::: "memory")
; #define PG8_WAIT_L(n) asm volatile("s_waitcnt lgkmcnt(" #n ")" ::: "memory")
; #define PG8_BAR __builtin_amdgcn_s_barrier()
; #define PG8_SCHED __builtin_amdgcn_sched_barrier(0)
; template <class Epi, class Sched, class GemmT>
; __device__ __forceinline__ void gemm_phase(LAS unsigned char* lds, const GemmT& g, const Sched& S, const Epi& E, const int wid) {
;     ...
;                 PG8_LDB(B0, 0, 0); PG8_LDB(B1, 0, 1); PG8_SCHED; PG8_LDA(At, 0, 0); PG8_STAGE(PG8_SA(1, 1), a1 + hstepA, voffA);
;                 PG8_WAIT_V(8); PG8_WAIT_L(0); PG8_BAR; PG8_MMA(0, 0, At, B0); PG8_MMA(0, 1, At, B1); PG8_BAR; PG8_SCHED;
;                 PG8_LDA(At, 0, 1); PG8_STAGE(PG8_SB(0, 0), b2, vB2); PG8_STAGE(PG8_SB(0, 1), b2 + hB2, vB2); PG8_STAGE(PG8_SA(0, 0), a2, vA2);
;                 PG8_WAIT_V(8); PG8_WAIT_L(0); PG8_BAR; PG8_MMA(1, 0, At, B0); PG8_MMA(1, 1, At, B1); PG8_BAR; PG8_SCHED;
.LBB0_417:
	ds_read_b128 v[140:143], v192
	ds_read_b128 v[144:147], v193
	ds_read_b128 v[148:151], v194
	ds_read_b128 v[152:155], v195
	ds_read_b128 v[156:159], v196
	ds_read_b128 v[160:163], v197
	ds_read_b128 v[164:167], v198
	ds_read_b128 v[168:171], v199
	s_add_u32 s39, s84, 0xfff00080
	s_addc_u32 s40, s85, -1
	s_cmp_eq_u32 s38, 60
	s_cselect_b32 s87, s57, s40
	s_cselect_b32 s86, s56, s39
	s_cselect_b32 s71, s16, s37
	s_cselect_b32 s70, s5, s36
	v_lshl_add_u64 v[176:177], s[84:85], 0, v[128:129]
	s_add_i32 m0, s9, 0xc000
	ds_read_b128 v[172:175], v200
	ds_read_b128 v[208:211], v200 offset:2048
	ds_read_b128 v[212:215], v201
	ds_read_b128 v[216:219], v201 offset:2048
	ds_read_b128 v[220:223], v200 offset:4096
	ds_read_b128 v[224:227], v200 offset:6144
	ds_read_b128 v[230:233], v201 offset:4096
	ds_read_b128 v[234:237], v201 offset:6144
	global_load_lds_dwordx4 v[176:177], off
	v_lshl_add_u64 v[176:177], s[84:85], 0, v[132:133]
	s_add_i32 m0, s9, 0xe000
	s_nop 0
	global_load_lds_dwordx4 v[176:177], off
	s_waitcnt vmcnt(8)
	s_waitcnt lgkmcnt(0)
	s_waitcnt lgkmcnt(0)
	v_mfma_f32_16x16x32_bf16 v[124:127], v[140:143], v[172:175], v[124:127]
	v_mfma_f32_16x16x32_bf16 v[124:127], v[144:147], v[212:215], v[124:127]
	v_mfma_f32_16x16x32_bf16 v[120:123], v[152:155], v[212:215], v[120:123]
	v_mfma_f32_16x16x32_bf16 v[120:123], v[148:151], v[172:175], v[120:123]
	s_barrier
	s_setprio 3
	v_mfma_f32_16x16x32_bf16 v[112:115], v[148:151], v[208:211], v[112:115]
	v_mfma_f32_16x16x32_bf16 v[112:115], v[152:155], v[216:219], v[112:115]
	v_mfma_f32_16x16x32_bf16 v[116:119], v[144:147], v[216:219], v[116:119]
	v_mfma_f32_16x16x32_bf16 v[116:119], v[140:143], v[208:211], v[116:119]
	v_mfma_f32_16x16x32_bf16 v[100:103], v[140:143], v[220:223], v[100:103]
	v_mfma_f32_16x16x32_bf16 v[100:103], v[144:147], v[230:233], v[100:103]
	v_mfma_f32_16x16x32_bf16 v[96:99], v[152:155], v[230:233], v[96:99]
	v_mfma_f32_16x16x32_bf16 v[96:99], v[148:151], v[220:223], v[96:99]
	v_mfma_f32_16x16x32_bf16 v[76:79], v[148:151], v[224:227], v[76:79]
	v_mfma_f32_16x16x32_bf16 v[76:79], v[152:155], v[234:237], v[76:79]
	v_mfma_f32_16x16x32_bf16 v[84:87], v[144:147], v[234:237], v[84:87]
	v_mfma_f32_16x16x32_bf16 v[84:87], v[140:143], v[224:227], v[84:87]
	s_setprio 0
	s_setprio 3
	v_mfma_f32_16x16x32_bf16 v[108:111], v[156:159], v[172:175], v[108:111]
	v_mfma_f32_16x16x32_bf16 v[108:111], v[160:163], v[212:215], v[108:111]
	v_mfma_f32_16x16x32_bf16 v[104:107], v[168:171], v[212:215], v[104:107]
	v_mfma_f32_16x16x32_bf16 v[104:107], v[164:167], v[172:175], v[104:107]
	v_mfma_f32_16x16x32_bf16 v[88:91], v[164:167], v[208:211], v[88:91]
	v_mfma_f32_16x16x32_bf16 v[88:91], v[168:171], v[216:219], v[88:91]
	v_mfma_f32_16x16x32_bf16 v[92:95], v[160:163], v[216:219], v[92:95]
	v_mfma_f32_16x16x32_bf16 v[92:95], v[156:159], v[208:211], v[92:95]
	v_mfma_f32_16x16x32_bf16 v[68:71], v[156:159], v[220:223], v[68:71]
	v_mfma_f32_16x16x32_bf16 v[68:71], v[160:163], v[230:233], v[68:71]
	v_mfma_f32_16x16x32_bf16 v[64:67], v[168:171], v[230:233], v[64:67]
	v_mfma_f32_16x16x32_bf16 v[64:67], v[164:167], v[220:223], v[64:67]
	v_mfma_f32_16x16x32_bf16 v[40:43], v[164:167], v[224:227], v[40:43]
	v_mfma_f32_16x16x32_bf16 v[40:43], v[168:171], v[234:237], v[40:43]
	v_mfma_f32_16x16x32_bf16 v[48:51], v[160:163], v[234:237], v[48:51]
	v_mfma_f32_16x16x32_bf16 v[48:51], v[156:159], v[224:227], v[48:51]
	s_setprio 0
	s_barrier
	s_add_i32 s39, s35, s68
	v_lshl_add_u64 v[176:177], s[70:71], 0, v[130:131]
	s_mov_b32 m0, s39
	ds_read_b128 v[172:175], v200 offset:16384
	ds_read_b128 v[208:211], v200 offset:18432
	ds_read_b128 v[212:215], v201 offset:16384
	ds_read_b128 v[216:219], v201 offset:18432
	ds_read_b128 v[220:223], v200 offset:20480
	ds_read_b128 v[224:227], v200 offset:22528
	ds_read_b128 v[230:233], v201 offset:20480
	ds_read_b128 v[234:237], v201 offset:22528
	global_load_lds_dwordx4 v[176:177], off
	s_add_i32 m0, s39, 0x2000
	s_add_u32 s40, s70, 0x100000
	v_lshl_add_u64 v[180:181], s[70:71], 0, v[134:135]
	s_addc_u32 s41, s71, 0
	s_add_i32 s39, s69, s68
	global_load_lds_dwordx4 v[180:181], off
	v_lshl_add_u64 v[184:185], s[40:41], 0, v[130:131]
	s_mov_b32 m0, s39
	v_lshl_add_u64 v[188:189], s[86:87], 0, v[132:133]
	global_load_lds_dwordx4 v[184:185], off
	v_lshl_add_u64 v[184:185], s[40:41], 0, v[134:135]
	s_add_i32 m0, s39, 0x2000
	s_nop 0
	global_load_lds_dwordx4 v[184:185], off
	v_lshl_add_u64 v[184:185], s[86:87], 0, v[128:129]
	s_mov_b32 m0, s9
	s_nop 0
	global_load_lds_dwordx4 v[184:185], off
	s_mov_b32 m0, s29
	s_nop 0
	global_load_lds_dwordx4 v[188:189], off
	s_waitcnt vmcnt(8)
	s_waitcnt lgkmcnt(0)
	s_waitcnt lgkmcnt(0)
	v_mfma_f32_16x16x32_bf16 v[28:31], v[140:143], v[172:175], v[28:31]
	v_mfma_f32_16x16x32_bf16 v[28:31], v[144:147], v[212:215], v[28:31]
	v_mfma_f32_16x16x32_bf16 v[24:27], v[152:155], v[212:215], v[24:27]
	v_mfma_f32_16x16x32_bf16 v[24:27], v[148:151], v[172:175], v[24:27]
	s_barrier
; #define PG8_STAGE(bufoff, gbase, voff) do { _Pragma("unroll") for (int _i = 0; _i < 2; ++_i) \
;         __builtin_amdgcn_global_load_lds((const unsigned*)((const char*)(gbase) + (voff)[_i]), (LAS unsigned*)(lds + (bufoff) + ldsw + _i * 8192), 16, 0, 0); } while (0)
; #define PG8_LDA(dst, b, h) do { _Pragma("unroll") for (int m = 0; m < 4; ++m) _Pragma("unroll") for (int k = 0; k < 2; ++k) dst[m][k] = *(const LAS bf16x8*)(lds + PG8_SA(b, h) + aoffk[k] + m * 2048); } while (0)
; #define PG8_LDB(dst, b, h) do { _Pragma("unroll") for (int n = 0; n < 2; ++n) _Pragma("unroll") for (int k = 0; k < 2; ++k) dst[n][k] = *(const LAS bf16x8*)(lds + PG8_SB(b, h) + boffk[k] + n * 2048); } while (0)
; #define PG8_WAIT_V(n) asm volatile("s_waitcnt vmcnt(" #n ")" ::: "memory")
; #define PG8_WAIT_L(n) asm volatile("s_waitcnt lgkmcnt(" #n ")" ::: "memory")
; #define PG8_BAR __builtin_amdgcn_s_barrier()
; #define PG8_SCHED __builtin_amdgcn_sched_barrier(0)
; template <class Epi, class Sched, class GemmT>
; __device__ __forceinline__ void gemm_phase(LAS unsigned char* lds, const GemmT& g, const Sched& S, const Epi& E, const int wid) {
;     ...
;                 PG8_WAIT_V(8); PG8_WAIT_L(0); PG8_BAR; PG8_MMA(1, 0, At, B0); PG8_MMA(1, 1, At, B1); PG8_BAR; PG8_SCHED;
;                 PG8_LDB(B0, 1, 0); PG8_LDB(B1, 1, 1); PG8_SCHED; PG8_LDA(At, 1, 0); PG8_STAGE(PG8_SA(0, 1), a2 + hA2, vA2);
;                 PG8_WAIT_V(8); PG8_WAIT_L(0); PG8_BAR; PG8_MMA(0, 0, At, B0); PG8_MMA(0, 1, At, B1); PG8_BAR; PG8_SCHED;
	s_setprio 3
	v_mfma_f32_16x16x32_bf16 v[16:19], v[148:151], v[208:211], v[16:19]
	v_mfma_f32_16x16x32_bf16 v[16:19], v[152:155], v[216:219], v[16:19]
	v_mfma_f32_16x16x32_bf16 v[20:23], v[144:147], v[216:219], v[20:23]
	v_mfma_f32_16x16x32_bf16 v[20:23], v[140:143], v[208:211], v[20:23]
	v_mfma_f32_16x16x32_bf16 v[12:15], v[140:143], v[220:223], v[12:15]
	v_mfma_f32_16x16x32_bf16 v[12:15], v[144:147], v[230:233], v[12:15]
	v_mfma_f32_16x16x32_bf16 v[8:11], v[152:155], v[230:233], v[8:11]
	v_mfma_f32_16x16x32_bf16 v[8:11], v[148:151], v[220:223], v[8:11]
	v_mfma_f32_16x16x32_bf16 v[0:3], v[148:151], v[224:227], v[0:3]
	v_mfma_f32_16x16x32_bf16 v[0:3], v[152:155], v[234:237], v[0:3]
	v_mfma_f32_16x16x32_bf16 v[4:7], v[144:147], v[234:237], v[4:7]
	v_mfma_f32_16x16x32_bf16 v[4:7], v[140:143], v[224:227], v[4:7]
	s_setprio 0
	s_setprio 3
	v_mfma_f32_16x16x32_bf16 v[80:83], v[156:159], v[172:175], v[80:83]
	v_mfma_f32_16x16x32_bf16 v[80:83], v[160:163], v[212:215], v[80:83]
	v_mfma_f32_16x16x32_bf16 v[72:75], v[168:171], v[212:215], v[72:75]
	v_mfma_f32_16x16x32_bf16 v[72:75], v[164:167], v[172:175], v[72:75]
	v_mfma_f32_16x16x32_bf16 v[56:59], v[164:167], v[208:211], v[56:59]
	v_mfma_f32_16x16x32_bf16 v[56:59], v[168:171], v[216:219], v[56:59]
	v_mfma_f32_16x16x32_bf16 v[60:63], v[160:163], v[216:219], v[60:63]
	v_mfma_f32_16x16x32_bf16 v[60:63], v[156:159], v[208:211], v[60:63]
	v_mfma_f32_16x16x32_bf16 v[52:55], v[156:159], v[220:223], v[52:55]
	v_mfma_f32_16x16x32_bf16 v[52:55], v[160:163], v[230:233], v[52:55]
	v_mfma_f32_16x16x32_bf16 v[44:47], v[168:171], v[230:233], v[44:47]
	v_mfma_f32_16x16x32_bf16 v[44:47], v[164:167], v[220:223], v[44:47]
	v_mfma_f32_16x16x32_bf16 v[32:35], v[164:167], v[224:227], v[32:35]
	v_mfma_f32_16x16x32_bf16 v[32:35], v[168:171], v[234:237], v[32:35]
	v_mfma_f32_16x16x32_bf16 v[36:39], v[160:163], v[234:237], v[36:39]
	v_mfma_f32_16x16x32_bf16 v[36:39], v[156:159], v[224:227], v[36:39]
	s_setprio 0
	s_barrier
	s_add_i32 s39, 0, 0x18000
	s_add_i32 s48, 0, 0x1c000
	v_add_u32_e32 v140, s39, v187
	v_add_u32_e32 v144, s39, v190
	v_add_u32_e32 v156, s48, v187
	v_add_u32_e32 v160, s48, v190
	ds_read_b128 v[140:143], v140
	ds_read_b128 v[144:147], v144
	ds_read_b128 v[148:151], v202
	ds_read_b128 v[152:155], v203
	ds_read_b128 v[156:159], v156
	ds_read_b128 v[160:163], v160
	ds_read_b128 v[164:167], v204
	ds_read_b128 v[168:171], v205
	s_add_u32 s40, s86, 0x100000
	s_addc_u32 s41, s87, 0
	s_mov_b32 m0, s93
	v_lshl_add_u64 v[238:239], s[40:41], 0, v[128:129]
	ds_read_b128 v[172:175], v200 offset:32768
	ds_read_b128 v[208:211], v200 offset:34816
	ds_read_b128 v[212:215], v201 offset:32768
	ds_read_b128 v[216:219], v201 offset:34816
	ds_read_b128 v[220:223], v200 offset:36864
	ds_read_b128 v[224:227], v200 offset:38912
	ds_read_b128 v[230:233], v201 offset:36864
	ds_read_b128 v[234:237], v201 offset:38912
	global_load_lds_dwordx4 v[238:239], off
	v_lshl_add_u64 v[238:239], s[40:41], 0, v[132:133]
	s_mov_b32 m0, s6
	s_nop 0
	global_load_lds_dwordx4 v[238:239], off
	s_waitcnt vmcnt(8)
	s_waitcnt lgkmcnt(0)
	s_waitcnt lgkmcnt(0)
	v_mfma_f32_16x16x32_bf16 v[124:127], v[140:143], v[172:175], v[124:127]
	v_mfma_f32_16x16x32_bf16 v[124:127], v[144:147], v[212:215], v[124:127]
	v_mfma_f32_16x16x32_bf16 v[120:123], v[152:155], v[212:215], v[120:123]
	v_mfma_f32_16x16x32_bf16 v[120:123], v[148:151], v[172:175], v[120:123]
	s_barrier
	s_setprio 3
	v_mfma_f32_16x16x32_bf16 v[112:115], v[148:151], v[208:211], v[112:115]
	v_mfma_f32_16x16x32_bf16 v[112:115], v[152:155], v[216:219], v[112:115]
	v_mfma_f32_16x16x32_bf16 v[116:119], v[144:147], v[216:219], v[116:119]
	v_mfma_f32_16x16x32_bf16 v[116:119], v[140:143], v[208:211], v[116:119]
	v_mfma_f32_16x16x32_bf16 v[100:103], v[140:143], v[220:223], v[100:103]
	v_mfma_f32_16x16x32_bf16 v[100:103], v[144:147], v[230:233], v[100:103]
	v_mfma_f32_16x16x32_bf16 v[96:99], v[152:155], v[230:233], v[96:99]
	v_mfma_f32_16x16x32_bf16 v[96:99], v[148:151], v[220:223], v[96:99]
	v_mfma_f32_16x16x32_bf16 v[76:79], v[148:151], v[224:227], v[76:79]
	v_mfma_f32_16x16x32_bf16 v[76:79], v[152:155], v[234:237], v[76:79]
	v_mfma_f32_16x16x32_bf16 v[84:87], v[144:147], v[234:237], v[84:87]
	v_mfma_f32_16x16x32_bf16 v[84:87], v[140:143], v[224:227], v[84:87]
	s_setprio 0
	s_setprio 3
	v_mfma_f32_16x16x32_bf16 v[108:111], v[156:159], v[172:175], v[108:111]
	v_mfma_f32_16x16x32_bf16 v[108:111], v[160:163], v[212:215], v[108:111]
	v_mfma_f32_16x16x32_bf16 v[104:107], v[168:171], v[212:215], v[104:107]
	v_mfma_f32_16x16x32_bf16 v[104:107], v[164:167], v[172:175], v[104:107]
	v_mfma_f32_16x16x32_bf16 v[88:91], v[164:167], v[208:211], v[88:91]
	v_mfma_f32_16x16x32_bf16 v[88:91], v[168:171], v[216:219], v[88:91]
	v_mfma_f32_16x16x32_bf16 v[92:95], v[160:163], v[216:219], v[92:95]
	v_mfma_f32_16x16x32_bf16 v[92:95], v[156:159], v[208:211], v[92:95]
	v_mfma_f32_16x16x32_bf16 v[68:71], v[156:159], v[220:223], v[68:71]
	v_mfma_f32_16x16x32_bf16 v[68:71], v[160:163], v[230:233], v[68:71]
	v_mfma_f32_16x16x32_bf16 v[64:67], v[168:171], v[230:233], v[64:67]
	v_mfma_f32_16x16x32_bf16 v[64:67], v[164:167], v[220:223], v[64:67]
	v_mfma_f32_16x16x32_bf16 v[40:43], v[164:167], v[224:227], v[40:43]
	v_mfma_f32_16x16x32_bf16 v[40:43], v[168:171], v[234:237], v[40:43]
	v_mfma_f32_16x16x32_bf16 v[48:51], v[160:163], v[234:237], v[48:51]
	v_mfma_f32_16x16x32_bf16 v[48:51], v[156:159], v[224:227], v[48:51]
	s_setprio 0
	s_barrier
; #define PG8_STAGE(bufoff, gbase, voff) do { _Pragma("unroll") for (int _i = 0; _i < 2; ++_i) \
;         __builtin_amdgcn_global_load_lds((const unsigned*)((const char*)(gbase) + (voff)[_i]), (LAS unsigned*)(lds + (bufoff) + ldsw + _i * 8192), 16, 0, 0); } while (0)
; #define PG8_LDA(dst, b, h) do { _Pragma("unroll") for (int m = 0; m < 4; ++m) _Pragma("unroll") for (int k = 0; k < 2; ++k) dst[m][k] = *(const LAS bf16x8*)(lds + PG8_SA(b, h) + aoffk[k] + m * 2048); } while (0)
; #define PG8_WAIT_V(n) asm volatile("s_waitcnt vmcnt(" #n ")" ::: "memory")
; #define PG8_WAIT_L(n) asm volatile("s_waitcnt lgkmcnt(" #n ")" ::: "memory")
; #define PG8_BAR __builtin_amdgcn_s_barrier()
; #define PG8_SCHED __builtin_amdgcn_sched_barrier(0)
; template <class Epi, class Sched, class GemmT>
; __device__ __forceinline__ void gemm_phase(LAS unsigned char* lds, const GemmT& g, const Sched& S, const Epi& E, const int wid) {
;     ...
;                 PG8_LDA(At, 1, 1); PG8_STAGE(PG8_SB(1, 0), b3, vB2); PG8_STAGE(PG8_SB(1, 1), b3 + hB2, vB2); PG8_STAGE(PG8_SA(1, 0), a3, vA2);
;                 PG8_WAIT_V(8); PG8_WAIT_L(0); PG8_BAR; PG8_MMA(1, 0, At, B0); PG8_MMA(1, 1, At, B1); PG8_BAR; PG8_SCHED;
;             }
	s_add_i32 s39, s39, s68
	v_lshl_add_u64 v[176:177], v[176:177], 0, s[66:67]
	s_mov_b32 m0, s39
	ds_read_b128 v[172:175], v200 offset:49152
	ds_read_b128 v[208:211], v200 offset:51200
	ds_read_b128 v[212:215], v201 offset:49152
	ds_read_b128 v[216:219], v201 offset:51200
	ds_read_b128 v[220:223], v200 offset:53248
	ds_read_b128 v[224:227], v200 offset:55296
	ds_read_b128 v[230:233], v201 offset:53248
	ds_read_b128 v[234:237], v201 offset:55296
	global_load_lds_dwordx4 v[176:177], off
	s_add_i32 m0, s39, 0x2000
	s_add_u32 s40, s70, 0x100080
	v_lshl_add_u64 v[176:177], v[180:181], 0, s[66:67]
	s_addc_u32 s41, s71, 0
	s_add_i32 s39, s48, s68
	global_load_lds_dwordx4 v[176:177], off
	v_lshl_add_u64 v[176:177], s[40:41], 0, v[130:131]
	s_mov_b32 m0, s39
	s_nop 0
	global_load_lds_dwordx4 v[176:177], off
	v_lshl_add_u64 v[176:177], s[40:41], 0, v[134:135]
	s_add_i32 m0, s39, 0x2000
	s_nop 0
	global_load_lds_dwordx4 v[176:177], off
	v_lshl_add_u64 v[176:177], v[184:185], 0, s[66:67]
	s_mov_b32 m0, s7
	s_nop 0
	global_load_lds_dwordx4 v[176:177], off
	v_lshl_add_u64 v[176:177], v[188:189], 0, s[66:67]
	s_mov_b32 m0, s12
	s_nop 0
	global_load_lds_dwordx4 v[176:177], off
	s_waitcnt vmcnt(8)
	s_waitcnt lgkmcnt(0)
	s_waitcnt lgkmcnt(0)
	v_mfma_f32_16x16x32_bf16 v[28:31], v[140:143], v[172:175], v[28:31]
	v_mfma_f32_16x16x32_bf16 v[28:31], v[144:147], v[212:215], v[28:31]
	v_mfma_f32_16x16x32_bf16 v[24:27], v[152:155], v[212:215], v[24:27]
	v_mfma_f32_16x16x32_bf16 v[24:27], v[148:151], v[172:175], v[24:27]
	s_barrier
	s_setprio 3
	v_mfma_f32_16x16x32_bf16 v[16:19], v[148:151], v[208:211], v[16:19]
	v_mfma_f32_16x16x32_bf16 v[16:19], v[152:155], v[216:219], v[16:19]
	v_mfma_f32_16x16x32_bf16 v[20:23], v[144:147], v[216:219], v[20:23]
	v_mfma_f32_16x16x32_bf16 v[20:23], v[140:143], v[208:211], v[20:23]
	v_mfma_f32_16x16x32_bf16 v[12:15], v[140:143], v[220:223], v[12:15]
	v_mfma_f32_16x16x32_bf16 v[12:15], v[144:147], v[230:233], v[12:15]
	v_mfma_f32_16x16x32_bf16 v[8:11], v[152:155], v[230:233], v[8:11]
	v_mfma_f32_16x16x32_bf16 v[8:11], v[148:151], v[220:223], v[8:11]
	v_mfma_f32_16x16x32_bf16 v[0:3], v[148:151], v[224:227], v[0:3]
	v_mfma_f32_16x16x32_bf16 v[0:3], v[152:155], v[234:237], v[0:3]
	v_mfma_f32_16x16x32_bf16 v[4:7], v[144:147], v[234:237], v[4:7]
	v_mfma_f32_16x16x32_bf16 v[4:7], v[140:143], v[224:227], v[4:7]
	s_setprio 0
	s_setprio 3
	v_mfma_f32_16x16x32_bf16 v[80:83], v[156:159], v[172:175], v[80:83]
	v_mfma_f32_16x16x32_bf16 v[80:83], v[160:163], v[212:215], v[80:83]
	v_mfma_f32_16x16x32_bf16 v[72:75], v[168:171], v[212:215], v[72:75]
	v_mfma_f32_16x16x32_bf16 v[72:75], v[164:167], v[172:175], v[72:75]
	v_mfma_f32_16x16x32_bf16 v[56:59], v[164:167], v[208:211], v[56:59]
	v_mfma_f32_16x16x32_bf16 v[56:59], v[168:171], v[216:219], v[56:59]
	v_mfma_f32_16x16x32_bf16 v[60:63], v[160:163], v[216:219], v[60:63]
	v_mfma_f32_16x16x32_bf16 v[60:63], v[156:159], v[208:211], v[60:63]
	v_mfma_f32_16x16x32_bf16 v[52:55], v[156:159], v[220:223], v[52:55]
	v_mfma_f32_16x16x32_bf16 v[52:55], v[160:163], v[230:233], v[52:55]
	v_mfma_f32_16x16x32_bf16 v[44:47], v[168:171], v[230:233], v[44:47]
	v_mfma_f32_16x16x32_bf16 v[44:47], v[164:167], v[220:223], v[44:47]
	v_mfma_f32_16x16x32_bf16 v[32:35], v[164:167], v[224:227], v[32:35]
	v_mfma_f32_16x16x32_bf16 v[32:35], v[168:171], v[234:237], v[32:35]
	v_mfma_f32_16x16x32_bf16 v[36:39], v[160:163], v[234:237], v[36:39]
	v_mfma_f32_16x16x32_bf16 v[36:39], v[156:159], v[224:227], v[36:39]
	s_setprio 0
	s_barrier
	s_add_i32 s38, s38, 2
	s_add_u32 s84, s84, 0x100
	s_addc_u32 s85, s85, 0
	s_add_u32 s36, s36, 0x100
	s_addc_u32 s37, s37, 0
	s_cmp_gt_u32 s38, 61
	s_cbranch_scc0 .LBB0_417
	s_and_b64 vcc, exec, s[20:21]
	s_cbranch_vccz .LBB0_420
	s_barrier

; #define PG8_STAGE(bufoff, gbase, voff) do { _Pragma("unroll") for (int _i = 0; _i < 2; ++_i) \
;         __builtin_amdgcn_global_load_lds((const unsigned*)((const char*)(gbase) + (voff)[_i]), (LAS unsigned*)(lds + (bufoff) + ldsw + _i * 8192), 16, 0, 0); } while (0)
; #define PG8_LDA(dst, b, h) do { _Pragma("unroll") for (int m = 0; m < 4; ++m) _Pragma("unroll") for (int k = 0; k < 2; ++k) dst[m][k] = *(const LAS bf16x8*)(lds + PG8_SA(b, h) + aoffk[k] + m * 2048); } while (0)
; #define PG8_LDB(dst, b, h) do { _Pragma("unroll") for (int n = 0; n < 2; ++n) _Pragma("unroll") for (int k = 0; k < 2; ++k) dst[n][k] = *(const LAS bf16x8*)(lds + PG8_SB(b, h) + boffk[k] + n * 2048); } while (0)
; #define PG8_WAIT_V(n) asm volatile("s_waitcnt vmcnt(" #n ")" ::: "memory")
; #define PG8_WAIT_L(n) asm volatile("s_waitcnt lgkmcnt(" #n ")" ::: "memory")
; #define PG8_BAR __builtin_amdgcn_s_barrier()
; #define PG8_SCHED __builtin_amdgcn_sched_barrier(0)
; template <class Epi, class Sched, class GemmT>
; __device__ __forceinline__ void gemm_phase(LAS unsigned char* lds, const GemmT& g, const Sched& S, const Epi& E, const int wid) {
;     ...
;             for (int t = 0; t < nt; t += 2) {
;                 const bool last = (t == nt - 2);
;                 const char* a1 = cA + (size_t)(t + 1) * kstep;
;                 const char* a2 = last ? ns.A : cA + (size_t)(t + 2) * kstep; const char* b2 = last ? ns.B : cB + (size_t)(t + 2) * kstep;
;                 const char* a3 = a2 + kstep; const char* b3 = b2 + kstep;
;                 unsigned vA2[2], vB2[2];
; #pragma unroll
;                 for (int i = 0; i < 2; ++i) { vA2[i] = last ? nvA[i] : voffA[i]; vB2[i] = last ? nvB[i] : voffB[i]; }
;                 const size_t hA2 = last ? nhA : hstepA, hB2 = last ? nhB : hstepB;
;                 PG8_LDB(B0, 0, 0); PG8_LDB(B1, 0, 1); PG8_SCHED; PG8_LDA(At, 0, 0); PG8_STAGE(PG8_SA(1, 1), a1 + hstepA, voffA);
;                 PG8_WAIT_V(8); PG8_WAIT_L(0); PG8_BAR; PG8_MMA(0, 0, At, B0); PG8_MMA(0, 1, At, B1); PG8_BAR; PG8_SCHED;
;                 PG8_LDA(At, 0, 1); PG8_STAGE(PG8_SB(0, 0), b2, vB2); PG8_STAGE(PG8_SB(0, 1), b2 + hB2, vB2); PG8_STAGE(PG8_SA(0, 0), a2, vA2);
;                 PG8_WAIT_V(8); PG8_WAIT_L(0); PG8_BAR; PG8_MMA(1, 0, At, B0); PG8_MMA(1, 1, At, B1); PG8_BAR; PG8_SCHED;
.LBB0_764:
	s_cmp_eq_u32 s43, s56
	s_cselect_b64 vcc, -1, 0
	s_add_i32 s90, s90, 2
	v_add_u32_e32 v131, s62, v208
	s_add_u32 s48, s50, s56
	v_add_u32_e32 v133, s62, v209
	ds_read_b128 v[144:147], v131
	ds_read_b128 v[148:151], v133
	v_add_u32_e32 v131, s63, v208
	s_addc_u32 s49, s51, s57
	v_add_u32_e32 v133, s63, v209
	ds_read_b128 v[152:155], v131
	ds_read_b128 v[156:159], v133
	v_add_u32_e32 v131, s64, v208
	s_add_u32 s58, s48, 0x100
	v_add_u32_e32 v133, s64, v209
	ds_read_b128 v[160:163], v131
	ds_read_b128 v[164:167], v133
	v_add_u32_e32 v131, s65, v208
	s_addc_u32 s59, s49, 0
	v_add_u32_e32 v133, s65, v209
	ds_read_b128 v[168:171], v131
	ds_read_b128 v[172:175], v133
	s_and_b64 s[48:49], vcc, exec
	s_cselect_b32 s59, s19, s59
	s_cselect_b32 s58, s18, s58
	s_add_u32 s60, s85, s56
	s_addc_u32 s61, s89, s57
	s_and_b64 s[48:49], vcc, exec
	v_cndmask_b32_e32 v138, v132, v190, vcc
	v_cndmask_b32_e32 v0, v143, v214, vcc
	v_cndmask_b32_e32 v140, v130, v194, vcc
	v_cndmask_b32_e32 v188, v142, v192, vcc
	s_cselect_b32 s61, s13, s61
	s_cselect_b32 s60, s12, s60
	s_cselect_b32 s91, 0, s45
	s_cselect_b32 s92, s6, s44
	v_lshl_add_u64 v[202:203], v[134:135], 0, s[56:57]
	s_add_i32 m0, s14, 0xc000
	ds_read_b128 v[176:179], v212
	ds_read_b128 v[180:183], v212 offset:2048
	ds_read_b128 v[184:187], v213
	ds_read_b128 v[216:219], v213 offset:2048
	ds_read_b128 v[220:223], v212 offset:4096
	ds_read_b128 v[224:227], v212 offset:6144
	ds_read_b128 v[230:233], v213 offset:4096
	ds_read_b128 v[234:237], v213 offset:6144
	global_load_lds_dwordx4 v[202:203], off
	v_lshl_add_u64 v[202:203], v[136:137], 0, s[56:57]
	s_add_i32 m0, s14, 0xe000
	s_nop 0
	global_load_lds_dwordx4 v[202:203], off
	s_waitcnt vmcnt(8)
	s_waitcnt lgkmcnt(0)
	s_waitcnt lgkmcnt(0)
	v_mfma_f32_16x16x32_bf16 v[126:129], v[144:147], v[176:179], v[126:129]
	v_mfma_f32_16x16x32_bf16 v[126:129], v[148:151], v[184:187], v[126:129]
	v_mfma_f32_16x16x32_bf16 v[122:125], v[156:159], v[184:187], v[122:125]
	v_mfma_f32_16x16x32_bf16 v[122:125], v[152:155], v[176:179], v[122:125]
	s_barrier
	s_setprio 3
	v_mfma_f32_16x16x32_bf16 v[106:109], v[152:155], v[180:183], v[106:109]
	v_mfma_f32_16x16x32_bf16 v[106:109], v[156:159], v[216:219], v[106:109]
	v_mfma_f32_16x16x32_bf16 v[110:113], v[148:151], v[216:219], v[110:113]
	v_mfma_f32_16x16x32_bf16 v[110:113], v[144:147], v[180:183], v[110:113]
	v_mfma_f32_16x16x32_bf16 v[94:97], v[144:147], v[220:223], v[94:97]
	v_mfma_f32_16x16x32_bf16 v[94:97], v[148:151], v[230:233], v[94:97]
	v_mfma_f32_16x16x32_bf16 v[90:93], v[156:159], v[230:233], v[90:93]
	v_mfma_f32_16x16x32_bf16 v[90:93], v[152:155], v[220:223], v[90:93]
	v_mfma_f32_16x16x32_bf16 v[74:77], v[152:155], v[224:227], v[74:77]
	v_mfma_f32_16x16x32_bf16 v[74:77], v[156:159], v[234:237], v[74:77]
	v_mfma_f32_16x16x32_bf16 v[78:81], v[148:151], v[234:237], v[78:81]
	v_mfma_f32_16x16x32_bf16 v[78:81], v[144:147], v[224:227], v[78:81]
	s_setprio 0
	s_setprio 3
	v_mfma_f32_16x16x32_bf16 v[118:121], v[160:163], v[176:179], v[118:121]
	v_mfma_f32_16x16x32_bf16 v[118:121], v[164:167], v[184:187], v[118:121]
	v_mfma_f32_16x16x32_bf16 v[114:117], v[172:175], v[184:187], v[114:117]
	v_mfma_f32_16x16x32_bf16 v[114:117], v[168:171], v[176:179], v[114:117]
	v_mfma_f32_16x16x32_bf16 v[98:101], v[168:171], v[180:183], v[98:101]
	v_mfma_f32_16x16x32_bf16 v[98:101], v[172:175], v[216:219], v[98:101]
	v_mfma_f32_16x16x32_bf16 v[102:105], v[164:167], v[216:219], v[102:105]
	v_mfma_f32_16x16x32_bf16 v[102:105], v[160:163], v[180:183], v[102:105]
	v_mfma_f32_16x16x32_bf16 v[86:89], v[160:163], v[220:223], v[86:89]
	v_mfma_f32_16x16x32_bf16 v[86:89], v[164:167], v[230:233], v[86:89]
	v_mfma_f32_16x16x32_bf16 v[82:85], v[172:175], v[230:233], v[82:85]
	v_mfma_f32_16x16x32_bf16 v[82:85], v[168:171], v[220:223], v[82:85]
	v_mfma_f32_16x16x32_bf16 v[66:69], v[168:171], v[224:227], v[66:69]
	v_mfma_f32_16x16x32_bf16 v[66:69], v[172:175], v[234:237], v[66:69]
	v_mfma_f32_16x16x32_bf16 v[70:73], v[164:167], v[234:237], v[70:73]
	v_mfma_f32_16x16x32_bf16 v[70:73], v[160:163], v[224:227], v[70:73]
	s_setprio 0
	s_barrier
	s_add_i32 s48, s62, s68
	s_mov_b32 m0, s48
	ds_read_b128 v[176:179], v212 offset:16384
	ds_read_b128 v[180:183], v213 offset:16384
	ds_read_b128 v[184:187], v212 offset:18432
	ds_read_b128 v[216:219], v213 offset:18432
	ds_read_b128 v[220:223], v212 offset:20480
	ds_read_b128 v[224:227], v213 offset:20480
	ds_read_b128 v[230:233], v212 offset:22528
	ds_read_b128 v[234:237], v213 offset:22528
	global_load_lds_dwordx4 v0, s[60:61]
	s_add_i32 m0, s48, 0x2000
	v_mov_b32_e32 v189, v1
	s_add_u32 s48, s60, s92
	v_lshl_add_u64 v[202:203], s[60:61], 0, v[0:1]
	v_lshl_add_u64 v[238:239], s[60:61], 0, v[188:189]
	global_load_lds_dwordx4 v188, s[60:61]
	s_addc_u32 s49, s61, s91
	s_add_i32 s60, s64, s68
	s_mov_b32 m0, s60
	v_mov_b32_e32 v139, v1
	global_load_lds_dwordx4 v0, s[48:49]
	s_add_i32 m0, s60, 0x2000
	v_mov_b32_e32 v141, v1
	global_load_lds_dwordx4 v188, s[48:49]
	s_mov_b32 m0, s14
	v_lshl_add_u64 v[240:241], s[48:49], 0, v[0:1]
	global_load_lds_dwordx4 v138, s[58:59]
	s_mov_b32 m0, s15
	v_lshl_add_u64 v[242:243], s[48:49], 0, v[188:189]
	global_load_lds_dwordx4 v140, s[58:59]
	s_waitcnt vmcnt(8)
	s_waitcnt lgkmcnt(0)
	v_lshl_add_u64 v[188:189], s[58:59], 0, v[138:139]
	v_lshl_add_u64 v[244:245], s[58:59], 0, v[140:141]
	s_waitcnt lgkmcnt(0)
	v_mfma_f32_16x16x32_bf16 v[62:65], v[144:147], v[176:179], v[62:65]
	v_mfma_f32_16x16x32_bf16 v[62:65], v[148:151], v[180:183], v[62:65]
	v_mfma_f32_16x16x32_bf16 v[58:61], v[156:159], v[180:183], v[58:61]
	v_mfma_f32_16x16x32_bf16 v[58:61], v[152:155], v[176:179], v[58:61]
	s_barrier
; #define PG8_STAGE(bufoff, gbase, voff) do { _Pragma("unroll") for (int _i = 0; _i < 2; ++_i) \
;         __builtin_amdgcn_global_load_lds((const unsigned*)((const char*)(gbase) + (voff)[_i]), (LAS unsigned*)(lds + (bufoff) + ldsw + _i * 8192), 16, 0, 0); } while (0)
; #define PG8_LDA(dst, b, h) do { _Pragma("unroll") for (int m = 0; m < 4; ++m) _Pragma("unroll") for (int k = 0; k < 2; ++k) dst[m][k] = *(const LAS bf16x8*)(lds + PG8_SA(b, h) + aoffk[k] + m * 2048); } while (0)
; #define PG8_LDB(dst, b, h) do { _Pragma("unroll") for (int n = 0; n < 2; ++n) _Pragma("unroll") for (int k = 0; k < 2; ++k) dst[n][k] = *(const LAS bf16x8*)(lds + PG8_SB(b, h) + boffk[k] + n * 2048); } while (0)
; #define PG8_WAIT_V(n) asm volatile("s_waitcnt vmcnt(" #n ")" ::: "memory")
; #define PG8_WAIT_L(n) asm volatile("s_waitcnt lgkmcnt(" #n ")" ::: "memory")
; #define PG8_BAR __builtin_amdgcn_s_barrier()
; #define PG8_SCHED __builtin_amdgcn_sched_barrier(0)
; template <class Epi, class Sched, class GemmT>
; __device__ __forceinline__ void gemm_phase(LAS unsigned char* lds, const GemmT& g, const Sched& S, const Epi& E, const int wid) {
;     ...
;                 PG8_WAIT_V(8); PG8_WAIT_L(0); PG8_BAR; PG8_MMA(1, 0, At, B0); PG8_MMA(1, 1, At, B1); PG8_BAR; PG8_SCHED;
;                 PG8_LDB(B0, 1, 0); PG8_LDB(B1, 1, 1); PG8_SCHED; PG8_LDA(At, 1, 0); PG8_STAGE(PG8_SA(0, 1), a2 + hA2, vA2);
;                 PG8_WAIT_V(8); PG8_WAIT_L(0); PG8_BAR; PG8_MMA(0, 0, At, B0); PG8_MMA(0, 1, At, B1); PG8_BAR; PG8_SCHED;
	s_setprio 3
	v_mfma_f32_16x16x32_bf16 v[42:45], v[152:155], v[184:187], v[42:45]
	v_mfma_f32_16x16x32_bf16 v[42:45], v[156:159], v[216:219], v[42:45]
	v_mfma_f32_16x16x32_bf16 v[46:49], v[148:151], v[216:219], v[46:49]
	v_mfma_f32_16x16x32_bf16 v[46:49], v[144:147], v[184:187], v[46:49]
	v_mfma_f32_16x16x32_bf16 v[30:33], v[144:147], v[220:223], v[30:33]
	v_mfma_f32_16x16x32_bf16 v[30:33], v[148:151], v[224:227], v[30:33]
	v_mfma_f32_16x16x32_bf16 v[22:25], v[156:159], v[224:227], v[22:25]
	v_mfma_f32_16x16x32_bf16 v[22:25], v[152:155], v[220:223], v[22:25]
	v_mfma_f32_16x16x32_bf16 v[6:9], v[152:155], v[230:233], v[6:9]
	v_mfma_f32_16x16x32_bf16 v[6:9], v[156:159], v[234:237], v[6:9]
	v_mfma_f32_16x16x32_bf16 v[14:17], v[148:151], v[234:237], v[14:17]
	v_mfma_f32_16x16x32_bf16 v[14:17], v[144:147], v[230:233], v[14:17]
	s_setprio 0
	s_setprio 3
	v_mfma_f32_16x16x32_bf16 v[54:57], v[160:163], v[176:179], v[54:57]
	v_mfma_f32_16x16x32_bf16 v[54:57], v[164:167], v[180:183], v[54:57]
	v_mfma_f32_16x16x32_bf16 v[50:53], v[172:175], v[180:183], v[50:53]
	v_mfma_f32_16x16x32_bf16 v[50:53], v[168:171], v[176:179], v[50:53]
	v_mfma_f32_16x16x32_bf16 v[34:37], v[168:171], v[184:187], v[34:37]
	v_mfma_f32_16x16x32_bf16 v[34:37], v[172:175], v[216:219], v[34:37]
	v_mfma_f32_16x16x32_bf16 v[38:41], v[164:167], v[216:219], v[38:41]
	v_mfma_f32_16x16x32_bf16 v[38:41], v[160:163], v[184:187], v[38:41]
	v_mfma_f32_16x16x32_bf16 v[26:29], v[160:163], v[220:223], v[26:29]
	v_mfma_f32_16x16x32_bf16 v[26:29], v[164:167], v[224:227], v[26:29]
	v_mfma_f32_16x16x32_bf16 v[18:21], v[172:175], v[224:227], v[18:21]
	v_mfma_f32_16x16x32_bf16 v[18:21], v[168:171], v[220:223], v[18:21]
	v_mfma_f32_16x16x32_bf16 v[2:5], v[168:171], v[230:233], v[2:5]
	v_mfma_f32_16x16x32_bf16 v[2:5], v[172:175], v[234:237], v[2:5]
	v_mfma_f32_16x16x32_bf16 v[10:13], v[164:167], v[234:237], v[10:13]
	v_mfma_f32_16x16x32_bf16 v[10:13], v[160:163], v[230:233], v[10:13]
	s_setprio 0
	s_barrier
	s_add_i32 s60, 0, 0x18000
	v_add_u32_e32 v0, s60, v208
	v_add_u32_e32 v131, s60, v209
	ds_read_b128 v[144:147], v0
	ds_read_b128 v[148:151], v131
	v_add_u32_e32 v0, s66, v208
	s_add_i32 s61, 0, 0x1c000
	v_add_u32_e32 v131, s66, v209
	ds_read_b128 v[152:155], v0
	ds_read_b128 v[156:159], v131
	v_add_u32_e32 v0, s61, v208
	v_add_u32_e32 v131, s61, v209
	ds_read_b128 v[160:163], v0
	ds_read_b128 v[164:167], v131
	v_add_u32_e32 v0, s67, v208
	v_add_u32_e32 v131, s67, v209
	ds_read_b128 v[168:171], v0
	ds_read_b128 v[172:175], v131
	s_add_u32 s48, s58, s92
	s_addc_u32 s49, s59, s91
	s_mov_b32 m0, s34
	ds_read_b128 v[176:179], v212 offset:32768
	ds_read_b128 v[180:183], v212 offset:34816
	ds_read_b128 v[184:187], v213 offset:32768
	ds_read_b128 v[216:219], v213 offset:34816
	ds_read_b128 v[220:223], v212 offset:36864
	ds_read_b128 v[224:227], v212 offset:38912
	ds_read_b128 v[230:233], v213 offset:36864
	ds_read_b128 v[234:237], v213 offset:38912
	global_load_lds_dwordx4 v138, s[48:49]
	s_mov_b32 m0, s35
	s_nop 0
	global_load_lds_dwordx4 v140, s[48:49]
	s_waitcnt vmcnt(8)
	s_waitcnt lgkmcnt(0)
	s_waitcnt lgkmcnt(0)
	v_mfma_f32_16x16x32_bf16 v[126:129], v[144:147], v[176:179], v[126:129]
	v_mfma_f32_16x16x32_bf16 v[126:129], v[148:151], v[184:187], v[126:129]
	v_mfma_f32_16x16x32_bf16 v[122:125], v[156:159], v[184:187], v[122:125]
	v_mfma_f32_16x16x32_bf16 v[122:125], v[152:155], v[176:179], v[122:125]
	s_barrier
	s_setprio 3
	v_mfma_f32_16x16x32_bf16 v[106:109], v[152:155], v[180:183], v[106:109]
	v_mfma_f32_16x16x32_bf16 v[106:109], v[156:159], v[216:219], v[106:109]
	v_mfma_f32_16x16x32_bf16 v[110:113], v[148:151], v[216:219], v[110:113]
	v_mfma_f32_16x16x32_bf16 v[110:113], v[144:147], v[180:183], v[110:113]
	v_mfma_f32_16x16x32_bf16 v[94:97], v[144:147], v[220:223], v[94:97]
	v_mfma_f32_16x16x32_bf16 v[94:97], v[148:151], v[230:233], v[94:97]
	v_mfma_f32_16x16x32_bf16 v[90:93], v[156:159], v[230:233], v[90:93]
	v_mfma_f32_16x16x32_bf16 v[90:93], v[152:155], v[220:223], v[90:93]
	v_mfma_f32_16x16x32_bf16 v[74:77], v[152:155], v[224:227], v[74:77]
	v_mfma_f32_16x16x32_bf16 v[74:77], v[156:159], v[234:237], v[74:77]
	v_mfma_f32_16x16x32_bf16 v[78:81], v[148:151], v[234:237], v[78:81]
	v_mfma_f32_16x16x32_bf16 v[78:81], v[144:147], v[224:227], v[78:81]
	s_setprio 0
	s_setprio 3
	v_mfma_f32_16x16x32_bf16 v[118:121], v[160:163], v[176:179], v[118:121]
	v_mfma_f32_16x16x32_bf16 v[118:121], v[164:167], v[184:187], v[118:121]
	v_mfma_f32_16x16x32_bf16 v[114:117], v[172:175], v[184:187], v[114:117]
	v_mfma_f32_16x16x32_bf16 v[114:117], v[168:171], v[176:179], v[114:117]
	v_mfma_f32_16x16x32_bf16 v[98:101], v[168:171], v[180:183], v[98:101]
	v_mfma_f32_16x16x32_bf16 v[98:101], v[172:175], v[216:219], v[98:101]
	v_mfma_f32_16x16x32_bf16 v[102:105], v[164:167], v[216:219], v[102:105]
	v_mfma_f32_16x16x32_bf16 v[102:105], v[160:163], v[180:183], v[102:105]
	v_mfma_f32_16x16x32_bf16 v[86:89], v[160:163], v[220:223], v[86:89]
	v_mfma_f32_16x16x32_bf16 v[86:89], v[164:167], v[230:233], v[86:89]
	v_mfma_f32_16x16x32_bf16 v[82:85], v[172:175], v[230:233], v[82:85]
	v_mfma_f32_16x16x32_bf16 v[82:85], v[168:171], v[220:223], v[82:85]
	v_mfma_f32_16x16x32_bf16 v[66:69], v[168:171], v[224:227], v[66:69]
	v_mfma_f32_16x16x32_bf16 v[66:69], v[172:175], v[234:237], v[66:69]
	v_mfma_f32_16x16x32_bf16 v[70:73], v[164:167], v[234:237], v[70:73]
	v_mfma_f32_16x16x32_bf16 v[70:73], v[160:163], v[224:227], v[70:73]
	s_setprio 0
	s_barrier
; #define PG8_STAGE(bufoff, gbase, voff) do { _Pragma("unroll") for (int _i = 0; _i < 2; ++_i) \
;         __builtin_amdgcn_global_load_lds((const unsigned*)((const char*)(gbase) + (voff)[_i]), (LAS unsigned*)(lds + (bufoff) + ldsw + _i * 8192), 16, 0, 0); } while (0)
; #define PG8_LDA(dst, b, h) do { _Pragma("unroll") for (int m = 0; m < 4; ++m) _Pragma("unroll") for (int k = 0; k < 2; ++k) dst[m][k] = *(const LAS bf16x8*)(lds + PG8_SA(b, h) + aoffk[k] + m * 2048); } while (0)
; #define PG8_WAIT_V(n) asm volatile("s_waitcnt vmcnt(" #n ")" ::: "memory")
; #define PG8_WAIT_L(n) asm volatile("s_waitcnt lgkmcnt(" #n ")" ::: "memory")
; #define PG8_BAR __builtin_amdgcn_s_barrier()
; #define PG8_SCHED __builtin_amdgcn_sched_barrier(0)
;     __device__ __forceinline__ void mid(Acc& acc, const Unit& u, int s, int wr, int wc, int fr, int fq) const {
;         int lo = (wr * 4 + wc) * 8192 + (fq * 16 + fr) * 16; asm volatile("" : "+v"(lo));
;         const unsigned char* gp = gate + ((size_t)(u.pm * 48 + s * 16 + u.pn) << 16) + lo;
;         u32x4 G[8][2];
; #pragma unroll
;         for (int i = 0; i < 8; ++i) { G[i][0] = __builtin_nontemporal_load((const u32x4*)(gp + i * 1024)); G[i][1] = __builtin_nontemporal_load((const u32x4*)(gp + (1 << 20) + i * 1024)); }
; template <class Epi, class Sched, class GemmT>
; __device__ __forceinline__ void gemm_phase(LAS unsigned char* lds, const GemmT& g, const Sched& S, const Epi& E, const int wid) {
;     ...
;                 PG8_LDA(At, 1, 1); PG8_STAGE(PG8_SB(1, 0), b3, vB2); PG8_STAGE(PG8_SB(1, 1), b3 + hB2, vB2); PG8_STAGE(PG8_SA(1, 0), a3, vA2);
;                 PG8_WAIT_V(8); PG8_WAIT_L(0); PG8_BAR; PG8_MMA(1, 0, At, B0); PG8_MMA(1, 1, At, B1); PG8_BAR; PG8_SCHED;
;             }
;             if constexpr (NSEG > 1) { if (sgi + 1 < NSEG) E.mid(acc, cur, sgi, wr, wc, fr, fq); }
	s_add_i32 s48, s60, s68
	v_lshl_add_u64 v[202:203], v[202:203], 0, s[20:21]
	s_mov_b32 m0, s48
	ds_read_b128 v[138:141], v212 offset:49152
	ds_read_b128 v[176:179], v212 offset:51200
	ds_read_b128 v[180:183], v213 offset:49152
	ds_read_b128 v[184:187], v213 offset:51200
	ds_read_b128 v[216:219], v212 offset:53248
	ds_read_b128 v[220:223], v212 offset:55296
	ds_read_b128 v[224:227], v213 offset:53248
	ds_read_b128 v[230:233], v213 offset:55296
	global_load_lds_dwordx4 v[202:203], off
	v_lshl_add_u64 v[202:203], v[238:239], 0, s[20:21]
	s_add_i32 m0, s48, 0x2000
	s_add_i32 s48, s61, s68
	global_load_lds_dwordx4 v[202:203], off
	v_lshl_add_u64 v[202:203], v[240:241], 0, s[20:21]
	s_mov_b32 m0, s48
	v_lshl_add_u64 v[188:189], v[188:189], 0, s[20:21]
	global_load_lds_dwordx4 v[202:203], off
	v_lshl_add_u64 v[202:203], v[242:243], 0, s[20:21]
	s_add_i32 m0, s48, 0x2000
	s_nop 0
	global_load_lds_dwordx4 v[202:203], off
	s_mov_b32 m0, s54
	s_nop 0
	global_load_lds_dwordx4 v[188:189], off
	v_lshl_add_u64 v[188:189], v[244:245], 0, s[20:21]
	s_mov_b32 m0, s55
	s_nop 0
	global_load_lds_dwordx4 v[188:189], off
	s_waitcnt vmcnt(8)
	s_waitcnt lgkmcnt(0)
	s_waitcnt lgkmcnt(0)
	v_mfma_f32_16x16x32_bf16 v[62:65], v[144:147], v[138:141], v[62:65]
	v_mfma_f32_16x16x32_bf16 v[62:65], v[148:151], v[180:183], v[62:65]
	v_mfma_f32_16x16x32_bf16 v[58:61], v[156:159], v[180:183], v[58:61]
	v_mfma_f32_16x16x32_bf16 v[58:61], v[152:155], v[138:141], v[58:61]
	s_barrier
	s_setprio 3
	v_mfma_f32_16x16x32_bf16 v[42:45], v[152:155], v[176:179], v[42:45]
	v_mfma_f32_16x16x32_bf16 v[42:45], v[156:159], v[184:187], v[42:45]
	v_mfma_f32_16x16x32_bf16 v[46:49], v[148:151], v[184:187], v[46:49]
	v_mfma_f32_16x16x32_bf16 v[46:49], v[144:147], v[176:179], v[46:49]
	v_mfma_f32_16x16x32_bf16 v[30:33], v[144:147], v[216:219], v[30:33]
	v_mfma_f32_16x16x32_bf16 v[30:33], v[148:151], v[224:227], v[30:33]
	v_mfma_f32_16x16x32_bf16 v[22:25], v[156:159], v[224:227], v[22:25]
	v_mfma_f32_16x16x32_bf16 v[22:25], v[152:155], v[216:219], v[22:25]
	v_mfma_f32_16x16x32_bf16 v[6:9], v[152:155], v[220:223], v[6:9]
	v_mfma_f32_16x16x32_bf16 v[6:9], v[156:159], v[230:233], v[6:9]
	v_mfma_f32_16x16x32_bf16 v[14:17], v[148:151], v[230:233], v[14:17]
	v_mfma_f32_16x16x32_bf16 v[14:17], v[144:147], v[220:223], v[14:17]
	s_setprio 0
	s_setprio 3
	v_mfma_f32_16x16x32_bf16 v[54:57], v[160:163], v[138:141], v[54:57]
	v_mfma_f32_16x16x32_bf16 v[54:57], v[164:167], v[180:183], v[54:57]
	v_mfma_f32_16x16x32_bf16 v[50:53], v[172:175], v[180:183], v[50:53]
	v_mfma_f32_16x16x32_bf16 v[50:53], v[168:171], v[138:141], v[50:53]
	v_mfma_f32_16x16x32_bf16 v[34:37], v[168:171], v[176:179], v[34:37]
	v_mfma_f32_16x16x32_bf16 v[34:37], v[172:175], v[184:187], v[34:37]
	v_mfma_f32_16x16x32_bf16 v[38:41], v[164:167], v[184:187], v[38:41]
	v_mfma_f32_16x16x32_bf16 v[38:41], v[160:163], v[176:179], v[38:41]
	v_mfma_f32_16x16x32_bf16 v[26:29], v[160:163], v[216:219], v[26:29]
	v_mfma_f32_16x16x32_bf16 v[26:29], v[164:167], v[224:227], v[26:29]
	v_mfma_f32_16x16x32_bf16 v[18:21], v[172:175], v[224:227], v[18:21]
	v_mfma_f32_16x16x32_bf16 v[18:21], v[168:171], v[216:219], v[18:21]
	v_mfma_f32_16x16x32_bf16 v[2:5], v[168:171], v[220:223], v[2:5]
	v_mfma_f32_16x16x32_bf16 v[2:5], v[172:175], v[230:233], v[2:5]
	v_mfma_f32_16x16x32_bf16 v[10:13], v[164:167], v[230:233], v[10:13]
	v_mfma_f32_16x16x32_bf16 v[10:13], v[160:163], v[220:223], v[10:13]
	s_setprio 0
	s_barrier
	s_add_u32 s56, s56, 0x100
	s_addc_u32 s57, s57, 0
	s_cmp_ge_u32 s90, s42
	s_cbranch_scc0 .LBB0_764
	s_and_b64 vcc, exec, s[52:53]
	s_cbranch_vccz .LBB0_767
	s_lshl_b32 s42, s83, 4
	s_add_i32 s42, s82, s42
	s_ashr_i32 s43, s42, 31
	s_lshl_b64 s[42:43], s[42:43], 16
	v_mov_b32_e32 v130, v210
	s_add_u32 s42, s22, s42
	s_addc_u32 s43, s23, s43
	v_ashrrev_i32_e32 v131, 31, v130
	v_lshl_add_u64 v[130:131], s[42:43], 0, v[130:131]
	v_add_co_u32_e32 v132, vcc, s69, v130
	s_mov_b32 s42, 0x101000
	s_nop 0
	v_addc_co_u32_e32 v133, vcc, 0, v131, vcc
	global_load_dwordx4 v[186:189], v[130:131], off nt
	v_add_co_u32_e32 v134, vcc, s42, v130
	s_movk_i32 s42, 0x1000
	s_nop 0
	v_addc_co_u32_e32 v135, vcc, 0, v131, vcc
	global_load_dwordx4 v[216:219], v[134:135], off offset:-4096 nt
	global_load_dwordx4 v[178:181], v[130:131], off offset:1024 nt
	global_load_dwordx4 v[182:185], v[132:133], off offset:1024 nt
	global_load_dwordx4 v[170:173], v[130:131], off offset:2048 nt
	global_load_dwordx4 v[174:177], v[132:133], off offset:2048 nt
	global_load_dwordx4 v[162:165], v[130:131], off offset:3072 nt
	global_load_dwordx4 v[166:169], v[132:133], off offset:3072 nt
	v_add_co_u32_e32 v130, vcc, s42, v130
	s_waitcnt vmcnt(0)
;     __device__ __forceinline__ void mid(Acc& acc, const Unit& u, int s, int wr, int wc, int fr, int fq) const {
;     ...
;         for (int i = 0; i < 8; ++i) { G[i][0] = __builtin_nontemporal_load((const u32x4*)(gp + i * 1024)); G[i][1] = __builtin_nontemporal_load((const u32x4*)(gp + (1 << 20) + i * 1024)); }
; #pragma unroll
;         for (int i = 0; i < 8; ++i) { const int ai = i >> 2, m = i & 3;
; #pragma unroll
;             for (int bj = 0; bj < 2; ++bj) {
;                 const u32x4 ga = G[i][0], gb = G[i][1];
;                 const u32x2 wa = bj == 0 ? (u32x2){ga.x, ga.y} : (u32x2){ga.z, ga.w}, wb = bj == 0 ? (u32x2){gb.x, gb.y} : (u32x2){gb.z, gb.w};
;                 float fa[8], fb[8]; gate_unpack8(wa, fa); gate_unpack8(wb, fb);
; #pragma unroll
;                 for (int e = 0; e < 8; ++e) fa[e] = fa[e] * __builtin_amdgcn_rcpf(fb[e]);
;                 f32x4& v0 = acc[ai][bj][m][0]; f32x4& v1 = acc[ai][bj][m][1];
;                 v0[0] *= fa[0]; v0[1] *= fa[1]; v0[2] *= fa[2]; v0[3] *= fa[3]; v1[0] *= fa[4]; v1[1] *= fa[5]; v1[2] *= fa[6]; v1[3] *= fa[7]; }
	v_cvt_f32_ubyte0_e32 v0, v216
	v_addc_co_u32_e32 v131, vcc, 0, v131, vcc
	global_load_dwordx4 v[154:157], v[130:131], off nt
	global_load_dwordx4 v[158:161], v[134:135], off nt
	global_load_dwordx4 v[146:149], v[130:131], off offset:1024 nt
	global_load_dwordx4 v[150:153], v[134:135], off offset:1024 nt
	global_load_dwordx4 v[138:141], v[130:131], off offset:2048 nt
	global_load_dwordx4 v[142:145], v[134:135], off offset:2048 nt
	s_nop 0
	global_load_dwordx4 v[130:133], v[130:131], off offset:3072 nt
	s_nop 0
	global_load_dwordx4 v[134:137], v[134:135], off offset:3072 nt
	v_cvt_f32_ubyte1_e32 v203, v216
	v_cvt_f32_ubyte2_e32 v215, v216
	v_cvt_f32_ubyte3_e32 v220, v216
	v_cvt_f32_ubyte0_e32 v221, v217
	v_cvt_f32_ubyte1_e32 v222, v217
	v_cvt_f32_ubyte2_e32 v223, v217
	v_cvt_f32_ubyte3_e32 v224, v217
	v_rcp_iflag_f32_e32 v202, v0
	v_rcp_iflag_f32_e32 v203, v203
	v_rcp_iflag_f32_e32 v216, v215
	v_rcp_iflag_f32_e32 v217, v220
	v_rcp_iflag_f32_e32 v220, v221
	v_rcp_iflag_f32_e32 v221, v222
	v_rcp_iflag_f32_e32 v222, v223
	v_rcp_iflag_f32_e32 v223, v224
	v_cvt_f32_ubyte3_e32 v225, v186
	v_cvt_f32_ubyte2_e32 v224, v186
	v_cvt_f32_ubyte1_e32 v227, v186
	v_cvt_f32_ubyte0_e32 v226, v186
	v_pk_mul_f32 v[202:203], v[202:203], v[226:227]
	v_pk_mul_f32 v[216:217], v[216:217], v[224:225]
	v_pk_mul_f32 v[126:127], v[126:127], v[202:203]
	v_pk_mul_f32 v[128:129], v[128:129], v[216:217]
	v_cvt_f32_ubyte3_e32 v203, v187
	v_cvt_f32_ubyte2_e32 v202, v187
	v_cvt_f32_ubyte1_e32 v217, v187
	v_cvt_f32_ubyte0_e32 v216, v187
	v_pk_mul_f32 v[186:187], v[220:221], v[216:217]
	v_pk_mul_f32 v[202:203], v[222:223], v[202:203]
	v_pk_mul_f32 v[122:123], v[122:123], v[186:187]
	v_pk_mul_f32 v[124:125], v[124:125], v[202:203]
	v_cvt_f32_ubyte0_e32 v0, v218
	v_cvt_f32_ubyte1_e32 v186, v218
	v_cvt_f32_ubyte2_e32 v187, v218
	v_cvt_f32_ubyte3_e32 v202, v218
	v_cvt_f32_ubyte0_e32 v203, v219
	v_cvt_f32_ubyte1_e32 v215, v219
	v_cvt_f32_ubyte2_e32 v220, v219
	v_cvt_f32_ubyte3_e32 v221, v219
	v_rcp_iflag_f32_e32 v216, v0
	v_rcp_iflag_f32_e32 v217, v186
	v_rcp_iflag_f32_e32 v218, v187
	v_rcp_iflag_f32_e32 v219, v202
	v_rcp_iflag_f32_e32 v202, v203
	v_rcp_iflag_f32_e32 v203, v215
	v_rcp_iflag_f32_e32 v186, v220
	v_rcp_iflag_f32_e32 v187, v221
	v_cvt_f32_ubyte3_e32 v221, v188
	v_cvt_f32_ubyte2_e32 v220, v188
	v_cvt_f32_ubyte1_e32 v223, v188
	v_cvt_f32_ubyte0_e32 v222, v188
	v_pk_mul_f32 v[216:217], v[216:217], v[222:223]
	v_pk_mul_f32 v[218:219], v[218:219], v[220:221]
	v_pk_mul_f32 v[118:119], v[118:119], v[216:217]
	v_pk_mul_f32 v[120:121], v[120:121], v[218:219]
	v_cvt_f32_ubyte3_e32 v217, v189
	v_cvt_f32_ubyte2_e32 v216, v189
	v_cvt_f32_ubyte1_e32 v219, v189
	v_cvt_f32_ubyte0_e32 v218, v189
	v_pk_mul_f32 v[188:189], v[202:203], v[218:219]
	v_pk_mul_f32 v[186:187], v[186:187], v[216:217]
	v_pk_mul_f32 v[114:115], v[114:115], v[188:189]
	v_pk_mul_f32 v[116:117], v[116:117], v[186:187]
	v_cvt_f32_ubyte0_e32 v0, v182
	v_cvt_f32_ubyte1_e32 v186, v182
	v_cvt_f32_ubyte2_e32 v187, v182
	v_cvt_f32_ubyte3_e32 v188, v182
	v_cvt_f32_ubyte0_e32 v189, v183
	v_cvt_f32_ubyte1_e32 v202, v183
	v_cvt_f32_ubyte2_e32 v203, v183
	v_cvt_f32_ubyte3_e32 v215, v183
	v_rcp_iflag_f32_e32 v182, v0
	v_rcp_iflag_f32_e32 v183, v186
	v_rcp_iflag_f32_e32 v186, v187
	v_rcp_iflag_f32_e32 v187, v188
	v_rcp_iflag_f32_e32 v188, v189
	v_rcp_iflag_f32_e32 v189, v202
	v_rcp_iflag_f32_e32 v202, v203
	v_rcp_iflag_f32_e32 v203, v215
	v_cvt_f32_ubyte3_e32 v217, v178
	v_cvt_f32_ubyte2_e32 v216, v178
	v_cvt_f32_ubyte1_e32 v219, v178
	v_cvt_f32_ubyte0_e32 v218, v178
	v_pk_mul_f32 v[182:183], v[182:183], v[218:219]
	v_pk_mul_f32 v[186:187], v[186:187], v[216:217]
	v_pk_mul_f32 v[110:111], v[110:111], v[182:183]
	v_pk_mul_f32 v[112:113], v[112:113], v[186:187]
	v_cvt_f32_ubyte3_e32 v183, v179
	v_cvt_f32_ubyte2_e32 v182, v179
	v_cvt_f32_ubyte1_e32 v187, v179
	v_cvt_f32_ubyte0_e32 v186, v179
	v_pk_mul_f32 v[178:179], v[188:189], v[186:187]
	v_pk_mul_f32 v[182:183], v[202:203], v[182:183]
	v_pk_mul_f32 v[106:107], v[106:107], v[178:179]
	v_pk_mul_f32 v[108:109], v[108:109], v[182:183]
	v_cvt_f32_ubyte0_e32 v0, v184
	v_cvt_f32_ubyte1_e32 v179, v184
	v_cvt_f32_ubyte2_e32 v182, v184
	v_cvt_f32_ubyte3_e32 v183, v184
	v_rcp_iflag_f32_e32 v178, v0
	v_rcp_iflag_f32_e32 v179, v179
	v_rcp_iflag_f32_e32 v182, v182
	v_rcp_iflag_f32_e32 v183, v183
	v_cvt_f32_ubyte0_e32 v184, v185
	v_cvt_f32_ubyte1_e32 v186, v185
	v_cvt_f32_ubyte2_e32 v187, v185
	v_cvt_f32_ubyte3_e32 v188, v185
	v_rcp_iflag_f32_e32 v184, v184
	v_rcp_iflag_f32_e32 v185, v186
	v_rcp_iflag_f32_e32 v186, v187
	v_rcp_iflag_f32_e32 v187, v188
	v_cvt_f32_ubyte3_e32 v189, v180
	v_cvt_f32_ubyte2_e32 v188, v180
	v_cvt_f32_ubyte1_e32 v203, v180
	v_cvt_f32_ubyte0_e32 v202, v180
	v_pk_mul_f32 v[178:179], v[178:179], v[202:203]
	v_pk_mul_f32 v[182:183], v[182:183], v[188:189]
	v_pk_mul_f32 v[102:103], v[102:103], v[178:179]
	v_pk_mul_f32 v[104:105], v[104:105], v[182:183]
	v_cvt_f32_ubyte3_e32 v179, v181
	v_cvt_f32_ubyte2_e32 v178, v181
	v_cvt_f32_ubyte1_e32 v183, v181
	v_cvt_f32_ubyte0_e32 v182, v181
	v_pk_mul_f32 v[180:181], v[184:185], v[182:183]
	v_pk_mul_f32 v[178:179], v[186:187], v[178:179]
	v_pk_mul_f32 v[98:99], v[98:99], v[180:181]
	v_pk_mul_f32 v[100:101], v[100:101], v[178:179]
	v_cvt_f32_ubyte0_e32 v0, v174
	v_cvt_f32_ubyte1_e32 v178, v174
	v_cvt_f32_ubyte2_e32 v179, v174
	v_cvt_f32_ubyte3_e32 v180, v174
	v_cvt_f32_ubyte0_e32 v181, v175
	v_cvt_f32_ubyte1_e32 v182, v175
	v_cvt_f32_ubyte2_e32 v183, v175
	v_cvt_f32_ubyte3_e32 v184, v175
	v_rcp_iflag_f32_e32 v174, v0
	v_rcp_iflag_f32_e32 v175, v178
	v_rcp_iflag_f32_e32 v178, v179
	v_rcp_iflag_f32_e32 v179, v180
	v_rcp_iflag_f32_e32 v180, v181
;     __device__ __forceinline__ void mid(Acc& acc, const Unit& u, int s, int wr, int wc, int fr, int fq) const {
;     ...
;         for (int i = 0; i < 8; ++i) { const int ai = i >> 2, m = i & 3;
; #pragma unroll
;             for (int bj = 0; bj < 2; ++bj) {
;                 const u32x4 ga = G[i][0], gb = G[i][1];
;                 const u32x2 wa = bj == 0 ? (u32x2){ga.x, ga.y} : (u32x2){ga.z, ga.w}, wb = bj == 0 ? (u32x2){gb.x, gb.y} : (u32x2){gb.z, gb.w};
;                 float fa[8], fb[8]; gate_unpack8(wa, fa); gate_unpack8(wb, fb);
; #pragma unroll
;                 for (int e = 0; e < 8; ++e) fa[e] = fa[e] * __builtin_amdgcn_rcpf(fb[e]);
;                 f32x4& v0 = acc[ai][bj][m][0]; f32x4& v1 = acc[ai][bj][m][1];
;                 v0[0] *= fa[0]; v0[1] *= fa[1]; v0[2] *= fa[2]; v0[3] *= fa[3]; v1[0] *= fa[4]; v1[1] *= fa[5]; v1[2] *= fa[6]; v1[3] *= fa[7]; }
;             __builtin_amdgcn_sched_barrier(0); }
	v_rcp_iflag_f32_e32 v181, v182
	v_rcp_iflag_f32_e32 v182, v183
	v_rcp_iflag_f32_e32 v183, v184
	v_cvt_f32_ubyte3_e32 v185, v170
	v_cvt_f32_ubyte2_e32 v184, v170
	v_cvt_f32_ubyte1_e32 v187, v170
	v_cvt_f32_ubyte0_e32 v186, v170
	v_pk_mul_f32 v[174:175], v[174:175], v[186:187]
	v_pk_mul_f32 v[178:179], v[178:179], v[184:185]
	v_pk_mul_f32 v[94:95], v[94:95], v[174:175]
	v_pk_mul_f32 v[96:97], v[96:97], v[178:179]
	v_cvt_f32_ubyte3_e32 v175, v171
	v_cvt_f32_ubyte2_e32 v174, v171
	v_cvt_f32_ubyte1_e32 v179, v171
	v_cvt_f32_ubyte0_e32 v178, v171
	v_pk_mul_f32 v[170:171], v[180:181], v[178:179]
	v_pk_mul_f32 v[174:175], v[182:183], v[174:175]
	v_pk_mul_f32 v[90:91], v[90:91], v[170:171]
	v_pk_mul_f32 v[92:93], v[92:93], v[174:175]
	v_cvt_f32_ubyte0_e32 v0, v176
	v_cvt_f32_ubyte1_e32 v171, v176
	v_cvt_f32_ubyte2_e32 v174, v176
	v_cvt_f32_ubyte3_e32 v175, v176
	v_rcp_iflag_f32_e32 v170, v0
	v_rcp_iflag_f32_e32 v171, v171
	v_rcp_iflag_f32_e32 v174, v174
	v_rcp_iflag_f32_e32 v175, v175
	v_cvt_f32_ubyte0_e32 v176, v177
	v_cvt_f32_ubyte1_e32 v178, v177
	v_cvt_f32_ubyte2_e32 v179, v177
	v_cvt_f32_ubyte3_e32 v180, v177
	v_rcp_iflag_f32_e32 v176, v176
	v_rcp_iflag_f32_e32 v177, v178
	v_rcp_iflag_f32_e32 v178, v179
	v_rcp_iflag_f32_e32 v179, v180
	v_cvt_f32_ubyte3_e32 v181, v172
	v_cvt_f32_ubyte2_e32 v180, v172
	v_cvt_f32_ubyte1_e32 v183, v172
	v_cvt_f32_ubyte0_e32 v182, v172
	v_pk_mul_f32 v[170:171], v[170:171], v[182:183]
	v_pk_mul_f32 v[174:175], v[174:175], v[180:181]
	v_pk_mul_f32 v[86:87], v[86:87], v[170:171]
	v_pk_mul_f32 v[88:89], v[88:89], v[174:175]
	v_cvt_f32_ubyte3_e32 v171, v173
	v_cvt_f32_ubyte2_e32 v170, v173
	v_cvt_f32_ubyte1_e32 v175, v173
	v_cvt_f32_ubyte0_e32 v174, v173
	v_pk_mul_f32 v[172:173], v[176:177], v[174:175]
	v_pk_mul_f32 v[170:171], v[178:179], v[170:171]
	v_pk_mul_f32 v[82:83], v[82:83], v[172:173]
	v_pk_mul_f32 v[84:85], v[84:85], v[170:171]
	v_cvt_f32_ubyte0_e32 v0, v166
	v_cvt_f32_ubyte1_e32 v170, v166
	v_cvt_f32_ubyte2_e32 v171, v166
	v_cvt_f32_ubyte3_e32 v172, v166
	v_cvt_f32_ubyte0_e32 v173, v167
	v_cvt_f32_ubyte1_e32 v174, v167
	v_cvt_f32_ubyte2_e32 v175, v167
	v_cvt_f32_ubyte3_e32 v176, v167
	v_rcp_iflag_f32_e32 v166, v0
	v_rcp_iflag_f32_e32 v167, v170
	v_rcp_iflag_f32_e32 v170, v171
	v_rcp_iflag_f32_e32 v171, v172
	v_rcp_iflag_f32_e32 v172, v173
	v_rcp_iflag_f32_e32 v173, v174
	v_rcp_iflag_f32_e32 v174, v175
	v_rcp_iflag_f32_e32 v175, v176
	v_cvt_f32_ubyte3_e32 v177, v162
	v_cvt_f32_ubyte2_e32 v176, v162
	v_cvt_f32_ubyte1_e32 v179, v162
	v_cvt_f32_ubyte0_e32 v178, v162
	v_pk_mul_f32 v[166:167], v[166:167], v[178:179]
	v_pk_mul_f32 v[170:171], v[170:171], v[176:177]
	v_pk_mul_f32 v[78:79], v[78:79], v[166:167]
	v_pk_mul_f32 v[80:81], v[80:81], v[170:171]
	v_cvt_f32_ubyte3_e32 v167, v163
	v_cvt_f32_ubyte2_e32 v166, v163
	v_cvt_f32_ubyte1_e32 v171, v163
	v_cvt_f32_ubyte0_e32 v170, v163
	v_pk_mul_f32 v[162:163], v[172:173], v[170:171]
	v_pk_mul_f32 v[166:167], v[174:175], v[166:167]
	v_pk_mul_f32 v[74:75], v[74:75], v[162:163]
	v_pk_mul_f32 v[76:77], v[76:77], v[166:167]
	v_cvt_f32_ubyte0_e32 v0, v168
	v_cvt_f32_ubyte1_e32 v163, v168
	v_cvt_f32_ubyte2_e32 v166, v168
	v_cvt_f32_ubyte3_e32 v167, v168
	v_rcp_iflag_f32_e32 v162, v0
	v_rcp_iflag_f32_e32 v163, v163
	v_rcp_iflag_f32_e32 v166, v166
	v_rcp_iflag_f32_e32 v167, v167
	v_cvt_f32_ubyte0_e32 v168, v169
	v_cvt_f32_ubyte1_e32 v170, v169
	v_cvt_f32_ubyte2_e32 v171, v169
	v_cvt_f32_ubyte3_e32 v172, v169
	v_rcp_iflag_f32_e32 v168, v168
	v_rcp_iflag_f32_e32 v169, v170
	v_rcp_iflag_f32_e32 v170, v171
	v_rcp_iflag_f32_e32 v171, v172
	v_cvt_f32_ubyte3_e32 v173, v164
	v_cvt_f32_ubyte2_e32 v172, v164
	v_cvt_f32_ubyte1_e32 v175, v164
	v_cvt_f32_ubyte0_e32 v174, v164
	v_pk_mul_f32 v[162:163], v[162:163], v[174:175]
	v_pk_mul_f32 v[166:167], v[166:167], v[172:173]
	v_pk_mul_f32 v[70:71], v[70:71], v[162:163]
	v_pk_mul_f32 v[72:73], v[72:73], v[166:167]
	v_cvt_f32_ubyte3_e32 v163, v165
	v_cvt_f32_ubyte2_e32 v162, v165
	v_cvt_f32_ubyte1_e32 v167, v165
	v_cvt_f32_ubyte0_e32 v166, v165
	v_pk_mul_f32 v[164:165], v[168:169], v[166:167]
	v_pk_mul_f32 v[162:163], v[170:171], v[162:163]
	v_pk_mul_f32 v[66:67], v[66:67], v[164:165]
	v_pk_mul_f32 v[68:69], v[68:69], v[162:163]
	s_waitcnt vmcnt(6)
	v_cvt_f32_ubyte0_e32 v0, v158
	v_cvt_f32_ubyte1_e32 v162, v158
	v_cvt_f32_ubyte2_e32 v163, v158
	v_cvt_f32_ubyte3_e32 v164, v158
	v_cvt_f32_ubyte0_e32 v165, v159
	v_cvt_f32_ubyte1_e32 v166, v159
	v_cvt_f32_ubyte2_e32 v167, v159
	v_cvt_f32_ubyte3_e32 v168, v159
	v_rcp_iflag_f32_e32 v158, v0
	v_rcp_iflag_f32_e32 v159, v162
	v_rcp_iflag_f32_e32 v162, v163
	v_rcp_iflag_f32_e32 v163, v164
	v_rcp_iflag_f32_e32 v164, v165
	v_rcp_iflag_f32_e32 v165, v166
	v_rcp_iflag_f32_e32 v166, v167
	v_rcp_iflag_f32_e32 v167, v168
	v_cvt_f32_ubyte3_e32 v169, v154
	v_cvt_f32_ubyte2_e32 v168, v154
	v_cvt_f32_ubyte1_e32 v171, v154
	v_cvt_f32_ubyte0_e32 v170, v154
	v_pk_mul_f32 v[158:159], v[158:159], v[170:171]
	v_pk_mul_f32 v[162:163], v[162:163], v[168:169]
	v_pk_mul_f32 v[62:63], v[62:63], v[158:159]
	v_pk_mul_f32 v[64:65], v[64:65], v[162:163]
	v_cvt_f32_ubyte3_e32 v159, v155
	v_cvt_f32_ubyte2_e32 v158, v155
	v_cvt_f32_ubyte1_e32 v163, v155
	v_cvt_f32_ubyte0_e32 v162, v155
	v_pk_mul_f32 v[154:155], v[164:165], v[162:163]
	v_pk_mul_f32 v[158:159], v[166:167], v[158:159]
	v_pk_mul_f32 v[58:59], v[58:59], v[154:155]
	v_pk_mul_f32 v[60:61], v[60:61], v[158:159]
	v_cvt_f32_ubyte0_e32 v0, v160
	v_cvt_f32_ubyte1_e32 v155, v160
	v_cvt_f32_ubyte2_e32 v158, v160
	v_cvt_f32_ubyte3_e32 v159, v160
	v_rcp_iflag_f32_e32 v154, v0
	v_rcp_iflag_f32_e32 v155, v155
	v_rcp_iflag_f32_e32 v158, v158
	v_rcp_iflag_f32_e32 v159, v159
	v_cvt_f32_ubyte0_e32 v160, v161
	v_cvt_f32_ubyte1_e32 v162, v161
	v_cvt_f32_ubyte2_e32 v163, v161
	v_cvt_f32_ubyte3_e32 v164, v161
	v_rcp_iflag_f32_e32 v160, v160
	v_rcp_iflag_f32_e32 v161, v162
	v_rcp_iflag_f32_e32 v162, v163
	v_rcp_iflag_f32_e32 v163, v164
	v_cvt_f32_ubyte3_e32 v165, v156
	v_cvt_f32_ubyte2_e32 v164, v156
	v_cvt_f32_ubyte1_e32 v167, v156
	v_cvt_f32_ubyte0_e32 v166, v156
	v_pk_mul_f32 v[154:155], v[154:155], v[166:167]
	v_pk_mul_f32 v[158:159], v[158:159], v[164:165]
	v_pk_mul_f32 v[54:55], v[54:55], v[154:155]
	v_pk_mul_f32 v[56:57], v[56:57], v[158:159]
	v_cvt_f32_ubyte3_e32 v155, v157
	v_cvt_f32_ubyte2_e32 v154, v157
	v_cvt_f32_ubyte1_e32 v159, v157
	v_cvt_f32_ubyte0_e32 v158, v157
	v_pk_mul_f32 v[156:157], v[160:161], v[158:159]
	v_pk_mul_f32 v[154:155], v[162:163], v[154:155]
	v_pk_mul_f32 v[50:51], v[50:51], v[156:157]
	v_pk_mul_f32 v[52:53], v[52:53], v[154:155]
	s_waitcnt vmcnt(4)
;     __device__ __forceinline__ void mid(Acc& acc, const Unit& u, int s, int wr, int wc, int fr, int fq) const {
;     ...
;         for (int i = 0; i < 8; ++i) { const int ai = i >> 2, m = i & 3;
; #pragma unroll
;             for (int bj = 0; bj < 2; ++bj) {
;                 const u32x4 ga = G[i][0], gb = G[i][1];
;                 const u32x2 wa = bj == 0 ? (u32x2){ga.x, ga.y} : (u32x2){ga.z, ga.w}, wb = bj == 0 ? (u32x2){gb.x, gb.y} : (u32x2){gb.z, gb.w};
;                 float fa[8], fb[8]; gate_unpack8(wa, fa); gate_unpack8(wb, fb);
; #pragma unroll
;                 for (int e = 0; e < 8; ++e) fa[e] = fa[e] * __builtin_amdgcn_rcpf(fb[e]);
;                 f32x4& v0 = acc[ai][bj][m][0]; f32x4& v1 = acc[ai][bj][m][1];
;                 v0[0] *= fa[0]; v0[1] *= fa[1]; v0[2] *= fa[2]; v0[3] *= fa[3]; v1[0] *= fa[4]; v1[1] *= fa[5]; v1[2] *= fa[6]; v1[3] *= fa[7]; }
;             __builtin_amdgcn_sched_barrier(0); }
	v_cvt_f32_ubyte0_e32 v0, v150
	v_cvt_f32_ubyte1_e32 v154, v150
	v_cvt_f32_ubyte2_e32 v155, v150
	v_cvt_f32_ubyte3_e32 v156, v150
	v_cvt_f32_ubyte0_e32 v157, v151
	v_cvt_f32_ubyte1_e32 v158, v151
	v_cvt_f32_ubyte2_e32 v159, v151
	v_cvt_f32_ubyte3_e32 v160, v151
	v_rcp_iflag_f32_e32 v150, v0
	v_rcp_iflag_f32_e32 v151, v154
	v_rcp_iflag_f32_e32 v154, v155
	v_rcp_iflag_f32_e32 v155, v156
	v_rcp_iflag_f32_e32 v156, v157
	v_rcp_iflag_f32_e32 v157, v158
	v_rcp_iflag_f32_e32 v158, v159
	v_rcp_iflag_f32_e32 v159, v160
	v_cvt_f32_ubyte3_e32 v161, v146
	v_cvt_f32_ubyte2_e32 v160, v146
	v_cvt_f32_ubyte1_e32 v163, v146
	v_cvt_f32_ubyte0_e32 v162, v146
	v_pk_mul_f32 v[150:151], v[150:151], v[162:163]
	v_pk_mul_f32 v[154:155], v[154:155], v[160:161]
	v_pk_mul_f32 v[46:47], v[46:47], v[150:151]
	v_pk_mul_f32 v[48:49], v[48:49], v[154:155]
	v_cvt_f32_ubyte3_e32 v151, v147
	v_cvt_f32_ubyte2_e32 v150, v147
	v_cvt_f32_ubyte1_e32 v155, v147
	v_cvt_f32_ubyte0_e32 v154, v147
	v_pk_mul_f32 v[146:147], v[156:157], v[154:155]
	v_pk_mul_f32 v[150:151], v[158:159], v[150:151]
	v_pk_mul_f32 v[42:43], v[42:43], v[146:147]
	v_pk_mul_f32 v[44:45], v[44:45], v[150:151]
	v_cvt_f32_ubyte0_e32 v0, v152
	v_cvt_f32_ubyte1_e32 v147, v152
	v_cvt_f32_ubyte2_e32 v150, v152
	v_cvt_f32_ubyte3_e32 v151, v152
	v_rcp_iflag_f32_e32 v146, v0
	v_rcp_iflag_f32_e32 v147, v147
	v_rcp_iflag_f32_e32 v150, v150
	v_rcp_iflag_f32_e32 v151, v151
	v_cvt_f32_ubyte0_e32 v152, v153
	v_cvt_f32_ubyte1_e32 v154, v153
	v_cvt_f32_ubyte2_e32 v155, v153
	v_cvt_f32_ubyte3_e32 v156, v153
	v_rcp_iflag_f32_e32 v152, v152
	v_rcp_iflag_f32_e32 v153, v154
	v_rcp_iflag_f32_e32 v154, v155
	v_rcp_iflag_f32_e32 v155, v156
	v_cvt_f32_ubyte3_e32 v157, v148
	v_cvt_f32_ubyte2_e32 v156, v148
	v_cvt_f32_ubyte1_e32 v159, v148
	v_cvt_f32_ubyte0_e32 v158, v148
	v_pk_mul_f32 v[146:147], v[146:147], v[158:159]
	v_pk_mul_f32 v[150:151], v[150:151], v[156:157]
	v_pk_mul_f32 v[38:39], v[38:39], v[146:147]
	v_pk_mul_f32 v[40:41], v[40:41], v[150:151]
	v_cvt_f32_ubyte3_e32 v147, v149
	v_cvt_f32_ubyte2_e32 v146, v149
	v_cvt_f32_ubyte1_e32 v151, v149
	v_cvt_f32_ubyte0_e32 v150, v149
	v_pk_mul_f32 v[148:149], v[152:153], v[150:151]
	v_pk_mul_f32 v[146:147], v[154:155], v[146:147]
	v_pk_mul_f32 v[34:35], v[34:35], v[148:149]
	v_pk_mul_f32 v[36:37], v[36:37], v[146:147]
	s_waitcnt vmcnt(2)
	v_cvt_f32_ubyte0_e32 v0, v142
	v_cvt_f32_ubyte1_e32 v146, v142
	v_cvt_f32_ubyte2_e32 v147, v142
	v_cvt_f32_ubyte3_e32 v148, v142
	v_cvt_f32_ubyte0_e32 v149, v143
	v_cvt_f32_ubyte1_e32 v150, v143
	v_cvt_f32_ubyte2_e32 v151, v143
	v_cvt_f32_ubyte3_e32 v152, v143
	v_rcp_iflag_f32_e32 v142, v0
	v_rcp_iflag_f32_e32 v143, v146
	v_rcp_iflag_f32_e32 v146, v147
	v_rcp_iflag_f32_e32 v147, v148
	v_rcp_iflag_f32_e32 v148, v149
	v_rcp_iflag_f32_e32 v149, v150
	v_rcp_iflag_f32_e32 v150, v151
	v_rcp_iflag_f32_e32 v151, v152
	v_cvt_f32_ubyte3_e32 v153, v138
	v_cvt_f32_ubyte2_e32 v152, v138
	v_cvt_f32_ubyte1_e32 v155, v138
	v_cvt_f32_ubyte0_e32 v154, v138
	v_pk_mul_f32 v[142:143], v[142:143], v[154:155]
	v_pk_mul_f32 v[146:147], v[146:147], v[152:153]
	v_pk_mul_f32 v[30:31], v[30:31], v[142:143]
	v_pk_mul_f32 v[32:33], v[32:33], v[146:147]
	v_cvt_f32_ubyte3_e32 v143, v139
	v_cvt_f32_ubyte2_e32 v142, v139
	v_cvt_f32_ubyte1_e32 v147, v139
	v_cvt_f32_ubyte0_e32 v146, v139
	v_pk_mul_f32 v[138:139], v[148:149], v[146:147]
	v_pk_mul_f32 v[142:143], v[150:151], v[142:143]
	v_pk_mul_f32 v[22:23], v[22:23], v[138:139]
	v_pk_mul_f32 v[24:25], v[24:25], v[142:143]
	v_cvt_f32_ubyte0_e32 v0, v144
	v_cvt_f32_ubyte1_e32 v139, v144
	v_cvt_f32_ubyte2_e32 v142, v144
	v_cvt_f32_ubyte3_e32 v143, v144
	v_rcp_iflag_f32_e32 v138, v0
	v_rcp_iflag_f32_e32 v139, v139
	v_rcp_iflag_f32_e32 v142, v142
	v_rcp_iflag_f32_e32 v143, v143
	v_cvt_f32_ubyte0_e32 v144, v145
	v_cvt_f32_ubyte1_e32 v146, v145
	v_cvt_f32_ubyte2_e32 v147, v145
	v_cvt_f32_ubyte3_e32 v148, v145
	v_rcp_iflag_f32_e32 v144, v144
	v_rcp_iflag_f32_e32 v145, v146
	v_rcp_iflag_f32_e32 v146, v147
	v_rcp_iflag_f32_e32 v147, v148
	v_cvt_f32_ubyte3_e32 v149, v140
	v_cvt_f32_ubyte2_e32 v148, v140
	v_cvt_f32_ubyte1_e32 v151, v140
	v_cvt_f32_ubyte0_e32 v150, v140
	v_pk_mul_f32 v[138:139], v[138:139], v[150:151]
	v_pk_mul_f32 v[142:143], v[142:143], v[148:149]
	v_pk_mul_f32 v[26:27], v[26:27], v[138:139]
	v_pk_mul_f32 v[28:29], v[28:29], v[142:143]
	v_cvt_f32_ubyte3_e32 v139, v141
	v_cvt_f32_ubyte2_e32 v138, v141
	v_cvt_f32_ubyte1_e32 v143, v141
	v_cvt_f32_ubyte0_e32 v142, v141
	v_pk_mul_f32 v[140:141], v[144:145], v[142:143]
	v_pk_mul_f32 v[138:139], v[146:147], v[138:139]
	v_pk_mul_f32 v[18:19], v[18:19], v[140:141]
	v_pk_mul_f32 v[20:21], v[20:21], v[138:139]
	s_waitcnt vmcnt(0)
	v_cvt_f32_ubyte0_e32 v0, v134
	v_cvt_f32_ubyte1_e32 v138, v134
	v_cvt_f32_ubyte2_e32 v139, v134
	v_cvt_f32_ubyte3_e32 v140, v134
	v_cvt_f32_ubyte0_e32 v141, v135
	v_cvt_f32_ubyte1_e32 v142, v135
	v_cvt_f32_ubyte2_e32 v143, v135
	v_cvt_f32_ubyte3_e32 v144, v135
	v_rcp_iflag_f32_e32 v134, v0
	v_rcp_iflag_f32_e32 v135, v138
	v_rcp_iflag_f32_e32 v138, v139
	v_rcp_iflag_f32_e32 v139, v140
	v_rcp_iflag_f32_e32 v140, v141
	v_rcp_iflag_f32_e32 v141, v142
	v_rcp_iflag_f32_e32 v142, v143
	v_rcp_iflag_f32_e32 v143, v144
	v_cvt_f32_ubyte3_e32 v145, v130
	v_cvt_f32_ubyte2_e32 v144, v130
	v_cvt_f32_ubyte1_e32 v147, v130
	v_cvt_f32_ubyte0_e32 v146, v130
	v_pk_mul_f32 v[134:135], v[134:135], v[146:147]
	v_pk_mul_f32 v[138:139], v[138:139], v[144:145]
	v_pk_mul_f32 v[14:15], v[14:15], v[134:135]
	v_pk_mul_f32 v[16:17], v[16:17], v[138:139]
	v_cvt_f32_ubyte3_e32 v135, v131
	v_cvt_f32_ubyte2_e32 v134, v131
	v_cvt_f32_ubyte1_e32 v139, v131
	v_cvt_f32_ubyte0_e32 v138, v131
	v_pk_mul_f32 v[130:131], v[140:141], v[138:139]
	v_pk_mul_f32 v[134:135], v[142:143], v[134:135]
	v_pk_mul_f32 v[6:7], v[6:7], v[130:131]
	v_pk_mul_f32 v[8:9], v[8:9], v[134:135]
	v_cvt_f32_ubyte0_e32 v0, v136
	v_cvt_f32_ubyte1_e32 v131, v136
	v_cvt_f32_ubyte2_e32 v134, v136
	v_cvt_f32_ubyte3_e32 v135, v136
	v_rcp_iflag_f32_e32 v130, v0
	v_rcp_iflag_f32_e32 v131, v131
	v_rcp_iflag_f32_e32 v134, v134
	v_rcp_iflag_f32_e32 v135, v135
	v_cvt_f32_ubyte0_e32 v136, v137
	v_cvt_f32_ubyte1_e32 v138, v137
	v_cvt_f32_ubyte2_e32 v139, v137
	v_cvt_f32_ubyte3_e32 v140, v137
	v_rcp_iflag_f32_e32 v136, v136
	v_rcp_iflag_f32_e32 v137, v138
	v_rcp_iflag_f32_e32 v138, v139
	v_rcp_iflag_f32_e32 v139, v140
	v_cvt_f32_ubyte3_e32 v141, v132
	v_cvt_f32_ubyte2_e32 v140, v132
	v_cvt_f32_ubyte1_e32 v143, v132
	v_cvt_f32_ubyte0_e32 v142, v132
	v_pk_mul_f32 v[130:131], v[130:131], v[142:143]
	v_pk_mul_f32 v[134:135], v[134:135], v[140:141]
	v_pk_mul_f32 v[10:11], v[10:11], v[130:131]
	v_pk_mul_f32 v[12:13], v[12:13], v[134:135]
	v_cvt_f32_ubyte3_e32 v131, v133
	v_cvt_f32_ubyte2_e32 v130, v133
	v_cvt_f32_ubyte1_e32 v135, v133
	v_cvt_f32_ubyte0_e32 v134, v133
	v_pk_mul_f32 v[132:133], v[136:137], v[134:135]
	v_pk_mul_f32 v[130:131], v[138:139], v[130:131]
	v_pk_mul_f32 v[2:3], v[2:3], v[132:133]
	v_pk_mul_f32 v[4:5], v[4:5], v[130:131]

; #define PG8_STAGE(bufoff, gbase, voff) do { _Pragma("unroll") for (int _i = 0; _i < 2; ++_i) \
;         __builtin_amdgcn_global_load_lds((const unsigned*)((const char*)(gbase) + (voff)[_i]), (LAS unsigned*)(lds + (bufoff) + ldsw + _i * 8192), 16, 0, 0); } while (0)
; #define PG8_LDA(dst, b, h) do { _Pragma("unroll") for (int m = 0; m < 4; ++m) _Pragma("unroll") for (int k = 0; k < 2; ++k) dst[m][k] = *(const LAS bf16x8*)(lds + PG8_SA(b, h) + aoffk[k] + m * 2048); } while (0)
; #define PG8_BAR __builtin_amdgcn_s_barrier()
; template <class Epi, class Sched, class GemmT>
; __device__ __forceinline__ void gemm_phase(LAS unsigned char* lds, const GemmT& g, const Sched& S, const Epi& E, const int wid) {
;     ...
;             for (int t = 0; t < nt; t += 2) {
;                 const bool last = (t == nt - 2);
;                 const char* a1 = cA + (size_t)(t + 1) * kstep;
;                 const char* a2 = last ? ns.A : cA + (size_t)(t + 2) * kstep; const char* b2 = last ? ns.B : cB + (size_t)(t + 2) * kstep;
;                 const char* a3 = a2 + kstep; const char* b3 = b2 + kstep;
;                 unsigned vA2[2], vB2[2];
; #pragma unroll
;                 for (int i = 0; i < 2; ++i) { vA2[i] = last ? nvA[i] : voffA[i]; vB2[i] = last ? nvB[i] : voffB[i]; }
;                 const size_t hA2 = last ? nhA : hstepA, hB2 = last ? nhB : hstepB;
;                 PG8_LDB(B0, 0, 0); PG8_LDB(B1, 0, 1); PG8_SCHED; PG8_LDA(At, 0, 0); PG8_STAGE(PG8_SA(1, 1), a1 + hstepA, voffA);
;                 PG8_WAIT_V(8); PG8_WAIT_L(0); PG8_BAR; PG8_MMA(0, 0, At, B0); PG8_MMA(0, 1, At, B1); PG8_BAR; PG8_SCHED;
;                 PG8_LDA(At, 0, 1); PG8_STAGE(PG8_SB(0, 0), b2, vB2); PG8_STAGE(PG8_SB(0, 1), b2 + hB2, vB2); PG8_STAGE(PG8_SA(0, 0), a2, vA2);
;                 PG8_WAIT_V(8); PG8_WAIT_L(0); PG8_BAR; PG8_MMA(1, 0, At, B0); PG8_MMA(1, 1, At, B1); PG8_BAR; PG8_SCHED;
;                 PG8_LDB(B0, 1, 0); PG8_LDB(B1, 1, 1); PG8_SCHED; PG8_LDA(At, 1, 0); PG8_STAGE(PG8_SA(0, 1), a2 + hA2, vA2);
;                 PG8_WAIT_V(8); PG8_WAIT_L(0); PG8_BAR; PG8_MMA(0, 0, At, B0); PG8_MMA(0, 1, At, B1); PG8_BAR; PG8_SCHED;
;                 PG8_LDA(At, 1, 1); PG8_STAGE(PG8_SB(1, 0), b3, vB2); PG8_STAGE(PG8_SB(1, 1), b3 + hB2, vB2); PG8_STAGE(PG8_SA(1, 0), a3, vA2);
;                 PG8_WAIT_V(8); PG8_WAIT_L(0); PG8_BAR; PG8_MMA(1, 0, At, B0); PG8_MMA(1, 1, At, B1); PG8_BAR; PG8_SCHED;
.LBB0_846:
	ds_read_b128 v[128:131], v194
	ds_read_b128 v[132:135], v195
	ds_read_b128 v[136:139], v196
	ds_read_b128 v[140:143], v197
	ds_read_b128 v[144:147], v198
	ds_read_b128 v[148:151], v199
	ds_read_b128 v[152:155], v200
	ds_read_b128 v[168:171], v201
	s_add_u32 s44, s42, 0xfff00080
	s_addc_u32 s45, s43, -1
	s_cmp_eq_u32 s62, 60
	s_cselect_b32 s51, s37, s45
	s_cselect_b32 s50, s36, s44
	s_cselect_b32 s45, s59, s61
	s_cselect_b32 s44, s41, s60
	v_lshl_add_u64 v[188:189], s[42:43], 0, v[156:157]
	s_add_i32 m0, s14, 0xc000
	ds_read_b128 v[172:175], v202
	ds_read_b128 v[176:179], v202 offset:2048
	ds_read_b128 v[180:183], v203
	ds_read_b128 v[184:187], v203 offset:2048
	ds_read_b128 v[208:211], v202 offset:4096
	ds_read_b128 v[212:215], v202 offset:6144
	ds_read_b128 v[216:219], v203 offset:4096
	ds_read_b128 v[220:223], v203 offset:6144
	global_load_lds_dwordx4 v[188:189], off
	v_lshl_add_u64 v[188:189], s[42:43], 0, v[160:161]
	s_add_i32 m0, s14, 0xe000
	s_nop 0
	global_load_lds_dwordx4 v[188:189], off
	s_waitcnt vmcnt(8)
	s_waitcnt lgkmcnt(0)
	s_waitcnt lgkmcnt(0)
	v_mfma_f32_16x16x32_bf16 v[124:127], v[128:131], v[172:175], v[124:127]
	v_mfma_f32_16x16x32_bf16 v[124:127], v[132:135], v[180:183], v[124:127]
	v_mfma_f32_16x16x32_bf16 v[120:123], v[140:143], v[180:183], v[120:123]
	v_mfma_f32_16x16x32_bf16 v[120:123], v[136:139], v[172:175], v[120:123]
	s_barrier
	s_setprio 3
	v_mfma_f32_16x16x32_bf16 v[104:107], v[136:139], v[176:179], v[104:107]
	v_mfma_f32_16x16x32_bf16 v[104:107], v[140:143], v[184:187], v[104:107]
	v_mfma_f32_16x16x32_bf16 v[108:111], v[132:135], v[184:187], v[108:111]
	v_mfma_f32_16x16x32_bf16 v[108:111], v[128:131], v[176:179], v[108:111]
	v_mfma_f32_16x16x32_bf16 v[92:95], v[128:131], v[208:211], v[92:95]
	v_mfma_f32_16x16x32_bf16 v[92:95], v[132:135], v[216:219], v[92:95]
	v_mfma_f32_16x16x32_bf16 v[88:91], v[140:143], v[216:219], v[88:91]
	v_mfma_f32_16x16x32_bf16 v[88:91], v[136:139], v[208:211], v[88:91]
	v_mfma_f32_16x16x32_bf16 v[72:75], v[136:139], v[212:215], v[72:75]
	v_mfma_f32_16x16x32_bf16 v[72:75], v[140:143], v[220:223], v[72:75]
	v_mfma_f32_16x16x32_bf16 v[76:79], v[132:135], v[220:223], v[76:79]
	v_mfma_f32_16x16x32_bf16 v[76:79], v[128:131], v[212:215], v[76:79]
	s_setprio 0
	s_setprio 3
	v_mfma_f32_16x16x32_bf16 v[116:119], v[144:147], v[172:175], v[116:119]
	v_mfma_f32_16x16x32_bf16 v[116:119], v[148:151], v[180:183], v[116:119]
	v_mfma_f32_16x16x32_bf16 v[112:115], v[168:171], v[180:183], v[112:115]
	v_mfma_f32_16x16x32_bf16 v[112:115], v[152:155], v[172:175], v[112:115]
	v_mfma_f32_16x16x32_bf16 v[96:99], v[152:155], v[176:179], v[96:99]
	v_mfma_f32_16x16x32_bf16 v[96:99], v[168:171], v[184:187], v[96:99]
	v_mfma_f32_16x16x32_bf16 v[100:103], v[148:151], v[184:187], v[100:103]
	v_mfma_f32_16x16x32_bf16 v[100:103], v[144:147], v[176:179], v[100:103]
	v_mfma_f32_16x16x32_bf16 v[84:87], v[144:147], v[208:211], v[84:87]
	v_mfma_f32_16x16x32_bf16 v[84:87], v[148:151], v[216:219], v[84:87]
	v_mfma_f32_16x16x32_bf16 v[80:83], v[168:171], v[216:219], v[80:83]
	v_mfma_f32_16x16x32_bf16 v[80:83], v[152:155], v[208:211], v[80:83]
	v_mfma_f32_16x16x32_bf16 v[64:67], v[152:155], v[212:215], v[64:67]
	v_mfma_f32_16x16x32_bf16 v[64:67], v[168:171], v[220:223], v[64:67]
	v_mfma_f32_16x16x32_bf16 v[68:71], v[148:151], v[220:223], v[68:71]
	v_mfma_f32_16x16x32_bf16 v[68:71], v[144:147], v[212:215], v[68:71]
	s_setprio 0
	s_barrier
	s_add_i32 s48, s54, s68
	v_lshl_add_u64 v[188:189], s[44:45], 0, v[158:159]
	s_mov_b32 m0, s48
	ds_read_b128 v[172:175], v202 offset:16384
	ds_read_b128 v[176:179], v202 offset:18432
	ds_read_b128 v[180:183], v203 offset:16384
	ds_read_b128 v[184:187], v203 offset:18432
	ds_read_b128 v[208:211], v202 offset:20480
	ds_read_b128 v[212:215], v202 offset:22528
	ds_read_b128 v[216:219], v203 offset:20480
	ds_read_b128 v[220:223], v203 offset:22528
	global_load_lds_dwordx4 v[188:189], off
	s_add_i32 m0, s48, 0x2000
	s_add_u32 s48, s44, 0x100000
	v_lshl_add_u64 v[224:225], s[44:45], 0, v[162:163]
	s_addc_u32 s49, s45, 0
	s_add_i32 s63, s55, s68
	global_load_lds_dwordx4 v[224:225], off
	v_lshl_add_u64 v[226:227], s[48:49], 0, v[158:159]
	s_mov_b32 m0, s63
	v_lshl_add_u64 v[230:231], s[50:51], 0, v[160:161]
	global_load_lds_dwordx4 v[226:227], off
	v_lshl_add_u64 v[226:227], s[48:49], 0, v[162:163]
	s_add_i32 m0, s63, 0x2000
	s_nop 0
	global_load_lds_dwordx4 v[226:227], off
	v_lshl_add_u64 v[226:227], s[50:51], 0, v[156:157]
	s_mov_b32 m0, s14
	s_nop 0
	global_load_lds_dwordx4 v[226:227], off
	s_mov_b32 m0, s15
	s_nop 0
	global_load_lds_dwordx4 v[230:231], off
	s_waitcnt vmcnt(8)
	s_waitcnt lgkmcnt(0)
	s_waitcnt lgkmcnt(0)
	v_mfma_f32_16x16x32_bf16 v[52:55], v[128:131], v[172:175], v[52:55]
	v_mfma_f32_16x16x32_bf16 v[52:55], v[132:135], v[180:183], v[52:55]
	v_mfma_f32_16x16x32_bf16 v[48:51], v[140:143], v[180:183], v[48:51]
	v_mfma_f32_16x16x32_bf16 v[48:51], v[136:139], v[172:175], v[48:51]
	s_barrier
; #define PG8_STAGE(bufoff, gbase, voff) do { _Pragma("unroll") for (int _i = 0; _i < 2; ++_i) \
;         __builtin_amdgcn_global_load_lds((const unsigned*)((const char*)(gbase) + (voff)[_i]), (LAS unsigned*)(lds + (bufoff) + ldsw + _i * 8192), 16, 0, 0); } while (0)
; #define PG8_LDA(dst, b, h) do { _Pragma("unroll") for (int m = 0; m < 4; ++m) _Pragma("unroll") for (int k = 0; k < 2; ++k) dst[m][k] = *(const LAS bf16x8*)(lds + PG8_SA(b, h) + aoffk[k] + m * 2048); } while (0)
; #define PG8_LDB(dst, b, h) do { _Pragma("unroll") for (int n = 0; n < 2; ++n) _Pragma("unroll") for (int k = 0; k < 2; ++k) dst[n][k] = *(const LAS bf16x8*)(lds + PG8_SB(b, h) + boffk[k] + n * 2048); } while (0)
; #define PG8_WAIT_V(n) asm volatile("s_waitcnt vmcnt(" #n ")" ::: "memory")
; #define PG8_WAIT_L(n) asm volatile("s_waitcnt lgkmcnt(" #n ")" ::: "memory")
; #define PG8_BAR __builtin_amdgcn_s_barrier()
; #define PG8_SCHED __builtin_amdgcn_sched_barrier(0)
; template <class Epi, class Sched, class GemmT>
; __device__ __forceinline__ void gemm_phase(LAS unsigned char* lds, const GemmT& g, const Sched& S, const Epi& E, const int wid) {
;     ...
;                 PG8_LDA(At, 0, 1); PG8_STAGE(PG8_SB(0, 0), b2, vB2); PG8_STAGE(PG8_SB(0, 1), b2 + hB2, vB2); PG8_STAGE(PG8_SA(0, 0), a2, vA2);
;                 PG8_WAIT_V(8); PG8_WAIT_L(0); PG8_BAR; PG8_MMA(1, 0, At, B0); PG8_MMA(1, 1, At, B1); PG8_BAR; PG8_SCHED;
;                 PG8_LDB(B0, 1, 0); PG8_LDB(B1, 1, 1); PG8_SCHED; PG8_LDA(At, 1, 0); PG8_STAGE(PG8_SA(0, 1), a2 + hA2, vA2);
;                 PG8_WAIT_V(8); PG8_WAIT_L(0); PG8_BAR; PG8_MMA(0, 0, At, B0); PG8_MMA(0, 1, At, B1); PG8_BAR; PG8_SCHED;
;                 PG8_LDA(At, 1, 1); PG8_STAGE(PG8_SB(1, 0), b3, vB2); PG8_STAGE(PG8_SB(1, 1), b3 + hB2, vB2); PG8_STAGE(PG8_SA(1, 0), a3, vA2);
	s_setprio 3
	v_mfma_f32_16x16x32_bf16 v[32:35], v[136:139], v[176:179], v[32:35]
	v_mfma_f32_16x16x32_bf16 v[32:35], v[140:143], v[184:187], v[32:35]
	v_mfma_f32_16x16x32_bf16 v[36:39], v[132:135], v[184:187], v[36:39]
	v_mfma_f32_16x16x32_bf16 v[36:39], v[128:131], v[176:179], v[36:39]
	v_mfma_f32_16x16x32_bf16 v[20:23], v[128:131], v[208:211], v[20:23]
	v_mfma_f32_16x16x32_bf16 v[20:23], v[132:135], v[216:219], v[20:23]
	v_mfma_f32_16x16x32_bf16 v[16:19], v[140:143], v[216:219], v[16:19]
	v_mfma_f32_16x16x32_bf16 v[16:19], v[136:139], v[208:211], v[16:19]
	v_mfma_f32_16x16x32_bf16 v[0:3], v[136:139], v[212:215], v[0:3]
	v_mfma_f32_16x16x32_bf16 v[0:3], v[140:143], v[220:223], v[0:3]
	v_mfma_f32_16x16x32_bf16 v[4:7], v[132:135], v[220:223], v[4:7]
	v_mfma_f32_16x16x32_bf16 v[4:7], v[128:131], v[212:215], v[4:7]
	s_setprio 0
	s_setprio 3
	v_mfma_f32_16x16x32_bf16 v[60:63], v[144:147], v[172:175], v[60:63]
	v_mfma_f32_16x16x32_bf16 v[60:63], v[148:151], v[180:183], v[60:63]
	v_mfma_f32_16x16x32_bf16 v[56:59], v[168:171], v[180:183], v[56:59]
	v_mfma_f32_16x16x32_bf16 v[56:59], v[152:155], v[172:175], v[56:59]
	v_mfma_f32_16x16x32_bf16 v[40:43], v[152:155], v[176:179], v[40:43]
	v_mfma_f32_16x16x32_bf16 v[40:43], v[168:171], v[184:187], v[40:43]
	v_mfma_f32_16x16x32_bf16 v[44:47], v[148:151], v[184:187], v[44:47]
	v_mfma_f32_16x16x32_bf16 v[44:47], v[144:147], v[176:179], v[44:47]
	v_mfma_f32_16x16x32_bf16 v[28:31], v[144:147], v[208:211], v[28:31]
	v_mfma_f32_16x16x32_bf16 v[28:31], v[148:151], v[216:219], v[28:31]
	v_mfma_f32_16x16x32_bf16 v[24:27], v[168:171], v[216:219], v[24:27]
	v_mfma_f32_16x16x32_bf16 v[24:27], v[152:155], v[208:211], v[24:27]
	v_mfma_f32_16x16x32_bf16 v[8:11], v[152:155], v[212:215], v[8:11]
	v_mfma_f32_16x16x32_bf16 v[8:11], v[168:171], v[220:223], v[8:11]
	v_mfma_f32_16x16x32_bf16 v[12:15], v[148:151], v[220:223], v[12:15]
	v_mfma_f32_16x16x32_bf16 v[12:15], v[144:147], v[212:215], v[12:15]
	s_setprio 0
	s_barrier
	s_add_i32 s63, 0, 0x18000
	s_add_i32 s64, 0, 0x1c000
	v_add_u32_e32 v128, s63, v191
	v_add_u32_e32 v132, s63, v192
	v_add_u32_e32 v144, s64, v191
	v_add_u32_e32 v148, s64, v192
	ds_read_b128 v[128:131], v128
	ds_read_b128 v[132:135], v132
	ds_read_b128 v[136:139], v204
	ds_read_b128 v[140:143], v205
	ds_read_b128 v[144:147], v144
	ds_read_b128 v[148:151], v148
	ds_read_b128 v[152:155], v206
	ds_read_b128 v[168:171], v207
	s_add_u32 s48, s50, 0x100000
	s_addc_u32 s49, s51, 0
	s_mov_b32 m0, s22
	v_lshl_add_u64 v[232:233], s[48:49], 0, v[156:157]
	ds_read_b128 v[172:175], v202 offset:32768
	ds_read_b128 v[176:179], v202 offset:34816
	ds_read_b128 v[180:183], v203 offset:32768
	ds_read_b128 v[184:187], v203 offset:34816
	ds_read_b128 v[208:211], v202 offset:36864
	ds_read_b128 v[212:215], v202 offset:38912
	ds_read_b128 v[216:219], v203 offset:36864
	ds_read_b128 v[220:223], v203 offset:38912
	global_load_lds_dwordx4 v[232:233], off
	v_lshl_add_u64 v[232:233], s[48:49], 0, v[160:161]
	s_mov_b32 m0, s23
	s_nop 0
	global_load_lds_dwordx4 v[232:233], off
	s_waitcnt vmcnt(8)
	s_waitcnt lgkmcnt(0)
	s_waitcnt lgkmcnt(0)
	v_mfma_f32_16x16x32_bf16 v[124:127], v[128:131], v[172:175], v[124:127]
	v_mfma_f32_16x16x32_bf16 v[124:127], v[132:135], v[180:183], v[124:127]
	v_mfma_f32_16x16x32_bf16 v[120:123], v[140:143], v[180:183], v[120:123]
	v_mfma_f32_16x16x32_bf16 v[120:123], v[136:139], v[172:175], v[120:123]
	s_barrier
	s_setprio 3
	v_mfma_f32_16x16x32_bf16 v[104:107], v[136:139], v[176:179], v[104:107]
	v_mfma_f32_16x16x32_bf16 v[104:107], v[140:143], v[184:187], v[104:107]
	v_mfma_f32_16x16x32_bf16 v[108:111], v[132:135], v[184:187], v[108:111]
	v_mfma_f32_16x16x32_bf16 v[108:111], v[128:131], v[176:179], v[108:111]
	v_mfma_f32_16x16x32_bf16 v[92:95], v[128:131], v[208:211], v[92:95]
	v_mfma_f32_16x16x32_bf16 v[92:95], v[132:135], v[216:219], v[92:95]
	v_mfma_f32_16x16x32_bf16 v[88:91], v[140:143], v[216:219], v[88:91]
	v_mfma_f32_16x16x32_bf16 v[88:91], v[136:139], v[208:211], v[88:91]
	v_mfma_f32_16x16x32_bf16 v[72:75], v[136:139], v[212:215], v[72:75]
	v_mfma_f32_16x16x32_bf16 v[72:75], v[140:143], v[220:223], v[72:75]
	v_mfma_f32_16x16x32_bf16 v[76:79], v[132:135], v[220:223], v[76:79]
	v_mfma_f32_16x16x32_bf16 v[76:79], v[128:131], v[212:215], v[76:79]
	s_setprio 0
	s_setprio 3
	v_mfma_f32_16x16x32_bf16 v[116:119], v[144:147], v[172:175], v[116:119]
	v_mfma_f32_16x16x32_bf16 v[116:119], v[148:151], v[180:183], v[116:119]
	v_mfma_f32_16x16x32_bf16 v[112:115], v[168:171], v[180:183], v[112:115]
	v_mfma_f32_16x16x32_bf16 v[112:115], v[152:155], v[172:175], v[112:115]
	v_mfma_f32_16x16x32_bf16 v[96:99], v[152:155], v[176:179], v[96:99]
	v_mfma_f32_16x16x32_bf16 v[96:99], v[168:171], v[184:187], v[96:99]
	v_mfma_f32_16x16x32_bf16 v[100:103], v[148:151], v[184:187], v[100:103]
	v_mfma_f32_16x16x32_bf16 v[100:103], v[144:147], v[176:179], v[100:103]
	v_mfma_f32_16x16x32_bf16 v[84:87], v[144:147], v[208:211], v[84:87]
	v_mfma_f32_16x16x32_bf16 v[84:87], v[148:151], v[216:219], v[84:87]
	v_mfma_f32_16x16x32_bf16 v[80:83], v[168:171], v[216:219], v[80:83]
	v_mfma_f32_16x16x32_bf16 v[80:83], v[152:155], v[208:211], v[80:83]
	v_mfma_f32_16x16x32_bf16 v[64:67], v[152:155], v[212:215], v[64:67]
	v_mfma_f32_16x16x32_bf16 v[64:67], v[168:171], v[220:223], v[64:67]
	v_mfma_f32_16x16x32_bf16 v[68:71], v[148:151], v[220:223], v[68:71]
	v_mfma_f32_16x16x32_bf16 v[68:71], v[144:147], v[212:215], v[68:71]
	s_setprio 0
	s_barrier
; #define PG8_STAGE(bufoff, gbase, voff) do { _Pragma("unroll") for (int _i = 0; _i < 2; ++_i) \
;         __builtin_amdgcn_global_load_lds((const unsigned*)((const char*)(gbase) + (voff)[_i]), (LAS unsigned*)(lds + (bufoff) + ldsw + _i * 8192), 16, 0, 0); } while (0)
; #define PG8_LDA(dst, b, h) do { _Pragma("unroll") for (int m = 0; m < 4; ++m) _Pragma("unroll") for (int k = 0; k < 2; ++k) dst[m][k] = *(const LAS bf16x8*)(lds + PG8_SA(b, h) + aoffk[k] + m * 2048); } while (0)
; #define PG8_WAIT_V(n) asm volatile("s_waitcnt vmcnt(" #n ")" ::: "memory")
; #define PG8_WAIT_L(n) asm volatile("s_waitcnt lgkmcnt(" #n ")" ::: "memory")
; #define PG8_BAR __builtin_amdgcn_s_barrier()
; #define PG8_SCHED __builtin_amdgcn_sched_barrier(0)
; template <class Epi, class Sched, class GemmT>
; __device__ __forceinline__ void gemm_phase(LAS unsigned char* lds, const GemmT& g, const Sched& S, const Epi& E, const int wid) {
;     ...
;                 PG8_LDA(At, 1, 1); PG8_STAGE(PG8_SB(1, 0), b3, vB2); PG8_STAGE(PG8_SB(1, 1), b3 + hB2, vB2); PG8_STAGE(PG8_SA(1, 0), a3, vA2);
;                 PG8_WAIT_V(8); PG8_WAIT_L(0); PG8_BAR; PG8_MMA(1, 0, At, B0); PG8_MMA(1, 1, At, B1); PG8_BAR; PG8_SCHED;
;             }
;             if constexpr (NSEG > 1) { if (sgi + 1 < NSEG) E.mid(acc, cur, sgi, wr, wc, fr, fq); }
;             cs = ns; cA = ns.A; cB = ns.B; hstepA = nhA; hstepB = nhB;
; #pragma unroll
;             for (int i = 0; i < 2; ++i) { voffA[i] = nvA[i]; voffB[i] = nvB[i]; }
;         }
;         if (wr == 0) PG8_BAR;
	s_add_i32 s48, s63, s68
	v_lshl_add_u64 v[188:189], v[188:189], 0, s[18:19]
	s_mov_b32 m0, s48
	ds_read_b128 v[172:175], v202 offset:49152
	ds_read_b128 v[176:179], v202 offset:51200
	ds_read_b128 v[180:183], v203 offset:49152
	ds_read_b128 v[184:187], v203 offset:51200
	ds_read_b128 v[208:211], v202 offset:53248
	ds_read_b128 v[212:215], v202 offset:55296
	ds_read_b128 v[216:219], v203 offset:53248
	ds_read_b128 v[220:223], v203 offset:55296
	global_load_lds_dwordx4 v[188:189], off
	s_add_i32 m0, s48, 0x2000
	s_add_u32 s44, s44, 0x100080
	v_lshl_add_u64 v[188:189], v[224:225], 0, s[18:19]
	s_addc_u32 s45, s45, 0
	s_add_i32 s48, s64, s68
	global_load_lds_dwordx4 v[188:189], off
	v_lshl_add_u64 v[188:189], s[44:45], 0, v[158:159]
	s_mov_b32 m0, s48
	s_nop 0
	global_load_lds_dwordx4 v[188:189], off
	v_lshl_add_u64 v[188:189], s[44:45], 0, v[162:163]
	s_add_i32 m0, s48, 0x2000
	s_nop 0
	global_load_lds_dwordx4 v[188:189], off
	v_lshl_add_u64 v[188:189], v[226:227], 0, s[18:19]
	s_mov_b32 m0, s34
	s_nop 0
	global_load_lds_dwordx4 v[188:189], off
	v_lshl_add_u64 v[188:189], v[230:231], 0, s[18:19]
	s_mov_b32 m0, s35
	s_nop 0
	global_load_lds_dwordx4 v[188:189], off
	s_waitcnt vmcnt(8)
	s_waitcnt lgkmcnt(0)
	s_waitcnt lgkmcnt(0)
	v_mfma_f32_16x16x32_bf16 v[52:55], v[128:131], v[172:175], v[52:55]
	v_mfma_f32_16x16x32_bf16 v[52:55], v[132:135], v[180:183], v[52:55]
	v_mfma_f32_16x16x32_bf16 v[48:51], v[140:143], v[180:183], v[48:51]
	v_mfma_f32_16x16x32_bf16 v[48:51], v[136:139], v[172:175], v[48:51]
	s_barrier
	s_setprio 3
	v_mfma_f32_16x16x32_bf16 v[32:35], v[136:139], v[176:179], v[32:35]
	v_mfma_f32_16x16x32_bf16 v[32:35], v[140:143], v[184:187], v[32:35]
	v_mfma_f32_16x16x32_bf16 v[36:39], v[132:135], v[184:187], v[36:39]
	v_mfma_f32_16x16x32_bf16 v[36:39], v[128:131], v[176:179], v[36:39]
	v_mfma_f32_16x16x32_bf16 v[20:23], v[128:131], v[208:211], v[20:23]
	v_mfma_f32_16x16x32_bf16 v[20:23], v[132:135], v[216:219], v[20:23]
	v_mfma_f32_16x16x32_bf16 v[16:19], v[140:143], v[216:219], v[16:19]
	v_mfma_f32_16x16x32_bf16 v[16:19], v[136:139], v[208:211], v[16:19]
	v_mfma_f32_16x16x32_bf16 v[0:3], v[136:139], v[212:215], v[0:3]
	v_mfma_f32_16x16x32_bf16 v[0:3], v[140:143], v[220:223], v[0:3]
	v_mfma_f32_16x16x32_bf16 v[4:7], v[132:135], v[220:223], v[4:7]
	v_mfma_f32_16x16x32_bf16 v[4:7], v[128:131], v[212:215], v[4:7]
	s_setprio 0
	s_setprio 3
	v_mfma_f32_16x16x32_bf16 v[60:63], v[144:147], v[172:175], v[60:63]
	v_mfma_f32_16x16x32_bf16 v[60:63], v[148:151], v[180:183], v[60:63]
	v_mfma_f32_16x16x32_bf16 v[56:59], v[168:171], v[180:183], v[56:59]
	v_mfma_f32_16x16x32_bf16 v[56:59], v[152:155], v[172:175], v[56:59]
	v_mfma_f32_16x16x32_bf16 v[40:43], v[152:155], v[176:179], v[40:43]
	v_mfma_f32_16x16x32_bf16 v[40:43], v[168:171], v[184:187], v[40:43]
	v_mfma_f32_16x16x32_bf16 v[44:47], v[148:151], v[184:187], v[44:47]
	v_mfma_f32_16x16x32_bf16 v[44:47], v[144:147], v[176:179], v[44:47]
	v_mfma_f32_16x16x32_bf16 v[28:31], v[144:147], v[208:211], v[28:31]
	v_mfma_f32_16x16x32_bf16 v[28:31], v[148:151], v[216:219], v[28:31]
	v_mfma_f32_16x16x32_bf16 v[24:27], v[168:171], v[216:219], v[24:27]
	v_mfma_f32_16x16x32_bf16 v[24:27], v[152:155], v[208:211], v[24:27]
	v_mfma_f32_16x16x32_bf16 v[8:11], v[152:155], v[212:215], v[8:11]
	v_mfma_f32_16x16x32_bf16 v[8:11], v[168:171], v[220:223], v[8:11]
	v_mfma_f32_16x16x32_bf16 v[12:15], v[148:151], v[220:223], v[12:15]
	v_mfma_f32_16x16x32_bf16 v[12:15], v[144:147], v[212:215], v[12:15]
	s_setprio 0
	s_barrier
	s_add_i32 s62, s62, 2
	s_add_u32 s42, s42, 0x100
	s_addc_u32 s43, s43, 0
	s_add_u32 s60, s60, 0x100
	s_addc_u32 s61, s61, 0
	s_cmp_gt_u32 s62, 61
	s_cbranch_scc0 .LBB0_846
	s_and_b64 vcc, exec, s[20:21]
	s_cbranch_vccz .LBB0_849
	s_barrier

; #define PG8_STAGE(bufoff, gbase, voff) do { _Pragma("unroll") for (int _i = 0; _i < 2; ++_i) \
;         __builtin_amdgcn_global_load_lds((const unsigned*)((const char*)(gbase) + (voff)[_i]), (LAS unsigned*)(lds + (bufoff) + ldsw + _i * 8192), 16, 0, 0); } while (0)
; #define PG8_LDA(dst, b, h) do { _Pragma("unroll") for (int m = 0; m < 4; ++m) _Pragma("unroll") for (int k = 0; k < 2; ++k) dst[m][k] = *(const LAS bf16x8*)(lds + PG8_SA(b, h) + aoffk[k] + m * 2048); } while (0)
; #define PG8_BAR __builtin_amdgcn_s_barrier()
; template <class Epi, class Sched, class GemmT>
; __device__ __forceinline__ void gemm_phase(LAS unsigned char* lds, const GemmT& g, const Sched& S, const Epi& E, const int wid) {
;     ...
;             for (int t = 0; t < nt; t += 2) {
;                 const bool last = (t == nt - 2);
;                 const char* a1 = cA + (size_t)(t + 1) * kstep;
;                 const char* a2 = last ? ns.A : cA + (size_t)(t + 2) * kstep; const char* b2 = last ? ns.B : cB + (size_t)(t + 2) * kstep;
;                 const char* a3 = a2 + kstep; const char* b3 = b2 + kstep;
;                 unsigned vA2[2], vB2[2];
; #pragma unroll
;                 for (int i = 0; i < 2; ++i) { vA2[i] = last ? nvA[i] : voffA[i]; vB2[i] = last ? nvB[i] : voffB[i]; }
;                 const size_t hA2 = last ? nhA : hstepA, hB2 = last ? nhB : hstepB;
;                 PG8_LDB(B0, 0, 0); PG8_LDB(B1, 0, 1); PG8_SCHED; PG8_LDA(At, 0, 0); PG8_STAGE(PG8_SA(1, 1), a1 + hstepA, voffA);
;                 PG8_WAIT_V(8); PG8_WAIT_L(0); PG8_BAR; PG8_MMA(0, 0, At, B0); PG8_MMA(0, 1, At, B1); PG8_BAR; PG8_SCHED;
;                 PG8_LDA(At, 0, 1); PG8_STAGE(PG8_SB(0, 0), b2, vB2); PG8_STAGE(PG8_SB(0, 1), b2 + hB2, vB2); PG8_STAGE(PG8_SA(0, 0), a2, vA2);
;                 PG8_WAIT_V(8); PG8_WAIT_L(0); PG8_BAR; PG8_MMA(1, 0, At, B0); PG8_MMA(1, 1, At, B1); PG8_BAR; PG8_SCHED;
;                 PG8_LDB(B0, 1, 0); PG8_LDB(B1, 1, 1); PG8_SCHED; PG8_LDA(At, 1, 0); PG8_STAGE(PG8_SA(0, 1), a2 + hA2, vA2);
;                 PG8_WAIT_V(8); PG8_WAIT_L(0); PG8_BAR; PG8_MMA(0, 0, At, B0); PG8_MMA(0, 1, At, B1); PG8_BAR; PG8_SCHED;
;                 PG8_LDA(At, 1, 1); PG8_STAGE(PG8_SB(1, 0), b3, vB2); PG8_STAGE(PG8_SB(1, 1), b3 + hB2, vB2); PG8_STAGE(PG8_SA(1, 0), a3, vA2);
;                 PG8_WAIT_V(8); PG8_WAIT_L(0); PG8_BAR; PG8_MMA(1, 0, At, B0); PG8_MMA(1, 1, At, B1); PG8_BAR; PG8_SCHED;
.LBB0_936:
	ds_read_b128 v[12:15], v223
	ds_read_b128 v[132:135], v224
	ds_read_b128 v[136:139], v225
	ds_read_b128 v[140:143], v226
	ds_read_b128 v[144:147], v227
	ds_read_b128 v[148:151], v229
	ds_read_b128 v[152:155], v230
	ds_read_b128 v[156:159], v231
	s_add_u32 s66, s64, 0xfff00080
	s_addc_u32 s67, s65, -1
	s_cmp_eq_u32 s81, 60
	s_cselect_b32 s71, s57, s67
	s_cselect_b32 s70, s56, s66
	s_cselect_b32 s67, s77, s79
	s_cselect_b32 s66, s63, s78
	v_lshl_add_u64 v[204:205], s[64:65], 0, v[176:177]
	s_add_i32 m0, s14, 0xc000
	ds_read_b128 v[160:163], v232
	ds_read_b128 v[164:167], v232 offset:2048
	ds_read_b128 v[168:171], v233
	ds_read_b128 v[172:175], v233 offset:2048
	ds_read_b128 v[188:191], v232 offset:4096
	ds_read_b128 v[192:195], v232 offset:6144
	ds_read_b128 v[196:199], v233 offset:4096
	ds_read_b128 v[200:203], v233 offset:6144
	global_load_lds_dwordx4 v[204:205], off
	v_lshl_add_u64 v[204:205], s[64:65], 0, v[180:181]
	s_add_i32 m0, s14, 0xe000
	s_nop 0
	global_load_lds_dwordx4 v[204:205], off
	s_waitcnt vmcnt(8)
	s_waitcnt lgkmcnt(0)
	s_waitcnt lgkmcnt(0)
	v_mfma_f32_16x16x32_bf16 v[124:127], v[12:15], v[160:163], v[124:127]
	v_mfma_f32_16x16x32_bf16 v[124:127], v[132:135], v[168:171], v[124:127]
	v_mfma_f32_16x16x32_bf16 v[120:123], v[140:143], v[168:171], v[120:123]
	v_mfma_f32_16x16x32_bf16 v[120:123], v[136:139], v[160:163], v[120:123]
	s_barrier
	s_setprio 3
	v_mfma_f32_16x16x32_bf16 v[104:107], v[136:139], v[164:167], v[104:107]
	v_mfma_f32_16x16x32_bf16 v[104:107], v[140:143], v[172:175], v[104:107]
	v_mfma_f32_16x16x32_bf16 v[40:43], v[132:135], v[172:175], v[40:43]
	v_mfma_f32_16x16x32_bf16 v[40:43], v[12:15], v[164:167], v[40:43]
	v_mfma_f32_16x16x32_bf16 v[32:35], v[12:15], v[188:191], v[32:35]
	v_mfma_f32_16x16x32_bf16 v[32:35], v[132:135], v[196:199], v[32:35]
	v_mfma_f32_16x16x32_bf16 v[96:99], v[140:143], v[196:199], v[96:99]
	v_mfma_f32_16x16x32_bf16 v[96:99], v[136:139], v[188:191], v[96:99]
	v_mfma_f32_16x16x32_bf16 v[92:95], v[136:139], v[192:195], v[92:95]
	v_mfma_f32_16x16x32_bf16 v[92:95], v[140:143], v[200:203], v[92:95]
	v_mfma_f32_16x16x32_bf16 v[112:115], v[132:135], v[200:203], v[112:115]
	v_mfma_f32_16x16x32_bf16 v[112:115], v[12:15], v[192:195], v[112:115]
	s_setprio 0
	s_setprio 3
	v_mfma_f32_16x16x32_bf16 v[68:71], v[144:147], v[160:163], v[68:71]
	v_mfma_f32_16x16x32_bf16 v[68:71], v[148:151], v[168:171], v[68:71]
	v_mfma_f32_16x16x32_bf16 v[60:63], v[156:159], v[168:171], v[60:63]
	v_mfma_f32_16x16x32_bf16 v[60:63], v[152:155], v[160:163], v[60:63]
	v_mfma_f32_16x16x32_bf16 v[20:23], v[152:155], v[164:167], v[20:23]
	v_mfma_f32_16x16x32_bf16 v[20:23], v[156:159], v[172:175], v[20:23]
	v_mfma_f32_16x16x32_bf16 v[76:79], v[148:151], v[172:175], v[76:79]
	v_mfma_f32_16x16x32_bf16 v[76:79], v[144:147], v[164:167], v[76:79]
	v_mfma_f32_16x16x32_bf16 v[72:75], v[144:147], v[188:191], v[72:75]
	v_mfma_f32_16x16x32_bf16 v[72:75], v[148:151], v[196:199], v[72:75]
	v_mfma_f32_16x16x32_bf16 v[16:19], v[156:159], v[196:199], v[16:19]
	v_mfma_f32_16x16x32_bf16 v[16:19], v[152:155], v[188:191], v[16:19]
	v_mfma_f32_16x16x32_bf16 v[80:83], v[152:155], v[192:195], v[80:83]
	v_mfma_f32_16x16x32_bf16 v[80:83], v[156:159], v[200:203], v[80:83]
	v_mfma_f32_16x16x32_bf16 v[84:87], v[148:151], v[200:203], v[84:87]
	v_mfma_f32_16x16x32_bf16 v[84:87], v[144:147], v[192:195], v[84:87]
	s_setprio 0
	s_barrier
	s_add_i32 s80, s69, s68
	v_lshl_add_u64 v[204:205], s[66:67], 0, v[178:179]
	s_mov_b32 m0, s80
	ds_read_b128 v[160:163], v232 offset:16384
	ds_read_b128 v[164:167], v232 offset:18432
	ds_read_b128 v[168:171], v233 offset:16384
	ds_read_b128 v[172:175], v233 offset:18432
	ds_read_b128 v[188:191], v232 offset:20480
	ds_read_b128 v[192:195], v232 offset:22528
	ds_read_b128 v[196:199], v233 offset:20480
	ds_read_b128 v[200:203], v233 offset:22528
	global_load_lds_dwordx4 v[204:205], off
	s_add_i32 m0, s80, 0x2000
	s_add_u32 s82, s66, 0x100000
	v_lshl_add_u64 v[206:207], s[66:67], 0, v[182:183]
	s_addc_u32 s83, s67, 0
	s_add_i32 s80, s72, s68
	global_load_lds_dwordx4 v[206:207], off
	v_lshl_add_u64 v[240:241], s[82:83], 0, v[178:179]
	s_mov_b32 m0, s80
	v_lshl_add_u64 v[242:243], s[70:71], 0, v[180:181]
	global_load_lds_dwordx4 v[240:241], off
	v_lshl_add_u64 v[240:241], s[82:83], 0, v[182:183]
	s_add_i32 m0, s80, 0x2000
	s_nop 0
	global_load_lds_dwordx4 v[240:241], off
	v_lshl_add_u64 v[240:241], s[70:71], 0, v[176:177]
	s_mov_b32 m0, s14
	s_nop 0
	global_load_lds_dwordx4 v[240:241], off
	s_mov_b32 m0, s15
	s_nop 0
	global_load_lds_dwordx4 v[242:243], off
	s_waitcnt vmcnt(8)
	s_waitcnt lgkmcnt(0)
	s_waitcnt lgkmcnt(0)
	v_mfma_f32_16x16x32_bf16 v[56:59], v[12:15], v[160:163], v[56:59]
	v_mfma_f32_16x16x32_bf16 v[56:59], v[132:135], v[168:171], v[56:59]
	v_mfma_f32_16x16x32_bf16 v[108:111], v[136:139], v[160:163], v[108:111]
	v_mfma_f32_16x16x32_bf16 v[108:111], v[140:143], v[168:171], v[108:111]
	s_barrier
; #define PG8_STAGE(bufoff, gbase, voff) do { _Pragma("unroll") for (int _i = 0; _i < 2; ++_i) \
;         __builtin_amdgcn_global_load_lds((const unsigned*)((const char*)(gbase) + (voff)[_i]), (LAS unsigned*)(lds + (bufoff) + ldsw + _i * 8192), 16, 0, 0); } while (0)
; #define PG8_LDA(dst, b, h) do { _Pragma("unroll") for (int m = 0; m < 4; ++m) _Pragma("unroll") for (int k = 0; k < 2; ++k) dst[m][k] = *(const LAS bf16x8*)(lds + PG8_SA(b, h) + aoffk[k] + m * 2048); } while (0)
; #define PG8_LDB(dst, b, h) do { _Pragma("unroll") for (int n = 0; n < 2; ++n) _Pragma("unroll") for (int k = 0; k < 2; ++k) dst[n][k] = *(const LAS bf16x8*)(lds + PG8_SB(b, h) + boffk[k] + n * 2048); } while (0)
; #define PG8_WAIT_V(n) asm volatile("s_waitcnt vmcnt(" #n ")" ::: "memory")
; #define PG8_WAIT_L(n) asm volatile("s_waitcnt lgkmcnt(" #n ")" ::: "memory")
; #define PG8_BAR __builtin_amdgcn_s_barrier()
; #define PG8_SCHED __builtin_amdgcn_sched_barrier(0)
; template <class Epi, class Sched, class GemmT>
; __device__ __forceinline__ void gemm_phase(LAS unsigned char* lds, const GemmT& g, const Sched& S, const Epi& E, const int wid) {
;     ...
;                 PG8_WAIT_V(8); PG8_WAIT_L(0); PG8_BAR; PG8_MMA(1, 0, At, B0); PG8_MMA(1, 1, At, B1); PG8_BAR; PG8_SCHED;
;                 PG8_LDB(B0, 1, 0); PG8_LDB(B1, 1, 1); PG8_SCHED; PG8_LDA(At, 1, 0); PG8_STAGE(PG8_SA(0, 1), a2 + hA2, vA2);
;                 PG8_WAIT_V(8); PG8_WAIT_L(0); PG8_BAR; PG8_MMA(0, 0, At, B0); PG8_MMA(0, 1, At, B1); PG8_BAR; PG8_SCHED;
;                 PG8_LDA(At, 1, 1); PG8_STAGE(PG8_SB(1, 0), b3, vB2); PG8_STAGE(PG8_SB(1, 1), b3 + hB2, vB2); PG8_STAGE(PG8_SA(1, 0), a3, vA2);
	s_setprio 3
	v_mfma_f32_16x16x32_bf16 v[36:39], v[12:15], v[164:167], v[36:39]
	v_mfma_f32_16x16x32_bf16 v[36:39], v[132:135], v[172:175], v[36:39]
	v_mfma_f32_16x16x32_bf16 v[100:103], v[136:139], v[164:167], v[100:103]
	v_mfma_f32_16x16x32_bf16 v[100:103], v[140:143], v[172:175], v[100:103]
	v_mfma_f32_16x16x32_bf16 v[28:31], v[12:15], v[188:191], v[28:31]
	v_mfma_f32_16x16x32_bf16 v[28:31], v[132:135], v[196:199], v[28:31]
	v_mfma_f32_16x16x32_bf16 v[88:91], v[136:139], v[188:191], v[88:91]
	v_mfma_f32_16x16x32_bf16 v[88:91], v[140:143], v[196:199], v[88:91]
	v_mfma_f32_16x16x32_bf16 v[24:27], v[136:139], v[192:195], v[24:27]
	v_mfma_f32_16x16x32_bf16 v[24:27], v[140:143], v[200:203], v[24:27]
	v_mfma_f32_16x16x32_bf16 v[12:15], v[12:15], v[192:195], v[64:67]
	v_mfma_f32_16x16x32_bf16 v[12:15], v[132:135], v[200:203], v[12:15]
	s_setprio 0
	s_setprio 3
	v_mfma_f32_16x16x32_bf16 v[64:67], v[144:147], v[192:195], v[116:119]
	v_mfma_f32_16x16x32_bf16 v[116:119], v[148:151], v[200:203], v[64:67]
	v_mfma_f32_16x16x32_bf16 v[44:47], v[144:147], v[160:163], v[44:47]
	v_mfma_f32_16x16x32_bf16 v[44:47], v[148:151], v[168:171], v[44:47]
	v_mfma_f32_16x16x32_bf16 v[0:3], v[152:155], v[160:163], v[0:3]
	v_mfma_f32_16x16x32_bf16 v[0:3], v[156:159], v[168:171], v[0:3]
	v_mfma_f32_16x16x32_bf16 v[48:51], v[144:147], v[164:167], v[48:51]
	v_mfma_f32_16x16x32_bf16 v[48:51], v[148:151], v[172:175], v[48:51]
	v_mfma_f32_16x16x32_bf16 v[4:7], v[152:155], v[164:167], v[4:7]
	v_mfma_f32_16x16x32_bf16 v[4:7], v[156:159], v[172:175], v[4:7]
	v_mfma_f32_16x16x32_bf16 v[64:67], v[152:155], v[192:195], v[128:131]
	v_mfma_f32_16x16x32_bf16 v[128:131], v[156:159], v[200:203], v[64:67]
	v_mfma_f32_16x16x32_bf16 v[52:55], v[144:147], v[188:191], v[52:55]
	v_mfma_f32_16x16x32_bf16 v[52:55], v[148:151], v[196:199], v[52:55]
	v_mfma_f32_16x16x32_bf16 v[8:11], v[152:155], v[188:191], v[8:11]
	v_mfma_f32_16x16x32_bf16 v[8:11], v[156:159], v[196:199], v[8:11]
	s_setprio 0
	s_barrier
	s_add_i32 s80, 0, 0x18000
	s_add_i32 s82, 0, 0x1c000
	v_add_u32_e32 v64, s80, v210
	v_add_u32_e32 v132, s80, v211
	v_add_u32_e32 v144, s82, v210
	v_add_u32_e32 v148, s82, v211
	ds_read_b128 v[64:67], v64
	ds_read_b128 v[132:135], v132
	ds_read_b128 v[136:139], v234
	ds_read_b128 v[140:143], v235
	ds_read_b128 v[144:147], v144
	ds_read_b128 v[148:151], v148
	ds_read_b128 v[152:155], v236
	ds_read_b128 v[156:159], v237
	s_add_u32 s70, s70, 0x100000
	s_addc_u32 s71, s71, 0
	s_mov_b32 m0, s23
	v_lshl_add_u64 v[244:245], s[70:71], 0, v[176:177]
	ds_read_b128 v[160:163], v232 offset:32768
	ds_read_b128 v[164:167], v232 offset:34816
	ds_read_b128 v[168:171], v233 offset:32768
	ds_read_b128 v[172:175], v233 offset:34816
	ds_read_b128 v[188:191], v232 offset:36864
	ds_read_b128 v[192:195], v232 offset:38912
	ds_read_b128 v[196:199], v233 offset:36864
	ds_read_b128 v[200:203], v233 offset:38912
	global_load_lds_dwordx4 v[244:245], off
	v_lshl_add_u64 v[244:245], s[70:71], 0, v[180:181]
	s_mov_b32 m0, s34
	s_nop 0
	global_load_lds_dwordx4 v[244:245], off
	s_waitcnt vmcnt(8)
	s_waitcnt lgkmcnt(0)
	s_waitcnt lgkmcnt(0)
	v_mfma_f32_16x16x32_bf16 v[124:127], v[64:67], v[160:163], v[124:127]
	v_mfma_f32_16x16x32_bf16 v[124:127], v[132:135], v[168:171], v[124:127]
	v_mfma_f32_16x16x32_bf16 v[120:123], v[140:143], v[168:171], v[120:123]
	v_mfma_f32_16x16x32_bf16 v[120:123], v[136:139], v[160:163], v[120:123]
	s_barrier
	s_setprio 3
	v_mfma_f32_16x16x32_bf16 v[104:107], v[136:139], v[164:167], v[104:107]
	v_mfma_f32_16x16x32_bf16 v[104:107], v[140:143], v[172:175], v[104:107]
	v_mfma_f32_16x16x32_bf16 v[40:43], v[132:135], v[172:175], v[40:43]
	v_mfma_f32_16x16x32_bf16 v[40:43], v[64:67], v[164:167], v[40:43]
	v_mfma_f32_16x16x32_bf16 v[32:35], v[64:67], v[188:191], v[32:35]
	v_mfma_f32_16x16x32_bf16 v[32:35], v[132:135], v[196:199], v[32:35]
	v_mfma_f32_16x16x32_bf16 v[96:99], v[140:143], v[196:199], v[96:99]
	v_mfma_f32_16x16x32_bf16 v[96:99], v[136:139], v[188:191], v[96:99]
	v_mfma_f32_16x16x32_bf16 v[92:95], v[136:139], v[192:195], v[92:95]
	v_mfma_f32_16x16x32_bf16 v[92:95], v[140:143], v[200:203], v[92:95]
	v_mfma_f32_16x16x32_bf16 v[112:115], v[132:135], v[200:203], v[112:115]
	v_mfma_f32_16x16x32_bf16 v[112:115], v[64:67], v[192:195], v[112:115]
	s_setprio 0
	s_setprio 3
	v_mfma_f32_16x16x32_bf16 v[68:71], v[144:147], v[160:163], v[68:71]
	v_mfma_f32_16x16x32_bf16 v[68:71], v[148:151], v[168:171], v[68:71]
	v_mfma_f32_16x16x32_bf16 v[60:63], v[156:159], v[168:171], v[60:63]
	v_mfma_f32_16x16x32_bf16 v[60:63], v[152:155], v[160:163], v[60:63]
	v_mfma_f32_16x16x32_bf16 v[20:23], v[152:155], v[164:167], v[20:23]
	v_mfma_f32_16x16x32_bf16 v[20:23], v[156:159], v[172:175], v[20:23]
	v_mfma_f32_16x16x32_bf16 v[76:79], v[148:151], v[172:175], v[76:79]
	v_mfma_f32_16x16x32_bf16 v[76:79], v[144:147], v[164:167], v[76:79]
	v_mfma_f32_16x16x32_bf16 v[72:75], v[144:147], v[188:191], v[72:75]
	v_mfma_f32_16x16x32_bf16 v[72:75], v[148:151], v[196:199], v[72:75]
	v_mfma_f32_16x16x32_bf16 v[16:19], v[156:159], v[196:199], v[16:19]
	v_mfma_f32_16x16x32_bf16 v[16:19], v[152:155], v[188:191], v[16:19]
	v_mfma_f32_16x16x32_bf16 v[80:83], v[152:155], v[192:195], v[80:83]
	v_mfma_f32_16x16x32_bf16 v[80:83], v[156:159], v[200:203], v[80:83]
	v_mfma_f32_16x16x32_bf16 v[84:87], v[148:151], v[200:203], v[84:87]
	v_mfma_f32_16x16x32_bf16 v[84:87], v[144:147], v[192:195], v[84:87]
	s_setprio 0
	s_barrier
; #define PG8_STAGE(bufoff, gbase, voff) do { _Pragma("unroll") for (int _i = 0; _i < 2; ++_i) \
;         __builtin_amdgcn_global_load_lds((const unsigned*)((const char*)(gbase) + (voff)[_i]), (LAS unsigned*)(lds + (bufoff) + ldsw + _i * 8192), 16, 0, 0); } while (0)
; #define PG8_LDA(dst, b, h) do { _Pragma("unroll") for (int m = 0; m < 4; ++m) _Pragma("unroll") for (int k = 0; k < 2; ++k) dst[m][k] = *(const LAS bf16x8*)(lds + PG8_SA(b, h) + aoffk[k] + m * 2048); } while (0)
; #define PG8_WAIT_V(n) asm volatile("s_waitcnt vmcnt(" #n ")" ::: "memory")
; #define PG8_WAIT_L(n) asm volatile("s_waitcnt lgkmcnt(" #n ")" ::: "memory")
; #define PG8_BAR __builtin_amdgcn_s_barrier()
; #define PG8_SCHED __builtin_amdgcn_sched_barrier(0)
; template <class Epi, class Sched, class GemmT>
; __device__ __forceinline__ void gemm_phase(LAS unsigned char* lds, const GemmT& g, const Sched& S, const Epi& E, const int wid) {
;     ...
;                 PG8_LDA(At, 1, 1); PG8_STAGE(PG8_SB(1, 0), b3, vB2); PG8_STAGE(PG8_SB(1, 1), b3 + hB2, vB2); PG8_STAGE(PG8_SA(1, 0), a3, vA2);
;                 PG8_WAIT_V(8); PG8_WAIT_L(0); PG8_BAR; PG8_MMA(1, 0, At, B0); PG8_MMA(1, 1, At, B1); PG8_BAR; PG8_SCHED;
;             }
;             if constexpr (NSEG > 1) { if (sgi + 1 < NSEG) E.mid(acc, cur, sgi, wr, wc, fr, fq); }
;             cs = ns; cA = ns.A; cB = ns.B; hstepA = nhA; hstepB = nhB;
; #pragma unroll
;             for (int i = 0; i < 2; ++i) { voffA[i] = nvA[i]; voffB[i] = nvB[i]; }
;         }
;         if (wr == 0) PG8_BAR;
	s_add_i32 s70, s80, s68
	v_lshl_add_u64 v[204:205], v[204:205], 0, s[38:39]
	s_mov_b32 m0, s70
	ds_read_b128 v[160:163], v232 offset:49152
	ds_read_b128 v[164:167], v232 offset:51200
	ds_read_b128 v[168:171], v233 offset:49152
	ds_read_b128 v[172:175], v233 offset:51200
	ds_read_b128 v[188:191], v232 offset:53248
	ds_read_b128 v[192:195], v232 offset:55296
	ds_read_b128 v[196:199], v233 offset:53248
	ds_read_b128 v[200:203], v233 offset:55296
	global_load_lds_dwordx4 v[204:205], off
	s_add_i32 m0, s70, 0x2000
	s_add_u32 s66, s66, 0x100080
	v_lshl_add_u64 v[204:205], v[206:207], 0, s[38:39]
	s_addc_u32 s67, s67, 0
	s_add_i32 s70, s82, s68
	global_load_lds_dwordx4 v[204:205], off
	v_lshl_add_u64 v[204:205], s[66:67], 0, v[178:179]
	s_mov_b32 m0, s70
	s_nop 0
	global_load_lds_dwordx4 v[204:205], off
	v_lshl_add_u64 v[204:205], s[66:67], 0, v[182:183]
	s_add_i32 m0, s70, 0x2000
	s_nop 0
	global_load_lds_dwordx4 v[204:205], off
	v_lshl_add_u64 v[204:205], v[240:241], 0, s[38:39]
	s_mov_b32 m0, s54
	s_nop 0
	global_load_lds_dwordx4 v[204:205], off
	v_lshl_add_u64 v[204:205], v[242:243], 0, s[38:39]
	s_mov_b32 m0, s55
	s_nop 0
	global_load_lds_dwordx4 v[204:205], off
	s_waitcnt vmcnt(8)
	s_waitcnt lgkmcnt(0)
	s_waitcnt lgkmcnt(0)
	v_mfma_f32_16x16x32_bf16 v[12:15], v[64:67], v[192:195], v[12:15]
	v_mfma_f32_16x16x32_bf16 v[56:59], v[64:67], v[160:163], v[56:59]
	v_mfma_f32_16x16x32_bf16 v[56:59], v[132:135], v[168:171], v[56:59]
	v_mfma_f32_16x16x32_bf16 v[108:111], v[136:139], v[160:163], v[108:111]
	s_barrier
	s_setprio 3
	v_mfma_f32_16x16x32_bf16 v[108:111], v[140:143], v[168:171], v[108:111]
	v_mfma_f32_16x16x32_bf16 v[36:39], v[64:67], v[164:167], v[36:39]
	v_mfma_f32_16x16x32_bf16 v[36:39], v[132:135], v[172:175], v[36:39]
	v_mfma_f32_16x16x32_bf16 v[100:103], v[136:139], v[164:167], v[100:103]
	v_mfma_f32_16x16x32_bf16 v[100:103], v[140:143], v[172:175], v[100:103]
	v_mfma_f32_16x16x32_bf16 v[28:31], v[64:67], v[188:191], v[28:31]
	v_mfma_f32_16x16x32_bf16 v[28:31], v[132:135], v[196:199], v[28:31]
	v_mfma_f32_16x16x32_bf16 v[88:91], v[136:139], v[188:191], v[88:91]
	v_mfma_f32_16x16x32_bf16 v[88:91], v[140:143], v[196:199], v[88:91]
	v_mfma_f32_16x16x32_bf16 v[64:67], v[132:135], v[200:203], v[12:15]
	v_mfma_f32_16x16x32_bf16 v[12:15], v[136:139], v[192:195], v[24:27]
	v_mfma_f32_16x16x32_bf16 v[24:27], v[140:143], v[200:203], v[12:15]
	s_setprio 0
	s_setprio 3
	v_mfma_f32_16x16x32_bf16 v[12:15], v[144:147], v[160:163], v[44:47]
	v_mfma_f32_16x16x32_bf16 v[44:47], v[148:151], v[168:171], v[12:15]
	v_mfma_f32_16x16x32_bf16 v[0:3], v[152:155], v[160:163], v[0:3]
	v_mfma_f32_16x16x32_bf16 v[0:3], v[156:159], v[168:171], v[0:3]
	v_mfma_f32_16x16x32_bf16 v[4:7], v[152:155], v[164:167], v[4:7]
	v_mfma_f32_16x16x32_bf16 v[4:7], v[156:159], v[172:175], v[4:7]
	v_mfma_f32_16x16x32_bf16 v[12:15], v[144:147], v[164:167], v[48:51]
	v_mfma_f32_16x16x32_bf16 v[48:51], v[148:151], v[172:175], v[12:15]
	v_mfma_f32_16x16x32_bf16 v[8:11], v[152:155], v[188:191], v[8:11]
	v_mfma_f32_16x16x32_bf16 v[8:11], v[156:159], v[196:199], v[8:11]
	v_mfma_f32_16x16x32_bf16 v[12:15], v[144:147], v[188:191], v[52:55]
	v_mfma_f32_16x16x32_bf16 v[52:55], v[148:151], v[196:199], v[12:15]
	v_mfma_f32_16x16x32_bf16 v[12:15], v[144:147], v[192:195], v[116:119]
	v_mfma_f32_16x16x32_bf16 v[116:119], v[148:151], v[200:203], v[12:15]
	v_mfma_f32_16x16x32_bf16 v[12:15], v[152:155], v[192:195], v[128:131]
	v_mfma_f32_16x16x32_bf16 v[128:131], v[156:159], v[200:203], v[12:15]
	s_setprio 0
	s_barrier
	s_add_i32 s81, s81, 2
	s_add_u32 s64, s64, 0x100
	s_addc_u32 s65, s65, 0
	s_add_u32 s78, s78, 0x100
	s_addc_u32 s79, s79, 0
	s_cmp_gt_u32 s81, 61
	s_cbranch_scc0 .LBB0_936
	s_and_b64 vcc, exec, s[40:41]
	s_cbranch_vccz .LBB0_939
	s_barrier

; #define PG8_STAGE(bufoff, gbase, voff) do { _Pragma("unroll") for (int _i = 0; _i < 2; ++_i) \
;         __builtin_amdgcn_global_load_lds((const unsigned*)((const char*)(gbase) + (voff)[_i]), (LAS unsigned*)(lds + (bufoff) + ldsw + _i * 8192), 16, 0, 0); } while (0)
; #define PG8_LDA(dst, b, h) do { _Pragma("unroll") for (int m = 0; m < 4; ++m) _Pragma("unroll") for (int k = 0; k < 2; ++k) dst[m][k] = *(const LAS bf16x8*)(lds + PG8_SA(b, h) + aoffk[k] + m * 2048); } while (0)
; #define PG8_BAR __builtin_amdgcn_s_barrier()
; template <class Epi, class Sched, class GemmT>
; __device__ __forceinline__ void gemm_phase(LAS unsigned char* lds, const GemmT& g, const Sched& S, const Epi& E, const int wid) {
;     ...
;             for (int t = 0; t < nt; t += 2) {
;                 const bool last = (t == nt - 2);
;                 const char* a1 = cA + (size_t)(t + 1) * kstep;
;                 const char* a2 = last ? ns.A : cA + (size_t)(t + 2) * kstep; const char* b2 = last ? ns.B : cB + (size_t)(t + 2) * kstep;
;                 const char* a3 = a2 + kstep; const char* b3 = b2 + kstep;
;                 unsigned vA2[2], vB2[2];
; #pragma unroll
;                 for (int i = 0; i < 2; ++i) { vA2[i] = last ? nvA[i] : voffA[i]; vB2[i] = last ? nvB[i] : voffB[i]; }
;                 const size_t hA2 = last ? nhA : hstepA, hB2 = last ? nhB : hstepB;
;                 PG8_LDB(B0, 0, 0); PG8_LDB(B1, 0, 1); PG8_SCHED; PG8_LDA(At, 0, 0); PG8_STAGE(PG8_SA(1, 1), a1 + hstepA, voffA);
;                 PG8_WAIT_V(8); PG8_WAIT_L(0); PG8_BAR; PG8_MMA(0, 0, At, B0); PG8_MMA(0, 1, At, B1); PG8_BAR; PG8_SCHED;
;                 PG8_LDA(At, 0, 1); PG8_STAGE(PG8_SB(0, 0), b2, vB2); PG8_STAGE(PG8_SB(0, 1), b2 + hB2, vB2); PG8_STAGE(PG8_SA(0, 0), a2, vA2);
;                 PG8_WAIT_V(8); PG8_WAIT_L(0); PG8_BAR; PG8_MMA(1, 0, At, B0); PG8_MMA(1, 1, At, B1); PG8_BAR; PG8_SCHED;
;                 PG8_LDB(B0, 1, 0); PG8_LDB(B1, 1, 1); PG8_SCHED; PG8_LDA(At, 1, 0); PG8_STAGE(PG8_SA(0, 1), a2 + hA2, vA2);
;                 PG8_WAIT_V(8); PG8_WAIT_L(0); PG8_BAR; PG8_MMA(0, 0, At, B0); PG8_MMA(0, 1, At, B1); PG8_BAR; PG8_SCHED;
;                 PG8_LDA(At, 1, 1); PG8_STAGE(PG8_SB(1, 0), b3, vB2); PG8_STAGE(PG8_SB(1, 1), b3 + hB2, vB2); PG8_STAGE(PG8_SA(1, 0), a3, vA2);
;                 PG8_WAIT_V(8); PG8_WAIT_L(0); PG8_BAR; PG8_MMA(1, 0, At, B0); PG8_MMA(1, 1, At, B1); PG8_BAR; PG8_SCHED;
.LBB0_1096:
	ds_read_b128 v[128:131], v188
	ds_read_b128 v[132:135], v189
	ds_read_b128 v[136:139], v190
	ds_read_b128 v[140:143], v191
	ds_read_b128 v[144:147], v192
	ds_read_b128 v[148:151], v193
	ds_read_b128 v[152:155], v194
	ds_read_b128 v[156:159], v195
	s_add_u32 s24, s22, 0xffd50080
	s_addc_u32 s25, s23, -1
	s_cmpk_eq_i32 s56, 0xa8
	s_cselect_b32 s27, s19, s25
	s_cselect_b32 s26, s18, s24
	s_cselect_b32 s25, s53, s55
	s_cselect_b32 s24, s52, s54
	v_lshl_add_u64 v[222:223], s[22:23], 0, v[168:169]
	s_add_i32 m0, s34, 0xc000
	ds_read_b128 v[160:163], v196
	ds_read_b128 v[164:167], v196 offset:2048
	ds_read_b128 v[180:183], v197
	ds_read_b128 v[202:205], v197 offset:2048
	ds_read_b128 v[206:209], v196 offset:4096
	ds_read_b128 v[210:213], v196 offset:6144
	ds_read_b128 v[214:217], v197 offset:4096
	ds_read_b128 v[218:221], v197 offset:6144
	global_load_lds_dwordx4 v[222:223], off
	v_lshl_add_u64 v[222:223], s[22:23], 0, v[172:173]
	s_add_i32 m0, s34, 0xe000
	s_nop 0
	global_load_lds_dwordx4 v[222:223], off
	s_waitcnt vmcnt(8)
	s_waitcnt lgkmcnt(0)
	s_waitcnt lgkmcnt(0)
	v_mfma_f32_16x16x32_bf16 v[124:127], v[128:131], v[160:163], v[124:127]
	v_mfma_f32_16x16x32_bf16 v[124:127], v[132:135], v[180:183], v[124:127]
	v_mfma_f32_16x16x32_bf16 v[120:123], v[140:143], v[180:183], v[120:123]
	v_mfma_f32_16x16x32_bf16 v[120:123], v[136:139], v[160:163], v[120:123]
	s_barrier
	s_setprio 3
	v_mfma_f32_16x16x32_bf16 v[104:107], v[136:139], v[164:167], v[104:107]
	v_mfma_f32_16x16x32_bf16 v[104:107], v[140:143], v[202:205], v[104:107]
	v_mfma_f32_16x16x32_bf16 v[112:115], v[132:135], v[202:205], v[112:115]
	v_mfma_f32_16x16x32_bf16 v[112:115], v[128:131], v[164:167], v[112:115]
	v_mfma_f32_16x16x32_bf16 v[96:99], v[128:131], v[206:209], v[96:99]
	v_mfma_f32_16x16x32_bf16 v[96:99], v[132:135], v[214:217], v[96:99]
	v_mfma_f32_16x16x32_bf16 v[88:91], v[140:143], v[214:217], v[88:91]
	v_mfma_f32_16x16x32_bf16 v[88:91], v[136:139], v[206:209], v[88:91]
	v_mfma_f32_16x16x32_bf16 v[72:75], v[136:139], v[210:213], v[72:75]
	v_mfma_f32_16x16x32_bf16 v[72:75], v[140:143], v[218:221], v[72:75]
	v_mfma_f32_16x16x32_bf16 v[80:83], v[132:135], v[218:221], v[80:83]
	v_mfma_f32_16x16x32_bf16 v[80:83], v[128:131], v[210:213], v[80:83]
	s_setprio 0
	s_setprio 3
	v_mfma_f32_16x16x32_bf16 v[116:119], v[144:147], v[160:163], v[116:119]
	v_mfma_f32_16x16x32_bf16 v[116:119], v[148:151], v[180:183], v[116:119]
	v_mfma_f32_16x16x32_bf16 v[108:111], v[156:159], v[180:183], v[108:111]
	v_mfma_f32_16x16x32_bf16 v[108:111], v[152:155], v[160:163], v[108:111]
	v_mfma_f32_16x16x32_bf16 v[92:95], v[152:155], v[164:167], v[92:95]
	v_mfma_f32_16x16x32_bf16 v[92:95], v[156:159], v[202:205], v[92:95]
	v_mfma_f32_16x16x32_bf16 v[100:103], v[148:151], v[202:205], v[100:103]
	v_mfma_f32_16x16x32_bf16 v[100:103], v[144:147], v[164:167], v[100:103]
	v_mfma_f32_16x16x32_bf16 v[84:87], v[144:147], v[206:209], v[84:87]
	v_mfma_f32_16x16x32_bf16 v[84:87], v[148:151], v[214:217], v[84:87]
	v_mfma_f32_16x16x32_bf16 v[76:79], v[156:159], v[214:217], v[76:79]
	v_mfma_f32_16x16x32_bf16 v[76:79], v[152:155], v[206:209], v[76:79]
	v_mfma_f32_16x16x32_bf16 v[60:63], v[152:155], v[210:213], v[60:63]
	v_mfma_f32_16x16x32_bf16 v[60:63], v[156:159], v[218:221], v[60:63]
	v_mfma_f32_16x16x32_bf16 v[68:71], v[148:151], v[218:221], v[68:71]
	v_mfma_f32_16x16x32_bf16 v[68:71], v[144:147], v[210:213], v[68:71]
	s_setprio 0
	s_barrier
	s_add_i32 s57, s41, s68
	v_lshl_add_u64 v[222:223], s[24:25], 0, v[170:171]
	s_mov_b32 m0, s57
	ds_read_b128 v[160:163], v196 offset:16384
	ds_read_b128 v[164:167], v196 offset:18432
	ds_read_b128 v[180:183], v197 offset:16384
	ds_read_b128 v[202:205], v197 offset:18432
	ds_read_b128 v[206:209], v196 offset:20480
	ds_read_b128 v[210:213], v196 offset:22528
	ds_read_b128 v[214:217], v197 offset:20480
	ds_read_b128 v[218:221], v197 offset:22528
	global_load_lds_dwordx4 v[222:223], off
	s_add_i32 m0, s57, 0x2000
	s_add_u32 s58, s24, 0x2b0000
	v_lshl_add_u64 v[224:225], s[24:25], 0, v[174:175]
	s_addc_u32 s59, s25, 0
	s_add_i32 s57, s42, s68
	global_load_lds_dwordx4 v[224:225], off
	v_lshl_add_u64 v[226:227], s[58:59], 0, v[170:171]
	s_mov_b32 m0, s57
	v_lshl_add_u64 v[228:229], s[26:27], 0, v[172:173]
	global_load_lds_dwordx4 v[226:227], off
	v_lshl_add_u64 v[226:227], s[58:59], 0, v[174:175]
	s_add_i32 m0, s57, 0x2000
	s_nop 0
	global_load_lds_dwordx4 v[226:227], off
	v_lshl_add_u64 v[226:227], s[26:27], 0, v[168:169]
	s_mov_b32 m0, s34
	s_nop 0
	global_load_lds_dwordx4 v[226:227], off
	s_mov_b32 m0, s35
	s_nop 0
	global_load_lds_dwordx4 v[228:229], off
	s_waitcnt vmcnt(8)
	s_waitcnt lgkmcnt(0)
	s_waitcnt lgkmcnt(0)
	v_mfma_f32_16x16x32_bf16 v[52:55], v[128:131], v[160:163], v[52:55]
	v_mfma_f32_16x16x32_bf16 v[52:55], v[132:135], v[180:183], v[52:55]
	v_mfma_f32_16x16x32_bf16 v[48:51], v[140:143], v[180:183], v[48:51]
	v_mfma_f32_16x16x32_bf16 v[48:51], v[136:139], v[160:163], v[48:51]
	s_barrier
; #define PG8_STAGE(bufoff, gbase, voff) do { _Pragma("unroll") for (int _i = 0; _i < 2; ++_i) \
;         __builtin_amdgcn_global_load_lds((const unsigned*)((const char*)(gbase) + (voff)[_i]), (LAS unsigned*)(lds + (bufoff) + ldsw + _i * 8192), 16, 0, 0); } while (0)
; #define PG8_LDA(dst, b, h) do { _Pragma("unroll") for (int m = 0; m < 4; ++m) _Pragma("unroll") for (int k = 0; k < 2; ++k) dst[m][k] = *(const LAS bf16x8*)(lds + PG8_SA(b, h) + aoffk[k] + m * 2048); } while (0)
; #define PG8_LDB(dst, b, h) do { _Pragma("unroll") for (int n = 0; n < 2; ++n) _Pragma("unroll") for (int k = 0; k < 2; ++k) dst[n][k] = *(const LAS bf16x8*)(lds + PG8_SB(b, h) + boffk[k] + n * 2048); } while (0)
; #define PG8_WAIT_V(n) asm volatile("s_waitcnt vmcnt(" #n ")" ::: "memory")
; #define PG8_WAIT_L(n) asm volatile("s_waitcnt lgkmcnt(" #n ")" ::: "memory")
; #define PG8_BAR __builtin_amdgcn_s_barrier()
; #define PG8_SCHED __builtin_amdgcn_sched_barrier(0)
; template <class Epi, class Sched, class GemmT>
; __device__ __forceinline__ void gemm_phase(LAS unsigned char* lds, const GemmT& g, const Sched& S, const Epi& E, const int wid) {
;     ...
;                 PG8_LDA(At, 0, 1); PG8_STAGE(PG8_SB(0, 0), b2, vB2); PG8_STAGE(PG8_SB(0, 1), b2 + hB2, vB2); PG8_STAGE(PG8_SA(0, 0), a2, vA2);
;                 PG8_WAIT_V(8); PG8_WAIT_L(0); PG8_BAR; PG8_MMA(1, 0, At, B0); PG8_MMA(1, 1, At, B1); PG8_BAR; PG8_SCHED;
;                 PG8_LDB(B0, 1, 0); PG8_LDB(B1, 1, 1); PG8_SCHED; PG8_LDA(At, 1, 0); PG8_STAGE(PG8_SA(0, 1), a2 + hA2, vA2);
;                 PG8_WAIT_V(8); PG8_WAIT_L(0); PG8_BAR; PG8_MMA(0, 0, At, B0); PG8_MMA(0, 1, At, B1); PG8_BAR; PG8_SCHED;
;                 PG8_LDA(At, 1, 1); PG8_STAGE(PG8_SB(1, 0), b3, vB2); PG8_STAGE(PG8_SB(1, 1), b3 + hB2, vB2); PG8_STAGE(PG8_SA(1, 0), a3, vA2);
	s_setprio 3
	v_mfma_f32_16x16x32_bf16 v[32:35], v[136:139], v[164:167], v[32:35]
	v_mfma_f32_16x16x32_bf16 v[32:35], v[140:143], v[202:205], v[32:35]
	v_mfma_f32_16x16x32_bf16 v[36:39], v[132:135], v[202:205], v[36:39]
	v_mfma_f32_16x16x32_bf16 v[36:39], v[128:131], v[164:167], v[36:39]
	v_mfma_f32_16x16x32_bf16 v[20:23], v[128:131], v[206:209], v[20:23]
	v_mfma_f32_16x16x32_bf16 v[20:23], v[132:135], v[214:217], v[20:23]
	v_mfma_f32_16x16x32_bf16 v[8:11], v[140:143], v[214:217], v[8:11]
	v_mfma_f32_16x16x32_bf16 v[8:11], v[136:139], v[206:209], v[8:11]
	v_mfma_f32_16x16x32_bf16 v[0:3], v[136:139], v[210:213], v[0:3]
	v_mfma_f32_16x16x32_bf16 v[0:3], v[140:143], v[218:221], v[0:3]
	v_mfma_f32_16x16x32_bf16 v[4:7], v[132:135], v[218:221], v[4:7]
	v_mfma_f32_16x16x32_bf16 v[4:7], v[128:131], v[210:213], v[4:7]
	s_setprio 0
	s_setprio 3
	v_mfma_f32_16x16x32_bf16 v[64:67], v[144:147], v[160:163], v[64:67]
	v_mfma_f32_16x16x32_bf16 v[64:67], v[148:151], v[180:183], v[64:67]
	v_mfma_f32_16x16x32_bf16 v[56:59], v[156:159], v[180:183], v[56:59]
	v_mfma_f32_16x16x32_bf16 v[56:59], v[152:155], v[160:163], v[56:59]
	v_mfma_f32_16x16x32_bf16 v[40:43], v[152:155], v[164:167], v[40:43]
	v_mfma_f32_16x16x32_bf16 v[40:43], v[156:159], v[202:205], v[40:43]
	v_mfma_f32_16x16x32_bf16 v[44:47], v[148:151], v[202:205], v[44:47]
	v_mfma_f32_16x16x32_bf16 v[44:47], v[144:147], v[164:167], v[44:47]
	v_mfma_f32_16x16x32_bf16 v[28:31], v[144:147], v[206:209], v[28:31]
	v_mfma_f32_16x16x32_bf16 v[28:31], v[148:151], v[214:217], v[28:31]
	v_mfma_f32_16x16x32_bf16 v[24:27], v[156:159], v[214:217], v[24:27]
	v_mfma_f32_16x16x32_bf16 v[24:27], v[152:155], v[206:209], v[24:27]
	v_mfma_f32_16x16x32_bf16 v[12:15], v[152:155], v[210:213], v[12:15]
	v_mfma_f32_16x16x32_bf16 v[12:15], v[156:159], v[218:221], v[12:15]
	v_mfma_f32_16x16x32_bf16 v[16:19], v[148:151], v[218:221], v[16:19]
	v_mfma_f32_16x16x32_bf16 v[16:19], v[144:147], v[210:213], v[16:19]
	s_setprio 0
	s_barrier
	s_add_i32 s57, 0, 0x18000
	s_add_i32 s58, 0, 0x1c000
	v_add_u32_e32 v128, s57, v185
	v_add_u32_e32 v132, s57, v186
	v_add_u32_e32 v144, s58, v185
	v_add_u32_e32 v148, s58, v186
	ds_read_b128 v[128:131], v128
	ds_read_b128 v[132:135], v132
	ds_read_b128 v[136:139], v198
	ds_read_b128 v[140:143], v199
	ds_read_b128 v[144:147], v144
	ds_read_b128 v[148:151], v148
	ds_read_b128 v[152:155], v200
	ds_read_b128 v[156:159], v201
	s_add_u32 s26, s26, 0x2b0000
	s_addc_u32 s27, s27, 0
	s_mov_b32 m0, s36
	v_lshl_add_u64 v[230:231], s[26:27], 0, v[168:169]
	ds_read_b128 v[160:163], v196 offset:32768
	ds_read_b128 v[164:167], v196 offset:34816
	ds_read_b128 v[180:183], v197 offset:32768
	ds_read_b128 v[202:205], v197 offset:34816
	ds_read_b128 v[206:209], v196 offset:36864
	ds_read_b128 v[210:213], v196 offset:38912
	ds_read_b128 v[214:217], v197 offset:36864
	ds_read_b128 v[218:221], v197 offset:38912
	global_load_lds_dwordx4 v[230:231], off
	v_lshl_add_u64 v[230:231], s[26:27], 0, v[172:173]
	s_mov_b32 m0, s37
	s_nop 0
	global_load_lds_dwordx4 v[230:231], off
	s_waitcnt vmcnt(8)
	s_waitcnt lgkmcnt(0)
	s_waitcnt lgkmcnt(0)
	v_mfma_f32_16x16x32_bf16 v[124:127], v[128:131], v[160:163], v[124:127]
	v_mfma_f32_16x16x32_bf16 v[124:127], v[132:135], v[180:183], v[124:127]
	v_mfma_f32_16x16x32_bf16 v[120:123], v[140:143], v[180:183], v[120:123]
	v_mfma_f32_16x16x32_bf16 v[120:123], v[136:139], v[160:163], v[120:123]
	s_barrier
	s_setprio 3
	v_mfma_f32_16x16x32_bf16 v[104:107], v[136:139], v[164:167], v[104:107]
	v_mfma_f32_16x16x32_bf16 v[104:107], v[140:143], v[202:205], v[104:107]
	v_mfma_f32_16x16x32_bf16 v[112:115], v[132:135], v[202:205], v[112:115]
	v_mfma_f32_16x16x32_bf16 v[112:115], v[128:131], v[164:167], v[112:115]
	v_mfma_f32_16x16x32_bf16 v[96:99], v[128:131], v[206:209], v[96:99]
	v_mfma_f32_16x16x32_bf16 v[96:99], v[132:135], v[214:217], v[96:99]
	v_mfma_f32_16x16x32_bf16 v[88:91], v[140:143], v[214:217], v[88:91]
	v_mfma_f32_16x16x32_bf16 v[88:91], v[136:139], v[206:209], v[88:91]
	v_mfma_f32_16x16x32_bf16 v[72:75], v[136:139], v[210:213], v[72:75]
	v_mfma_f32_16x16x32_bf16 v[72:75], v[140:143], v[218:221], v[72:75]
	v_mfma_f32_16x16x32_bf16 v[80:83], v[132:135], v[218:221], v[80:83]
	v_mfma_f32_16x16x32_bf16 v[80:83], v[128:131], v[210:213], v[80:83]
	s_setprio 0
	s_setprio 3
	v_mfma_f32_16x16x32_bf16 v[116:119], v[144:147], v[160:163], v[116:119]
	v_mfma_f32_16x16x32_bf16 v[116:119], v[148:151], v[180:183], v[116:119]
	v_mfma_f32_16x16x32_bf16 v[108:111], v[156:159], v[180:183], v[108:111]
	v_mfma_f32_16x16x32_bf16 v[108:111], v[152:155], v[160:163], v[108:111]
	v_mfma_f32_16x16x32_bf16 v[92:95], v[152:155], v[164:167], v[92:95]
	v_mfma_f32_16x16x32_bf16 v[92:95], v[156:159], v[202:205], v[92:95]
	v_mfma_f32_16x16x32_bf16 v[100:103], v[148:151], v[202:205], v[100:103]
	v_mfma_f32_16x16x32_bf16 v[100:103], v[144:147], v[164:167], v[100:103]
	v_mfma_f32_16x16x32_bf16 v[84:87], v[144:147], v[206:209], v[84:87]
	v_mfma_f32_16x16x32_bf16 v[84:87], v[148:151], v[214:217], v[84:87]
	v_mfma_f32_16x16x32_bf16 v[76:79], v[156:159], v[214:217], v[76:79]
	v_mfma_f32_16x16x32_bf16 v[76:79], v[152:155], v[206:209], v[76:79]
	v_mfma_f32_16x16x32_bf16 v[60:63], v[152:155], v[210:213], v[60:63]
	v_mfma_f32_16x16x32_bf16 v[60:63], v[156:159], v[218:221], v[60:63]
	v_mfma_f32_16x16x32_bf16 v[68:71], v[148:151], v[218:221], v[68:71]
	v_mfma_f32_16x16x32_bf16 v[68:71], v[144:147], v[210:213], v[68:71]
	s_setprio 0
	s_barrier
; #define PG8_STAGE(bufoff, gbase, voff) do { _Pragma("unroll") for (int _i = 0; _i < 2; ++_i) \
;         __builtin_amdgcn_global_load_lds((const unsigned*)((const char*)(gbase) + (voff)[_i]), (LAS unsigned*)(lds + (bufoff) + ldsw + _i * 8192), 16, 0, 0); } while (0)
; #define PG8_LDA(dst, b, h) do { _Pragma("unroll") for (int m = 0; m < 4; ++m) _Pragma("unroll") for (int k = 0; k < 2; ++k) dst[m][k] = *(const LAS bf16x8*)(lds + PG8_SA(b, h) + aoffk[k] + m * 2048); } while (0)
; #define PG8_WAIT_V(n) asm volatile("s_waitcnt vmcnt(" #n ")" ::: "memory")
; #define PG8_WAIT_L(n) asm volatile("s_waitcnt lgkmcnt(" #n ")" ::: "memory")
; #define PG8_BAR __builtin_amdgcn_s_barrier()
; #define PG8_SCHED __builtin_amdgcn_sched_barrier(0)
; template <class Epi, class Sched, class GemmT>
; __device__ __forceinline__ void gemm_phase(LAS unsigned char* lds, const GemmT& g, const Sched& S, const Epi& E, const int wid) {
;     ...
;                 PG8_LDA(At, 1, 1); PG8_STAGE(PG8_SB(1, 0), b3, vB2); PG8_STAGE(PG8_SB(1, 1), b3 + hB2, vB2); PG8_STAGE(PG8_SA(1, 0), a3, vA2);
;                 PG8_WAIT_V(8); PG8_WAIT_L(0); PG8_BAR; PG8_MMA(1, 0, At, B0); PG8_MMA(1, 1, At, B1); PG8_BAR; PG8_SCHED;
;             }
;             if constexpr (NSEG > 1) { if (sgi + 1 < NSEG) E.mid(acc, cur, sgi, wr, wc, fr, fq); }
;             cs = ns; cA = ns.A; cB = ns.B; hstepA = nhA; hstepB = nhB;
; #pragma unroll
;             for (int i = 0; i < 2; ++i) { voffA[i] = nvA[i]; voffB[i] = nvB[i]; }
;         }
;         if (wr == 0) PG8_BAR;
	s_add_i32 s26, s57, s68
	v_lshl_add_u64 v[222:223], v[222:223], 0, s[6:7]
	s_mov_b32 m0, s26
	ds_read_b128 v[160:163], v196 offset:49152
	ds_read_b128 v[164:167], v196 offset:51200
	ds_read_b128 v[180:183], v197 offset:49152
	ds_read_b128 v[202:205], v197 offset:51200
	ds_read_b128 v[206:209], v196 offset:53248
	ds_read_b128 v[210:213], v196 offset:55296
	ds_read_b128 v[214:217], v197 offset:53248
	ds_read_b128 v[218:221], v197 offset:55296
	global_load_lds_dwordx4 v[222:223], off
	s_add_i32 m0, s26, 0x2000
	s_add_u32 s24, s24, 0x2b0080
	v_lshl_add_u64 v[222:223], v[224:225], 0, s[6:7]
	s_addc_u32 s25, s25, 0
	s_add_i32 s26, s58, s68
	global_load_lds_dwordx4 v[222:223], off
	v_lshl_add_u64 v[222:223], s[24:25], 0, v[170:171]
	s_mov_b32 m0, s26
	s_nop 0
	global_load_lds_dwordx4 v[222:223], off
	v_lshl_add_u64 v[222:223], s[24:25], 0, v[174:175]
	s_add_i32 m0, s26, 0x2000
	s_nop 0
	global_load_lds_dwordx4 v[222:223], off
	v_lshl_add_u64 v[222:223], v[226:227], 0, s[6:7]
	s_mov_b32 m0, s39
	s_nop 0
	global_load_lds_dwordx4 v[222:223], off
	v_lshl_add_u64 v[222:223], v[228:229], 0, s[6:7]
	s_mov_b32 m0, s40
	s_nop 0
	global_load_lds_dwordx4 v[222:223], off
	s_waitcnt vmcnt(8)
	s_waitcnt lgkmcnt(0)
	s_waitcnt lgkmcnt(0)
	v_mfma_f32_16x16x32_bf16 v[52:55], v[128:131], v[160:163], v[52:55]
	v_mfma_f32_16x16x32_bf16 v[52:55], v[132:135], v[180:183], v[52:55]
	v_mfma_f32_16x16x32_bf16 v[48:51], v[140:143], v[180:183], v[48:51]
	v_mfma_f32_16x16x32_bf16 v[48:51], v[136:139], v[160:163], v[48:51]
	s_barrier
	s_setprio 3
	v_mfma_f32_16x16x32_bf16 v[32:35], v[136:139], v[164:167], v[32:35]
	v_mfma_f32_16x16x32_bf16 v[32:35], v[140:143], v[202:205], v[32:35]
	v_mfma_f32_16x16x32_bf16 v[36:39], v[132:135], v[202:205], v[36:39]
	v_mfma_f32_16x16x32_bf16 v[36:39], v[128:131], v[164:167], v[36:39]
	v_mfma_f32_16x16x32_bf16 v[20:23], v[128:131], v[206:209], v[20:23]
	v_mfma_f32_16x16x32_bf16 v[20:23], v[132:135], v[214:217], v[20:23]
	v_mfma_f32_16x16x32_bf16 v[8:11], v[140:143], v[214:217], v[8:11]
	v_mfma_f32_16x16x32_bf16 v[8:11], v[136:139], v[206:209], v[8:11]
	v_mfma_f32_16x16x32_bf16 v[0:3], v[136:139], v[210:213], v[0:3]
	v_mfma_f32_16x16x32_bf16 v[0:3], v[140:143], v[218:221], v[0:3]
	v_mfma_f32_16x16x32_bf16 v[4:7], v[132:135], v[218:221], v[4:7]
	v_mfma_f32_16x16x32_bf16 v[4:7], v[128:131], v[210:213], v[4:7]
	s_setprio 0
	s_setprio 3
	v_mfma_f32_16x16x32_bf16 v[64:67], v[144:147], v[160:163], v[64:67]
	v_mfma_f32_16x16x32_bf16 v[64:67], v[148:151], v[180:183], v[64:67]
	v_mfma_f32_16x16x32_bf16 v[56:59], v[156:159], v[180:183], v[56:59]
	v_mfma_f32_16x16x32_bf16 v[56:59], v[152:155], v[160:163], v[56:59]
	v_mfma_f32_16x16x32_bf16 v[40:43], v[152:155], v[164:167], v[40:43]
	v_mfma_f32_16x16x32_bf16 v[40:43], v[156:159], v[202:205], v[40:43]
	v_mfma_f32_16x16x32_bf16 v[44:47], v[148:151], v[202:205], v[44:47]
	v_mfma_f32_16x16x32_bf16 v[44:47], v[144:147], v[164:167], v[44:47]
	v_mfma_f32_16x16x32_bf16 v[28:31], v[144:147], v[206:209], v[28:31]
	v_mfma_f32_16x16x32_bf16 v[28:31], v[148:151], v[214:217], v[28:31]
	v_mfma_f32_16x16x32_bf16 v[24:27], v[156:159], v[214:217], v[24:27]
	v_mfma_f32_16x16x32_bf16 v[24:27], v[152:155], v[206:209], v[24:27]
	v_mfma_f32_16x16x32_bf16 v[12:15], v[152:155], v[210:213], v[12:15]
	v_mfma_f32_16x16x32_bf16 v[12:15], v[156:159], v[218:221], v[12:15]
	v_mfma_f32_16x16x32_bf16 v[16:19], v[148:151], v[218:221], v[16:19]
	v_mfma_f32_16x16x32_bf16 v[16:19], v[144:147], v[210:213], v[16:19]
	s_setprio 0
	s_barrier
	s_add_i32 s56, s56, 2
	s_add_u32 s22, s22, 0x100
	s_addc_u32 s23, s23, 0
	s_add_u32 s54, s54, 0x100
	s_addc_u32 s55, s55, 0
	s_cmpk_gt_u32 s56, 0xa9
	s_cbranch_scc0 .LBB0_1096
	s_and_b64 vcc, exec, s[8:9]
	s_cbranch_vccz .LBB0_1099
	s_barrier
